# GELU (S5 output GEMM) and GLU-sigmoid epilogues: IEEE f32 division chains replaced by f32 rcp*mul (still f32), dead chain code eliminated; on-chip Z carry scan
# baseline (speedup 1.0000x reference)
; #define PG8_STAGE(bufoff, gbase, voff) do { _Pragma("unroll") for (int _i = 0; _i < 2; ++_i) \
;         __builtin_amdgcn_global_load_lds((const unsigned*)((const char*)(gbase) + (voff)[_i]), (LAS unsigned*)(lds + (bufoff) + ldsw + _i * 8192), 16, 0, 0); } while (0)
; #define PG8_LDA(dst, b, h) do { _Pragma("unroll") for (int m = 0; m < 4; ++m) _Pragma("unroll") for (int k = 0; k < 2; ++k) dst[m][k] = *(const LAS bf16x8*)(lds + PG8_SA(b, h) + aoff + m * 2048 + k * 1024); } while (0)
; #define PG8_LDB(dst, b, h) do { _Pragma("unroll") for (int n = 0; n < 2; ++n) _Pragma("unroll") for (int k = 0; k < 2; ++k) dst[n][k] = *(const LAS bf16x8*)(lds + PG8_SB(b, h) + boff + n * 2048 + k * 1024); } while (0)
; #define PG8_MMA(ai, bj, At, Bt) do { __builtin_amdgcn_s_setprio(1); _Pragma("unroll") for (int m = 0; m < 4; ++m) _Pragma("unroll") for (int n = 0; n < 2; ++n) _Pragma("unroll") for (int k = 0; k < 2; ++k) \
;         acc[ai][bj][m][n] = __builtin_amdgcn_mfma_f32_16x16x32_bf16(Bt[n][k], At[m][k], acc[ai][bj][m][n], 0, 0, 0); __builtin_amdgcn_s_setprio(0); } while (0)
; #define PG8_WAIT_V(n) asm volatile("s_waitcnt vmcnt(" #n ")" ::: "memory")
; #define PG8_WAIT_L(n) asm volatile("s_waitcnt lgkmcnt(" #n ")" ::: "memory")
; #define PG8_BAR __builtin_amdgcn_s_barrier()
; template <class Epi, class Sched>
; __device__ __forceinline__ void gemm_phase(LAS unsigned char* lds, const Gemm g, const Sched& S, const Epi& E) {
;     ...
;             const bool last = (t == nt - 2);
;             const char* a1 = cA + (size_t)(t + 1) * kstep;
;             const char* a2 = last ? nA : cA + (size_t)(t + 2) * kstep; const char* b2 = last ? nB : cB + (size_t)(t + 2) * kstep;
;             const char* a3 = a2 + kstep; const char* b3 = b2 + kstep;
;             PG8_LDB(B0, 0, 0); PG8_SCHED; PG8_LDA(At, 0, 0); PG8_STAGE(PG8_SA(1, 1), a1 + hstepA, voffA);
;             PG8_WAIT_L(8); PG8_BAR; PG8_WAIT_L(0); PG8_MMA(0, 0, At, B0); PG8_BAR; PG8_SCHED;
;             PG8_LDB(B1, 0, 1); PG8_STAGE(PG8_SB(0, 0), b2, voffB);
;             PG8_BAR; PG8_WAIT_L(0); PG8_MMA(0, 1, At, B1); PG8_BAR;
;             PG8_LDA(At, 0, 1); PG8_STAGE(PG8_SA(0, 0), a2, voffA);
;             PG8_BAR; PG8_WAIT_L(0); PG8_MMA(1, 0, At, B0); PG8_BAR; PG8_SCHED;
;             PG8_STAGE(PG8_SB(0, 1), b2 + hstepB, voffB);
;             PG8_WAIT_V(6); PG8_BAR; PG8_MMA(1, 1, At, B1); PG8_BAR;
.LBB0_595:
	v_add_u32_e32 v144, s24, v1
	ds_read_b128 v[172:175], v144
	ds_read_b128 v[176:179], v144 offset:1024
	ds_read_b128 v[180:183], v144 offset:2048
	ds_read_b128 v[184:187], v144 offset:3072
	s_add_u32 s42, s36, 0x100
	s_addc_u32 s43, s37, 0
	s_cmp_eq_u32 s54, 8
	s_cselect_b32 s47, s21, s43
	s_cselect_b32 s46, s20, s42
	s_cselect_b32 s45, s1, s29
	s_cselect_b32 s44, s0, s28
	v_lshl_add_u64 v[144:145], s[36:37], 0, v[140:141]
	s_add_i32 m0, s34, 0xc000
	ds_read_b128 v[188:191], v170
	ds_read_b128 v[192:195], v170 offset:1024
	ds_read_b128 v[196:199], v170 offset:2048
	ds_read_b128 v[210:213], v170 offset:3072
	ds_read_b128 v[214:217], v170 offset:4096
	ds_read_b128 v[218:221], v170 offset:5120
	ds_read_b128 v[222:225], v170 offset:6144
	ds_read_b128 v[226:229], v170 offset:7168
	global_load_lds_dwordx4 v[144:145], off
	v_lshl_add_u64 v[144:145], s[36:37], 0, v[142:143]
	s_add_i32 m0, s34, 0xe000
	s_nop 0
	global_load_lds_dwordx4 v[144:145], off
	s_waitcnt lgkmcnt(8)
	s_barrier
	s_waitcnt lgkmcnt(0)
	s_setprio 1
	s_waitcnt lgkmcnt(0)
	v_mfma_f32_16x16x32_bf16 v[126:129], v[172:175], v[188:191], v[126:129]
	v_mfma_f32_16x16x32_bf16 v[122:125], v[180:183], v[188:191], v[122:125]
	v_mfma_f32_16x16x32_bf16 v[110:113], v[172:175], v[196:199], v[110:113]
	v_mfma_f32_16x16x32_bf16 v[106:109], v[180:183], v[196:199], v[106:109]
	v_mfma_f32_16x16x32_bf16 v[94:97], v[172:175], v[214:217], v[94:97]
	v_mfma_f32_16x16x32_bf16 v[90:93], v[180:183], v[214:217], v[90:93]
	v_mfma_f32_16x16x32_bf16 v[78:81], v[172:175], v[222:225], v[78:81]
	v_mfma_f32_16x16x32_bf16 v[74:77], v[180:183], v[222:225], v[74:77]
	v_mfma_f32_16x16x32_bf16 v[126:129], v[176:179], v[192:195], v[126:129]
	v_mfma_f32_16x16x32_bf16 v[122:125], v[184:187], v[192:195], v[122:125]
	v_mfma_f32_16x16x32_bf16 v[110:113], v[176:179], v[210:213], v[110:113]
	v_mfma_f32_16x16x32_bf16 v[106:109], v[184:187], v[210:213], v[106:109]
	v_mfma_f32_16x16x32_bf16 v[94:97], v[176:179], v[218:221], v[94:97]
	v_mfma_f32_16x16x32_bf16 v[90:93], v[184:187], v[218:221], v[90:93]
	v_mfma_f32_16x16x32_bf16 v[78:81], v[176:179], v[226:229], v[78:81]
	v_mfma_f32_16x16x32_bf16 v[74:77], v[184:187], v[226:229], v[74:77]
	s_setprio 0
	s_barrier
	v_add_u32_e32 v144, s25, v1
	s_add_i32 s23, s24, s13
	ds_read_b128 v[230:233], v144
	ds_read_b128 v[234:237], v144 offset:1024
	ds_read_b128 v[238:241], v144 offset:2048
	ds_read_b128 v[242:245], v144 offset:3072
	v_lshl_add_u64 v[144:145], s[44:45], 0, v[132:133]
	s_mov_b32 m0, s23
	v_lshl_add_u64 v[246:247], s[44:45], 0, v[136:137]
	global_load_lds_dwordx4 v[144:145], off
	s_add_i32 m0, s23, 0x2000
	s_nop 0
	global_load_lds_dwordx4 v[246:247], off
	s_barrier
	s_waitcnt lgkmcnt(0)
	s_setprio 1
	s_waitcnt lgkmcnt(0)
	v_mfma_f32_16x16x32_bf16 v[118:121], v[230:233], v[188:191], v[118:121]
	v_mfma_f32_16x16x32_bf16 v[114:117], v[238:241], v[188:191], v[114:117]
	v_mfma_f32_16x16x32_bf16 v[102:105], v[230:233], v[196:199], v[102:105]
	v_mfma_f32_16x16x32_bf16 v[98:101], v[238:241], v[196:199], v[98:101]
	v_mfma_f32_16x16x32_bf16 v[86:89], v[230:233], v[214:217], v[86:89]
	v_mfma_f32_16x16x32_bf16 v[82:85], v[238:241], v[214:217], v[82:85]
	v_mfma_f32_16x16x32_bf16 v[70:73], v[230:233], v[222:225], v[70:73]
	v_mfma_f32_16x16x32_bf16 v[66:69], v[238:241], v[222:225], v[66:69]
	v_mfma_f32_16x16x32_bf16 v[118:121], v[234:237], v[192:195], v[118:121]
	v_mfma_f32_16x16x32_bf16 v[114:117], v[242:245], v[192:195], v[114:117]
	v_mfma_f32_16x16x32_bf16 v[102:105], v[234:237], v[210:213], v[102:105]
	v_mfma_f32_16x16x32_bf16 v[98:101], v[242:245], v[210:213], v[98:101]
	v_mfma_f32_16x16x32_bf16 v[86:89], v[234:237], v[218:221], v[86:89]
	v_mfma_f32_16x16x32_bf16 v[82:85], v[242:245], v[218:221], v[82:85]
	v_mfma_f32_16x16x32_bf16 v[70:73], v[234:237], v[226:229], v[70:73]
	v_mfma_f32_16x16x32_bf16 v[66:69], v[242:245], v[226:229], v[66:69]
	s_setprio 0
	s_mov_b32 m0, s34
	v_lshl_add_u64 v[248:249], s[46:47], 0, v[130:131]
	s_barrier
	ds_read_b128 v[188:191], v170 offset:16384
	ds_read_b128 v[192:195], v170 offset:17408
	ds_read_b128 v[196:199], v170 offset:18432
	ds_read_b128 v[210:213], v170 offset:19456
	ds_read_b128 v[214:217], v170 offset:20480
	ds_read_b128 v[218:221], v170 offset:21504
	ds_read_b128 v[222:225], v170 offset:22528
	ds_read_b128 v[226:229], v170 offset:23552
	global_load_lds_dwordx4 v[248:249], off
	v_lshl_add_u64 v[250:251], s[46:47], 0, v[134:135]
	s_mov_b32 m0, s35
	s_nop 0
	global_load_lds_dwordx4 v[250:251], off
	s_barrier
	s_waitcnt lgkmcnt(0)
	s_setprio 1
	s_waitcnt lgkmcnt(0)
	v_mfma_f32_16x16x32_bf16 v[62:65], v[172:175], v[188:191], v[62:65]
	v_mfma_f32_16x16x32_bf16 v[58:61], v[180:183], v[188:191], v[58:61]
	v_mfma_f32_16x16x32_bf16 v[46:49], v[172:175], v[196:199], v[46:49]
	v_mfma_f32_16x16x32_bf16 v[42:45], v[180:183], v[196:199], v[42:45]
	v_mfma_f32_16x16x32_bf16 v[30:33], v[172:175], v[214:217], v[30:33]
	v_mfma_f32_16x16x32_bf16 v[26:29], v[180:183], v[214:217], v[26:29]
	v_mfma_f32_16x16x32_bf16 v[14:17], v[172:175], v[222:225], v[14:17]
	v_mfma_f32_16x16x32_bf16 v[10:13], v[180:183], v[222:225], v[10:13]
	v_mfma_f32_16x16x32_bf16 v[62:65], v[176:179], v[192:195], v[62:65]
	v_mfma_f32_16x16x32_bf16 v[58:61], v[184:187], v[192:195], v[58:61]
	v_mfma_f32_16x16x32_bf16 v[46:49], v[176:179], v[210:213], v[46:49]
	v_mfma_f32_16x16x32_bf16 v[42:45], v[184:187], v[210:213], v[42:45]
	v_mfma_f32_16x16x32_bf16 v[30:33], v[176:179], v[218:221], v[30:33]
	v_mfma_f32_16x16x32_bf16 v[26:29], v[184:187], v[218:221], v[26:29]
	v_mfma_f32_16x16x32_bf16 v[14:17], v[176:179], v[226:229], v[14:17]
	v_mfma_f32_16x16x32_bf16 v[10:13], v[184:187], v[226:229], v[10:13]
	s_setprio 0
	s_barrier
; #define PG8_STAGE(bufoff, gbase, voff) do { _Pragma("unroll") for (int _i = 0; _i < 2; ++_i) \
;         __builtin_amdgcn_global_load_lds((const unsigned*)((const char*)(gbase) + (voff)[_i]), (LAS unsigned*)(lds + (bufoff) + ldsw + _i * 8192), 16, 0, 0); } while (0)
; #define PG8_LDA(dst, b, h) do { _Pragma("unroll") for (int m = 0; m < 4; ++m) _Pragma("unroll") for (int k = 0; k < 2; ++k) dst[m][k] = *(const LAS bf16x8*)(lds + PG8_SA(b, h) + aoff + m * 2048 + k * 1024); } while (0)
; #define PG8_LDB(dst, b, h) do { _Pragma("unroll") for (int n = 0; n < 2; ++n) _Pragma("unroll") for (int k = 0; k < 2; ++k) dst[n][k] = *(const LAS bf16x8*)(lds + PG8_SB(b, h) + boff + n * 2048 + k * 1024); } while (0)
; #define PG8_MMA(ai, bj, At, Bt) do { __builtin_amdgcn_s_setprio(1); _Pragma("unroll") for (int m = 0; m < 4; ++m) _Pragma("unroll") for (int n = 0; n < 2; ++n) _Pragma("unroll") for (int k = 0; k < 2; ++k) \
;         acc[ai][bj][m][n] = __builtin_amdgcn_mfma_f32_16x16x32_bf16(Bt[n][k], At[m][k], acc[ai][bj][m][n], 0, 0, 0); __builtin_amdgcn_s_setprio(0); } while (0)
; #define PG8_WAIT_V(n) asm volatile("s_waitcnt vmcnt(" #n ")" ::: "memory")
; #define PG8_WAIT_L(n) asm volatile("s_waitcnt lgkmcnt(" #n ")" ::: "memory")
; #define PG8_BAR __builtin_amdgcn_s_barrier()
; #define PG8_SCHED __builtin_amdgcn_sched_barrier(0)
; template <class Epi, class Sched>
; __device__ __forceinline__ void gemm_phase(LAS unsigned char* lds, const Gemm g, const Sched& S, const Epi& E) {
;     ...
;             PG8_WAIT_V(6); PG8_BAR; PG8_MMA(1, 1, At, B1); PG8_BAR;
;             PG8_LDB(B0, 1, 0); PG8_SCHED; PG8_LDA(At, 1, 0); PG8_STAGE(PG8_SA(0, 1), a2 + hstepA, voffA);
;             PG8_WAIT_L(8); PG8_BAR; PG8_WAIT_L(0); PG8_MMA(0, 0, At, B0); PG8_BAR; PG8_SCHED;
;             PG8_LDB(B1, 1, 1); PG8_STAGE(PG8_SB(1, 0), b3, voffB);
;             PG8_BAR; PG8_WAIT_L(0); PG8_MMA(0, 1, At, B1); PG8_BAR;
;             PG8_LDA(At, 1, 1); PG8_STAGE(PG8_SA(1, 0), a3, voffA);
;             PG8_BAR; PG8_WAIT_L(0); PG8_MMA(1, 0, At, B0); PG8_BAR; PG8_SCHED;
	s_add_u32 s36, s44, 0x30000
	s_addc_u32 s37, s45, 0
	s_add_i32 s23, s25, s13
	v_lshl_add_u64 v[172:173], s[36:37], 0, v[132:133]
	s_mov_b32 m0, s23
	s_nop 0
	global_load_lds_dwordx4 v[172:173], off
	v_lshl_add_u64 v[172:173], s[36:37], 0, v[136:137]
	s_add_i32 m0, s23, 0x2000
	s_nop 0
	global_load_lds_dwordx4 v[172:173], off
	s_waitcnt vmcnt(6)
	s_barrier
	s_setprio 1
	v_mfma_f32_16x16x32_bf16 v[54:57], v[230:233], v[188:191], v[54:57]
	v_mfma_f32_16x16x32_bf16 v[50:53], v[238:241], v[188:191], v[50:53]
	v_mfma_f32_16x16x32_bf16 v[38:41], v[230:233], v[196:199], v[38:41]
	v_mfma_f32_16x16x32_bf16 v[34:37], v[238:241], v[196:199], v[34:37]
	v_mfma_f32_16x16x32_bf16 v[22:25], v[230:233], v[214:217], v[22:25]
	v_mfma_f32_16x16x32_bf16 v[18:21], v[238:241], v[214:217], v[18:21]
	v_mfma_f32_16x16x32_bf16 v[6:9], v[230:233], v[222:225], v[6:9]
	v_mfma_f32_16x16x32_bf16 v[2:5], v[238:241], v[222:225], v[2:5]
	v_mfma_f32_16x16x32_bf16 v[54:57], v[234:237], v[192:195], v[54:57]
	v_mfma_f32_16x16x32_bf16 v[50:53], v[242:245], v[192:195], v[50:53]
	v_mfma_f32_16x16x32_bf16 v[38:41], v[234:237], v[210:213], v[38:41]
	v_mfma_f32_16x16x32_bf16 v[34:37], v[242:245], v[210:213], v[34:37]
	v_mfma_f32_16x16x32_bf16 v[22:25], v[234:237], v[218:221], v[22:25]
	v_mfma_f32_16x16x32_bf16 v[18:21], v[242:245], v[218:221], v[18:21]
	v_mfma_f32_16x16x32_bf16 v[6:9], v[234:237], v[226:229], v[6:9]
	v_mfma_f32_16x16x32_bf16 v[2:5], v[242:245], v[226:229], v[2:5]
	s_setprio 0
	v_add_u32_e32 v171, s27, v1
	s_barrier
	ds_read_b128 v[172:175], v171
	ds_read_b128 v[176:179], v171 offset:1024
	ds_read_b128 v[180:183], v171 offset:2048
	ds_read_b128 v[184:187], v171 offset:3072
	s_add_u32 s36, s46, 0x30000
	s_addc_u32 s37, s47, 0
	s_mov_b32 m0, s48
	v_lshl_add_u64 v[230:231], s[36:37], 0, v[130:131]
	ds_read_b128 v[188:191], v170 offset:32768
	ds_read_b128 v[192:195], v170 offset:33792
	ds_read_b128 v[196:199], v170 offset:34816
	ds_read_b128 v[210:213], v170 offset:35840
	ds_read_b128 v[214:217], v170 offset:36864
	ds_read_b128 v[218:221], v170 offset:37888
	ds_read_b128 v[222:225], v170 offset:38912
	ds_read_b128 v[226:229], v170 offset:39936
	global_load_lds_dwordx4 v[230:231], off
	v_lshl_add_u64 v[230:231], s[36:37], 0, v[134:135]
	s_mov_b32 m0, s49
	s_nop 0
	global_load_lds_dwordx4 v[230:231], off
	s_waitcnt lgkmcnt(8)
	s_barrier
	s_waitcnt lgkmcnt(0)
	s_setprio 1
	s_waitcnt lgkmcnt(0)
	v_mfma_f32_16x16x32_bf16 v[126:129], v[172:175], v[188:191], v[126:129]
	v_mfma_f32_16x16x32_bf16 v[122:125], v[180:183], v[188:191], v[122:125]
	v_mfma_f32_16x16x32_bf16 v[110:113], v[172:175], v[196:199], v[110:113]
	v_mfma_f32_16x16x32_bf16 v[106:109], v[180:183], v[196:199], v[106:109]
	v_mfma_f32_16x16x32_bf16 v[94:97], v[172:175], v[214:217], v[94:97]
	v_mfma_f32_16x16x32_bf16 v[90:93], v[180:183], v[214:217], v[90:93]
	v_mfma_f32_16x16x32_bf16 v[78:81], v[172:175], v[222:225], v[78:81]
	v_mfma_f32_16x16x32_bf16 v[74:77], v[180:183], v[222:225], v[74:77]
	v_mfma_f32_16x16x32_bf16 v[126:129], v[176:179], v[192:195], v[126:129]
	v_mfma_f32_16x16x32_bf16 v[122:125], v[184:187], v[192:195], v[122:125]
	v_mfma_f32_16x16x32_bf16 v[110:113], v[176:179], v[210:213], v[110:113]
	v_mfma_f32_16x16x32_bf16 v[106:109], v[184:187], v[210:213], v[106:109]
	v_mfma_f32_16x16x32_bf16 v[94:97], v[176:179], v[218:221], v[94:97]
	v_mfma_f32_16x16x32_bf16 v[90:93], v[184:187], v[218:221], v[90:93]
	v_mfma_f32_16x16x32_bf16 v[78:81], v[176:179], v[226:229], v[78:81]
	v_mfma_f32_16x16x32_bf16 v[74:77], v[184:187], v[226:229], v[74:77]
	s_setprio 0
	s_barrier
	s_add_i32 s23, s27, s13
	v_add_u32_e32 v171, s31, v1
	v_lshl_add_u64 v[144:145], v[144:145], 0, s[10:11]
	s_mov_b32 m0, s23
	ds_read_b128 v[230:233], v171
	ds_read_b128 v[234:237], v171 offset:1024
	ds_read_b128 v[238:241], v171 offset:2048
	ds_read_b128 v[242:245], v171 offset:3072
	global_load_lds_dwordx4 v[144:145], off
	v_lshl_add_u64 v[144:145], v[246:247], 0, s[10:11]
	s_add_i32 m0, s23, 0x2000
	s_nop 0
	global_load_lds_dwordx4 v[144:145], off
	s_barrier
	s_waitcnt lgkmcnt(0)
	s_setprio 1
	s_waitcnt lgkmcnt(0)
	v_mfma_f32_16x16x32_bf16 v[118:121], v[230:233], v[188:191], v[118:121]
	v_mfma_f32_16x16x32_bf16 v[114:117], v[238:241], v[188:191], v[114:117]
	v_mfma_f32_16x16x32_bf16 v[102:105], v[230:233], v[196:199], v[102:105]
	v_mfma_f32_16x16x32_bf16 v[98:101], v[238:241], v[196:199], v[98:101]
	v_mfma_f32_16x16x32_bf16 v[86:89], v[230:233], v[214:217], v[86:89]
	v_mfma_f32_16x16x32_bf16 v[82:85], v[238:241], v[214:217], v[82:85]
	v_mfma_f32_16x16x32_bf16 v[70:73], v[230:233], v[222:225], v[70:73]
	v_mfma_f32_16x16x32_bf16 v[66:69], v[238:241], v[222:225], v[66:69]
	v_mfma_f32_16x16x32_bf16 v[118:121], v[234:237], v[192:195], v[118:121]
	v_mfma_f32_16x16x32_bf16 v[114:117], v[242:245], v[192:195], v[114:117]
	v_mfma_f32_16x16x32_bf16 v[102:105], v[234:237], v[210:213], v[102:105]
	v_mfma_f32_16x16x32_bf16 v[98:101], v[242:245], v[210:213], v[98:101]
	v_mfma_f32_16x16x32_bf16 v[86:89], v[234:237], v[218:221], v[86:89]
	v_mfma_f32_16x16x32_bf16 v[82:85], v[242:245], v[218:221], v[82:85]
	v_mfma_f32_16x16x32_bf16 v[70:73], v[234:237], v[226:229], v[70:73]
	v_mfma_f32_16x16x32_bf16 v[66:69], v[242:245], v[226:229], v[66:69]
	s_setprio 0
	s_mov_b32 m0, s50
	v_lshl_add_u64 v[144:145], v[248:249], 0, s[10:11]
	s_barrier
	ds_read_b128 v[188:191], v170 offset:49152
	ds_read_b128 v[192:195], v170 offset:50176
	ds_read_b128 v[196:199], v170 offset:51200
	ds_read_b128 v[210:213], v170 offset:52224
	ds_read_b128 v[214:217], v170 offset:53248
	ds_read_b128 v[218:221], v170 offset:54272
	ds_read_b128 v[222:225], v170 offset:55296
	ds_read_b128 v[226:229], v170 offset:56320
	global_load_lds_dwordx4 v[144:145], off
	v_lshl_add_u64 v[144:145], v[250:251], 0, s[10:11]
	s_mov_b32 m0, s51
	s_nop 0
	global_load_lds_dwordx4 v[144:145], off
	s_barrier
; #define LAS __attribute__((address_space(3)))
; __device__ __forceinline__ unsigned cvt_pk_bf16(float lo, float hi) { unsigned r; asm volatile("v_cvt_pk_bf16_f32 %0, %1, %2" : "=v"(r) : "v"(lo), "v"(hi)); return r; }
; __device__ __forceinline__ float gelu_tanh(float x) { const float z = 0.7978845608f * (x + 0.044715f * x * x * x); const float th = 1.0f - 2.0f / (__expf(2.0f * z) + 1.0f); return 0.5f * x * (1.0f + th); }
; #define PG8_STAGE(bufoff, gbase, voff) do { _Pragma("unroll") for (int _i = 0; _i < 2; ++_i) \
;         __builtin_amdgcn_global_load_lds((const unsigned*)((const char*)(gbase) + (voff)[_i]), (LAS unsigned*)(lds + (bufoff) + ldsw + _i * 8192), 16, 0, 0); } while (0)
; #define PG8_WAIT_V(n) asm volatile("s_waitcnt vmcnt(" #n ")" ::: "memory")
; #define PG8_WAIT_L(n) asm volatile("s_waitcnt lgkmcnt(" #n ")" ::: "memory")
;     __device__ __forceinline__ void operator()(const f32x4 (&acc)[2][2][4][2], const Unit& u, int ui, const LAS float* rtab, int wr, int wc, int fr, int fq) const {
;         const int g = u.pm; const int n0 = wr * 64 + fr; const int lc0 = (u.pn & 1) * 256 + wc * 32 + 8 * fq;
; #pragma unroll
;         for (int ai = 0; ai < 2; ++ai)
; #pragma unroll
;             for (int m = 0; m < 4; ++m) {
;                 const int n = n0 + ai * HALF + m * 16;
; #pragma unroll
;                 for (int bj = 0; bj < 2; ++bj) {
;                     const int lc = lc0 + bj * HALF, t = lc >> 4, co = lc & 15; const int token = n * 32 + t;
;                     const f32x4 a0 = acc[ai][bj][m][0], a1 = acc[ai][bj][m][1];
;                     u32x4 w; w.x = cvt_pk_bf16(gelu_tanh(a0[0]), gelu_tanh(a0[1])); w.y = cvt_pk_bf16(gelu_tanh(a0[2]), gelu_tanh(a0[3]));
;                     w.z = cvt_pk_bf16(gelu_tanh(a1[0]), gelu_tanh(a1[1])); w.w = cvt_pk_bf16(gelu_tanh(a1[2]), gelu_tanh(a1[3]));
;                     *(u32x4*)(Y + (size_t)token * 1024 + 16 * g + co) = w;
; template <class Epi, class Sched>
; __device__ __forceinline__ void gemm_phase(LAS unsigned char* lds, const Gemm g, const Sched& S, const Epi& E) {
;     ...
;             PG8_BAR; PG8_WAIT_L(0); PG8_MMA(1, 0, At, B0); PG8_BAR; PG8_SCHED;
;             PG8_STAGE(PG8_SB(1, 1), b3 + hstepB, voffB);
;             PG8_WAIT_V(6); PG8_BAR; PG8_MMA(1, 1, At, B1); PG8_BAR;
;         }
;         E(acc, cur, ui, (const LAS float*)(lds + STAGE_BYTES), wr, wc, fr, fq);
	s_waitcnt lgkmcnt(0)
	s_setprio 1
	s_waitcnt lgkmcnt(0)
	v_mfma_f32_16x16x32_bf16 v[62:65], v[172:175], v[188:191], v[62:65]
	v_mfma_f32_16x16x32_bf16 v[58:61], v[180:183], v[188:191], v[58:61]
	v_mfma_f32_16x16x32_bf16 v[46:49], v[172:175], v[196:199], v[46:49]
	v_mfma_f32_16x16x32_bf16 v[42:45], v[180:183], v[196:199], v[42:45]
	v_mfma_f32_16x16x32_bf16 v[30:33], v[172:175], v[214:217], v[30:33]
	v_mfma_f32_16x16x32_bf16 v[26:29], v[180:183], v[214:217], v[26:29]
	v_mfma_f32_16x16x32_bf16 v[14:17], v[172:175], v[222:225], v[14:17]
	v_mfma_f32_16x16x32_bf16 v[10:13], v[180:183], v[222:225], v[10:13]
	v_mfma_f32_16x16x32_bf16 v[62:65], v[176:179], v[192:195], v[62:65]
	v_mfma_f32_16x16x32_bf16 v[58:61], v[184:187], v[192:195], v[58:61]
	v_mfma_f32_16x16x32_bf16 v[46:49], v[176:179], v[210:213], v[46:49]
	v_mfma_f32_16x16x32_bf16 v[42:45], v[184:187], v[210:213], v[42:45]
	v_mfma_f32_16x16x32_bf16 v[30:33], v[176:179], v[218:221], v[30:33]
	v_mfma_f32_16x16x32_bf16 v[26:29], v[184:187], v[218:221], v[26:29]
	v_mfma_f32_16x16x32_bf16 v[14:17], v[176:179], v[226:229], v[14:17]
	v_mfma_f32_16x16x32_bf16 v[10:13], v[184:187], v[226:229], v[10:13]
	s_setprio 0
	s_barrier
	s_add_u32 s36, s44, 0x30080
	s_addc_u32 s37, s45, 0
	s_add_i32 s23, s31, s13
	v_lshl_add_u64 v[144:145], s[36:37], 0, v[132:133]
	s_mov_b32 m0, s23
	s_nop 0
	global_load_lds_dwordx4 v[144:145], off
	v_lshl_add_u64 v[144:145], s[36:37], 0, v[136:137]
	s_add_i32 m0, s23, 0x2000
	s_nop 0
	global_load_lds_dwordx4 v[144:145], off
	s_waitcnt vmcnt(6)
	s_barrier
	s_setprio 1
	v_mfma_f32_16x16x32_bf16 v[54:57], v[230:233], v[188:191], v[54:57]
	v_mfma_f32_16x16x32_bf16 v[50:53], v[238:241], v[188:191], v[50:53]
	v_mfma_f32_16x16x32_bf16 v[38:41], v[230:233], v[196:199], v[38:41]
	v_mfma_f32_16x16x32_bf16 v[34:37], v[238:241], v[196:199], v[34:37]
	v_mfma_f32_16x16x32_bf16 v[22:25], v[230:233], v[214:217], v[22:25]
	v_mfma_f32_16x16x32_bf16 v[18:21], v[238:241], v[214:217], v[18:21]
	v_mfma_f32_16x16x32_bf16 v[6:9], v[230:233], v[222:225], v[6:9]
	v_mfma_f32_16x16x32_bf16 v[2:5], v[238:241], v[222:225], v[2:5]
	v_mfma_f32_16x16x32_bf16 v[54:57], v[234:237], v[192:195], v[54:57]
	v_mfma_f32_16x16x32_bf16 v[50:53], v[242:245], v[192:195], v[50:53]
	v_mfma_f32_16x16x32_bf16 v[38:41], v[234:237], v[210:213], v[38:41]
	v_mfma_f32_16x16x32_bf16 v[34:37], v[242:245], v[210:213], v[34:37]
	v_mfma_f32_16x16x32_bf16 v[22:25], v[234:237], v[218:221], v[22:25]
	v_mfma_f32_16x16x32_bf16 v[18:21], v[242:245], v[218:221], v[18:21]
	v_mfma_f32_16x16x32_bf16 v[6:9], v[234:237], v[226:229], v[6:9]
	v_mfma_f32_16x16x32_bf16 v[2:5], v[242:245], v[226:229], v[2:5]
	s_setprio 0
	s_add_i32 s54, s54, 2
	s_add_u32 s28, s28, 0x100
	s_addc_u32 s29, s29, 0
	s_cmp_gt_u32 s54, 9
	s_mov_b64 s[36:37], s[42:43]
	s_barrier
	s_cbranch_scc0 .LBB0_595
	v_mul_f32_e32 v144, 0x3d372713, v126
	v_mul_f32_e32 v144, v126, v144
	v_fma_f32 v144, v126, v144, v126
	v_mul_f32_e32 v144, 0x3f4c422a, v144
	v_add_f32_e32 v144, v144, v144
	v_mul_f32_e32 v144, 0x3fb8aa3b, v144
	v_exp_f32_e32 v144, v144
	v_mul_f32_e32 v126, 0.5, v126
	s_lshl_b32 s23, s26, 8
	s_and_b32 s23, s23, 0x100
	v_add_f32_e32 v145, 1.0, v144
	v_div_scale_f32 v172, s[28:29], v145, v145, 2.0
	v_rcp_f32_e32 v173, v172
	v_or_b32_e32 v144, s23, v162
	v_lshrrev_b32_e32 v171, 4, v144
	v_or_b32_e32 v144, v171, v146
	v_fma_f32 v174, -v172, v173, 1.0
	v_fmac_f32_e32 v173, v174, v173
	v_div_scale_f32 v174, vcc, 2.0, v145, 2.0
	v_mul_f32_e32 v175, v174, v173
	v_mul_f32_e32 v174, 0x3d372713, v127
	v_mul_f32_e32 v174, v127, v174
	v_fma_f32 v174, v127, v174, v127
	v_mul_f32_e32 v174, 0x3f4c422a, v174
	v_add_f32_e32 v174, v174, v174
	v_mul_f32_e32 v174, 0x3fb8aa3b, v174
	v_exp_f32_e32 v174, v174
	v_rcp_f32_e32 v145, v145
	s_nop 0
	v_add_f32_e32 v145, v145, v145
	v_sub_f32_e32 v145, 1.0, v145
	v_add_f32_e32 v172, 1.0, v174
	v_div_scale_f32 v173, s[28:29], v172, v172, 2.0
	v_rcp_f32_e32 v174, v173
	v_add_f32_e32 v145, 1.0, v145
	v_mul_f32_e32 v126, v126, v145
	v_mul_f32_e32 v127, 0.5, v127
	v_fma_f32 v145, -v173, v174, 1.0
	v_fmac_f32_e32 v174, v145, v174
	v_div_scale_f32 v145, vcc, 2.0, v172, 2.0
	v_mul_f32_e32 v175, v145, v174
	v_fma_f32 v176, -v173, v175, v145
	v_mul_f32_e32 v173, 0x3d372713, v128
	v_mul_f32_e32 v173, v128, v173
	v_fma_f32 v173, v128, v173, v128
	v_mul_f32_e32 v173, 0x3f4c422a, v173
	v_add_f32_e32 v173, v173, v173
	v_mul_f32_e32 v173, 0x3fb8aa3b, v173
	v_exp_f32_e32 v173, v173
	v_rcp_f32_e32 v145, v172
	s_nop 0
	v_add_f32_e32 v145, v145, v145
	v_sub_f32_e32 v145, 1.0, v145
	v_add_f32_e32 v172, 1.0, v173
	v_add_f32_e32 v145, 1.0, v145
	v_mul_f32_e32 v127, v127, v145
	v_cvt_pk_bf16_f32 v126, v126, v127
	v_mul_f32_e32 v173, 0x3d372713, v129
	v_mul_f32_e32 v173, v129, v173
	v_fma_f32 v173, v129, v173, v129
	v_mul_f32_e32 v173, 0x3f4c422a, v173
	v_add_f32_e32 v173, v173, v173
	v_mul_f32_e32 v173, 0x3fb8aa3b, v173
	v_exp_f32_e32 v173, v173
	v_rcp_f32_e32 v127, v172
	s_nop 0
	v_add_f32_e32 v127, v127, v127
	v_sub_f32_e32 v127, 1.0, v127
	v_add_f32_e32 v145, 1.0, v173
	v_div_scale_f32 v172, s[28:29], v145, v145, 2.0
	v_rcp_f32_e32 v173, v172
	v_mul_f32_e32 v128, 0.5, v128
	v_add_f32_e32 v127, 1.0, v127
	v_mul_f32_e32 v127, v128, v127
	v_fma_f32 v128, -v172, v173, 1.0
	v_fmac_f32_e32 v173, v128, v173
	v_div_scale_f32 v128, vcc, 2.0, v145, 2.0
	v_mul_f32_e32 v174, v128, v173
	v_fma_f32 v175, -v172, v174, v128
	v_mul_f32_e32 v172, 0x3d372713, v122
	v_mul_f32_e32 v172, v122, v172
	v_fma_f32 v172, v122, v172, v122
	v_mul_f32_e32 v172, 0x3f4c422a, v172
	v_add_f32_e32 v172, v172, v172
	v_mul_f32_e32 v172, 0x3fb8aa3b, v172
	v_exp_f32_e32 v172, v172
	v_rcp_f32_e32 v128, v145
; #define LAS __attribute__((address_space(3)))
; __device__ __forceinline__ unsigned cvt_pk_bf16(float lo, float hi) { unsigned r; asm volatile("v_cvt_pk_bf16_f32 %0, %1, %2" : "=v"(r) : "v"(lo), "v"(hi)); return r; }
; __device__ __forceinline__ float gelu_tanh(float x) { const float z = 0.7978845608f * (x + 0.044715f * x * x * x); const float th = 1.0f - 2.0f / (__expf(2.0f * z) + 1.0f); return 0.5f * x * (1.0f + th); }
;     __device__ __forceinline__ void operator()(const f32x4 (&acc)[2][2][4][2], const Unit& u, int ui, const LAS float* rtab, int wr, int wc, int fr, int fq) const {
;         const int g = u.pm; const int n0 = wr * 64 + fr; const int lc0 = (u.pn & 1) * 256 + wc * 32 + 8 * fq;
; #pragma unroll
;         for (int ai = 0; ai < 2; ++ai)
; #pragma unroll
;             for (int m = 0; m < 4; ++m) {
;                 const int n = n0 + ai * HALF + m * 16;
; #pragma unroll
;                 for (int bj = 0; bj < 2; ++bj) {
;                     const int lc = lc0 + bj * HALF, t = lc >> 4, co = lc & 15; const int token = n * 32 + t;
;                     const f32x4 a0 = acc[ai][bj][m][0], a1 = acc[ai][bj][m][1];
;                     u32x4 w; w.x = cvt_pk_bf16(gelu_tanh(a0[0]), gelu_tanh(a0[1])); w.y = cvt_pk_bf16(gelu_tanh(a0[2]), gelu_tanh(a0[3]));
;                     w.z = cvt_pk_bf16(gelu_tanh(a1[0]), gelu_tanh(a1[1])); w.w = cvt_pk_bf16(gelu_tanh(a1[2]), gelu_tanh(a1[3]));
;                     *(u32x4*)(Y + (size_t)token * 1024 + 16 * g + co) = w;
	s_nop 0
	v_add_f32_e32 v128, v128, v128
	v_sub_f32_e32 v128, 1.0, v128
	v_add_f32_e32 v145, 1.0, v172
	v_mul_f32_e32 v129, 0.5, v129
	v_add_f32_e32 v128, 1.0, v128
	v_mul_f32_e32 v128, v129, v128
	v_cvt_pk_bf16_f32 v127, v127, v128
	v_mul_f32_e32 v172, 0x3d372713, v123
	v_mul_f32_e32 v172, v123, v172
	v_fma_f32 v172, v123, v172, v123
	v_mul_f32_e32 v172, 0x3f4c422a, v172
	v_add_f32_e32 v172, v172, v172
	v_mul_f32_e32 v172, 0x3fb8aa3b, v172
	v_exp_f32_e32 v172, v172
	v_rcp_f32_e32 v128, v145
	s_nop 0
	v_add_f32_e32 v128, v128, v128
	v_sub_f32_e32 v128, 1.0, v128
	v_add_f32_e32 v129, 1.0, v172
	v_mul_f32_e32 v122, 0.5, v122
	v_add_f32_e32 v128, 1.0, v128
	v_mul_f32_e32 v122, v122, v128
	v_mul_f32_e32 v145, 0x3d372713, v124
	v_mul_f32_e32 v145, v124, v145
	v_fma_f32 v145, v124, v145, v124
	v_mul_f32_e32 v145, 0x3f4c422a, v145
	v_add_f32_e32 v145, v145, v145
	v_mul_f32_e32 v145, 0x3fb8aa3b, v145
	v_exp_f32_e32 v145, v145
	v_rcp_f32_e32 v128, v129
	s_nop 0
	v_add_f32_e32 v128, v128, v128
	v_sub_f32_e32 v128, 1.0, v128
	v_add_f32_e32 v129, 1.0, v145
	v_mul_f32_e32 v123, 0.5, v123
	v_add_f32_e32 v128, 1.0, v128
	v_mul_f32_e32 v123, v123, v128
	v_cvt_pk_bf16_f32 v128, v122, v123
	v_mul_f32_e32 v145, 0x3d372713, v125
	v_mul_f32_e32 v145, v125, v145
	v_fma_f32 v145, v125, v145, v125
	v_mul_f32_e32 v145, 0x3f4c422a, v145
	v_add_f32_e32 v145, v145, v145
	v_mul_f32_e32 v145, 0x3fb8aa3b, v145
	v_exp_f32_e32 v145, v145
	v_rcp_f32_e32 v122, v129
	s_nop 0
	v_add_f32_e32 v122, v122, v122
	v_sub_f32_e32 v122, 1.0, v122
	v_add_f32_e32 v123, 1.0, v145
	v_mul_f32_e32 v124, 0.5, v124
	v_add_f32_e32 v122, 1.0, v122
	v_mul_f32_e32 v122, v124, v122
	v_rcp_f32_e32 v123, v123
	s_nop 0
	v_add_f32_e32 v123, v123, v123
	v_sub_f32_e32 v123, 1.0, v123
	v_mul_f32_e32 v124, 0.5, v125
	v_add_f32_e32 v123, 1.0, v123
	v_mul_f32_e32 v123, v124, v123
	v_cvt_pk_bf16_f32 v129, v122, v123
	v_mul_f32_e32 v122, 0x3d372713, v118
	v_mul_f32_e32 v122, v118, v122
	v_fma_f32 v122, v118, v122, v118
	v_mul_f32_e32 v122, 0x3f4c422a, v122
	v_add_f32_e32 v122, v122, v122
	v_mul_f32_e32 v122, 0x3fb8aa3b, v122
	v_exp_f32_e32 v124, v122
	v_ashrrev_i32_e32 v145, 31, v144
	v_lshlrev_b64 v[122:123], 11, v[144:145]
	v_lshl_add_u64 v[122:123], v[138:139], 0, v[122:123]
	v_add_f32_e32 v125, 1.0, v124
	global_store_dwordx4 v[122:123], v[126:129], off
	v_mul_f32_e32 v118, 0.5, v118
	v_or_b32_e32 v124, 8, v171
	v_mul_f32_e32 v127, 0x3d372713, v119
	v_mul_f32_e32 v127, v119, v127
	v_fma_f32 v127, v119, v127, v119
	v_mul_f32_e32 v127, 0x3f4c422a, v127
	v_add_f32_e32 v127, v127, v127
	v_mul_f32_e32 v127, 0x3fb8aa3b, v127
	v_exp_f32_e32 v127, v127
	v_rcp_f32_e32 v123, v125
	s_nop 0
	v_add_f32_e32 v123, v123, v123
	v_add_f32_e32 v125, 1.0, v127
	v_sub_f32_e32 v123, 1.0, v123
	v_add_f32_e32 v123, 1.0, v123
	v_mul_f32_e32 v118, v118, v123
	v_mul_f32_e32 v126, 0x3d372713, v120
	v_mul_f32_e32 v126, v120, v126
	v_fma_f32 v126, v120, v126, v120
	v_mul_f32_e32 v126, 0x3f4c422a, v126
	v_add_f32_e32 v126, v126, v126
	v_mul_f32_e32 v126, 0x3fb8aa3b, v126
	v_exp_f32_e32 v126, v126
	v_rcp_f32_e32 v123, v125
	s_nop 0
	v_add_f32_e32 v123, v123, v123
	v_sub_f32_e32 v123, 1.0, v123
	v_add_f32_e32 v125, 1.0, v126
	v_mul_f32_e32 v119, 0.5, v119
	v_add_f32_e32 v123, 1.0, v123
	v_mul_f32_e32 v119, v119, v123
	v_cvt_pk_bf16_f32 v118, v118, v119
	v_mul_f32_e32 v126, 0x3d372713, v121
	v_mul_f32_e32 v126, v121, v126
	v_fma_f32 v126, v121, v126, v121
	v_mul_f32_e32 v126, 0x3f4c422a, v126
	v_add_f32_e32 v126, v126, v126
	v_mul_f32_e32 v126, 0x3fb8aa3b, v126
	v_exp_f32_e32 v126, v126
	v_rcp_f32_e32 v119, v125
	s_nop 0
	v_add_f32_e32 v119, v119, v119
	v_sub_f32_e32 v119, 1.0, v119
	v_add_f32_e32 v123, 1.0, v126
	v_mul_f32_e32 v120, 0.5, v120
	v_add_f32_e32 v119, 1.0, v119
	v_mul_f32_e32 v119, v120, v119
	v_mul_f32_e32 v125, 0x3d372713, v114
	v_mul_f32_e32 v125, v114, v125
	v_fma_f32 v125, v114, v125, v114
	v_mul_f32_e32 v125, 0x3f4c422a, v125
	v_add_f32_e32 v125, v125, v125
	v_mul_f32_e32 v125, 0x3fb8aa3b, v125
	v_exp_f32_e32 v125, v125
	v_rcp_f32_e32 v120, v123
	s_nop 0
	v_add_f32_e32 v120, v120, v120
	v_sub_f32_e32 v120, 1.0, v120
	v_add_f32_e32 v123, 1.0, v125
	v_mul_f32_e32 v121, 0.5, v121
	v_add_f32_e32 v120, 1.0, v120
	v_mul_f32_e32 v120, v121, v120
	v_cvt_pk_bf16_f32 v119, v119, v120
	v_mul_f32_e32 v125, 0x3d372713, v115
	v_mul_f32_e32 v125, v115, v125
	v_fma_f32 v125, v115, v125, v115
	v_mul_f32_e32 v125, 0x3f4c422a, v125
	v_add_f32_e32 v125, v125, v125
	v_mul_f32_e32 v125, 0x3fb8aa3b, v125
	v_exp_f32_e32 v125, v125
	v_rcp_f32_e32 v120, v123
	s_nop 0
	v_add_f32_e32 v120, v120, v120
	v_sub_f32_e32 v120, 1.0, v120
	v_add_f32_e32 v121, 1.0, v125
	v_mul_f32_e32 v114, 0.5, v114
	v_add_f32_e32 v120, 1.0, v120
	v_mul_f32_e32 v114, v114, v120
	v_mul_f32_e32 v123, 0x3d372713, v116
	v_mul_f32_e32 v123, v116, v123
	v_fma_f32 v123, v116, v123, v116
	v_mul_f32_e32 v123, 0x3f4c422a, v123
	v_add_f32_e32 v123, v123, v123
	v_mul_f32_e32 v123, 0x3fb8aa3b, v123
	v_exp_f32_e32 v123, v123
	v_rcp_f32_e32 v120, v121
	s_nop 0
	v_add_f32_e32 v120, v120, v120
	v_sub_f32_e32 v120, 1.0, v120
	v_add_f32_e32 v121, 1.0, v123
	v_mul_f32_e32 v115, 0.5, v115
	v_add_f32_e32 v120, 1.0, v120
	v_mul_f32_e32 v115, v115, v120
	v_cvt_pk_bf16_f32 v120, v114, v115
	v_mul_f32_e32 v123, 0x3d372713, v117
	v_mul_f32_e32 v123, v117, v123
	v_fma_f32 v123, v117, v123, v117
	v_mul_f32_e32 v123, 0x3f4c422a, v123
	v_add_f32_e32 v123, v123, v123
	v_mul_f32_e32 v123, 0x3fb8aa3b, v123
	v_exp_f32_e32 v123, v123
	v_rcp_f32_e32 v114, v121
	s_nop 0
	v_add_f32_e32 v114, v114, v114
	v_sub_f32_e32 v114, 1.0, v114
	v_add_f32_e32 v115, 1.0, v123
	v_mul_f32_e32 v116, 0.5, v116
; #define LAS __attribute__((address_space(3)))
; __device__ __forceinline__ unsigned cvt_pk_bf16(float lo, float hi) { unsigned r; asm volatile("v_cvt_pk_bf16_f32 %0, %1, %2" : "=v"(r) : "v"(lo), "v"(hi)); return r; }
; __device__ __forceinline__ float gelu_tanh(float x) { const float z = 0.7978845608f * (x + 0.044715f * x * x * x); const float th = 1.0f - 2.0f / (__expf(2.0f * z) + 1.0f); return 0.5f * x * (1.0f + th); }
;     __device__ __forceinline__ void operator()(const f32x4 (&acc)[2][2][4][2], const Unit& u, int ui, const LAS float* rtab, int wr, int wc, int fr, int fq) const {
;         const int g = u.pm; const int n0 = wr * 64 + fr; const int lc0 = (u.pn & 1) * 256 + wc * 32 + 8 * fq;
; #pragma unroll
;         for (int ai = 0; ai < 2; ++ai)
; #pragma unroll
;             for (int m = 0; m < 4; ++m) {
;                 const int n = n0 + ai * HALF + m * 16;
; #pragma unroll
;                 for (int bj = 0; bj < 2; ++bj) {
;                     const int lc = lc0 + bj * HALF, t = lc >> 4, co = lc & 15; const int token = n * 32 + t;
;                     const f32x4 a0 = acc[ai][bj][m][0], a1 = acc[ai][bj][m][1];
;                     u32x4 w; w.x = cvt_pk_bf16(gelu_tanh(a0[0]), gelu_tanh(a0[1])); w.y = cvt_pk_bf16(gelu_tanh(a0[2]), gelu_tanh(a0[3]));
;                     w.z = cvt_pk_bf16(gelu_tanh(a1[0]), gelu_tanh(a1[1])); w.w = cvt_pk_bf16(gelu_tanh(a1[2]), gelu_tanh(a1[3]));
;                     *(u32x4*)(Y + (size_t)token * 1024 + 16 * g + co) = w;
	v_add_f32_e32 v114, 1.0, v114
	v_mul_f32_e32 v114, v116, v114
	v_rcp_f32_e32 v115, v115
	s_nop 0
	v_add_f32_e32 v115, v115, v115
	v_sub_f32_e32 v115, 1.0, v115
	v_mul_f32_e32 v116, 0.5, v117
	v_add_f32_e32 v115, 1.0, v115
	v_mul_f32_e32 v115, v116, v115
	v_mul_f32_e32 v116, 0x3d372713, v110
	v_mul_f32_e32 v116, v110, v116
	v_fma_f32 v116, v110, v116, v110
	v_mul_f32_e32 v116, 0x3f4c422a, v116
	v_add_f32_e32 v116, v116, v116
	v_mul_f32_e32 v116, 0x3fb8aa3b, v116
	v_exp_f32_e32 v116, v116
	v_or_b32_e32 v122, v124, v146
	v_ashrrev_i32_e32 v123, 31, v122
	v_cvt_pk_bf16_f32 v121, v114, v115
	v_add_f32_e32 v116, 1.0, v116
	v_lshlrev_b64 v[114:115], 11, v[122:123]
	v_lshl_add_u64 v[114:115], v[138:139], 0, v[114:115]
	global_store_dwordx4 v[114:115], v[118:121], off
	v_mul_f32_e32 v110, 0.5, v110
	v_mul_f32_e32 v117, 0x3d372713, v111
	v_mul_f32_e32 v117, v111, v117
	v_fma_f32 v117, v111, v117, v111
	v_mul_f32_e32 v117, 0x3f4c422a, v117
	v_add_f32_e32 v117, v117, v117
	v_mul_f32_e32 v117, 0x3fb8aa3b, v117
	v_exp_f32_e32 v117, v117
	v_rcp_f32_e32 v115, v116
	s_nop 0
	v_add_f32_e32 v115, v115, v115
	v_sub_f32_e32 v115, 1.0, v115
	v_add_f32_e32 v116, 1.0, v117
	v_add_f32_e32 v115, 1.0, v115
	v_mul_f32_e32 v110, v110, v115
	v_mul_f32_e32 v111, 0.5, v111
	v_mul_f32_e32 v117, 0x3d372713, v112
	v_mul_f32_e32 v117, v112, v117
	v_fma_f32 v117, v112, v117, v112
	v_mul_f32_e32 v117, 0x3f4c422a, v117
	v_add_f32_e32 v117, v117, v117
	v_mul_f32_e32 v117, 0x3fb8aa3b, v117
	v_exp_f32_e32 v117, v117
	v_rcp_f32_e32 v115, v116
	s_nop 0
	v_add_f32_e32 v115, v115, v115
	v_sub_f32_e32 v115, 1.0, v115
	v_add_f32_e32 v116, 1.0, v117
	v_add_f32_e32 v115, 1.0, v115
	v_mul_f32_e32 v111, v111, v115
	v_cvt_pk_bf16_f32 v110, v110, v111
	v_mul_f32_e32 v117, 0x3d372713, v113
	v_mul_f32_e32 v117, v113, v117
	v_fma_f32 v117, v113, v117, v113
	v_mul_f32_e32 v117, 0x3f4c422a, v117
	v_add_f32_e32 v117, v117, v117
	v_mul_f32_e32 v117, 0x3fb8aa3b, v117
	v_exp_f32_e32 v117, v117
	v_rcp_f32_e32 v111, v116
	s_nop 0
	v_add_f32_e32 v111, v111, v111
	v_sub_f32_e32 v111, 1.0, v111
	v_add_f32_e32 v115, 1.0, v117
	v_mul_f32_e32 v112, 0.5, v112
	v_add_f32_e32 v111, 1.0, v111
	v_mul_f32_e32 v111, v112, v111
	v_mul_f32_e32 v116, 0x3d372713, v106
	v_mul_f32_e32 v116, v106, v116
	v_fma_f32 v116, v106, v116, v106
	v_mul_f32_e32 v116, 0x3f4c422a, v116
	v_add_f32_e32 v116, v116, v116
	v_mul_f32_e32 v116, 0x3fb8aa3b, v116
	v_exp_f32_e32 v116, v116
	v_rcp_f32_e32 v112, v115
	s_nop 0
	v_add_f32_e32 v112, v112, v112
	v_sub_f32_e32 v112, 1.0, v112
	v_add_f32_e32 v115, 1.0, v116
	v_mul_f32_e32 v113, 0.5, v113
	v_add_f32_e32 v112, 1.0, v112
	v_mul_f32_e32 v112, v113, v112
	v_cvt_pk_bf16_f32 v111, v111, v112
	v_mul_f32_e32 v116, 0x3d372713, v107
	v_mul_f32_e32 v116, v107, v116
	v_fma_f32 v116, v107, v116, v107
	v_mul_f32_e32 v116, 0x3f4c422a, v116
	v_add_f32_e32 v116, v116, v116
	v_mul_f32_e32 v116, 0x3fb8aa3b, v116
	v_exp_f32_e32 v116, v116
	v_rcp_f32_e32 v112, v115
	s_nop 0
	v_add_f32_e32 v112, v112, v112
	v_sub_f32_e32 v112, 1.0, v112
	v_add_f32_e32 v113, 1.0, v116
	v_mul_f32_e32 v106, 0.5, v106
	v_add_f32_e32 v112, 1.0, v112
	v_mul_f32_e32 v106, v106, v112
	v_mul_f32_e32 v115, 0x3d372713, v108
	v_mul_f32_e32 v115, v108, v115
	v_fma_f32 v115, v108, v115, v108
	v_mul_f32_e32 v115, 0x3f4c422a, v115
	v_add_f32_e32 v115, v115, v115
	v_mul_f32_e32 v115, 0x3fb8aa3b, v115
	v_exp_f32_e32 v115, v115
	v_rcp_f32_e32 v112, v113
	s_nop 0
	v_add_f32_e32 v112, v112, v112
	v_sub_f32_e32 v112, 1.0, v112
	v_add_f32_e32 v113, 1.0, v115
	v_mul_f32_e32 v107, 0.5, v107
	v_add_f32_e32 v112, 1.0, v112
	v_mul_f32_e32 v107, v107, v112
	v_cvt_pk_bf16_f32 v112, v106, v107
	v_mul_f32_e32 v115, 0x3d372713, v109
	v_mul_f32_e32 v115, v109, v115
	v_fma_f32 v115, v109, v115, v109
	v_mul_f32_e32 v115, 0x3f4c422a, v115
	v_add_f32_e32 v115, v115, v115
	v_mul_f32_e32 v115, 0x3fb8aa3b, v115
	v_exp_f32_e32 v115, v115
	v_rcp_f32_e32 v106, v113
	s_nop 0
	v_add_f32_e32 v106, v106, v106
	v_sub_f32_e32 v106, 1.0, v106
	v_add_f32_e32 v107, 1.0, v115
	v_mul_f32_e32 v108, 0.5, v108
	v_add_f32_e32 v106, 1.0, v106
	v_mul_f32_e32 v106, v108, v106
	v_rcp_f32_e32 v107, v107
	s_nop 0
	v_add_f32_e32 v107, v107, v107
	v_sub_f32_e32 v107, 1.0, v107
	v_mul_f32_e32 v108, 0.5, v109
	v_add_f32_e32 v107, 1.0, v107
	v_mul_f32_e32 v107, v108, v107
	v_mul_f32_e32 v108, 0x3d372713, v102
	v_mul_f32_e32 v108, v102, v108
	v_fma_f32 v108, v102, v108, v102
	v_mul_f32_e32 v108, 0x3f4c422a, v108
	v_add_f32_e32 v108, v108, v108
	v_mul_f32_e32 v108, 0x3fb8aa3b, v108
	v_exp_f32_e32 v108, v108
	v_or_b32_e32 v114, v171, v147
	v_ashrrev_i32_e32 v115, 31, v114
	v_cvt_pk_bf16_f32 v113, v106, v107
	v_add_f32_e32 v108, 1.0, v108
	v_lshlrev_b64 v[106:107], 11, v[114:115]
	v_lshl_add_u64 v[106:107], v[138:139], 0, v[106:107]
	global_store_dwordx4 v[106:107], v[110:113], off
	v_mul_f32_e32 v102, 0.5, v102
	v_mul_f32_e32 v109, 0x3d372713, v103
	v_mul_f32_e32 v109, v103, v109
	v_fma_f32 v109, v103, v109, v103
	v_mul_f32_e32 v109, 0x3f4c422a, v109
	v_add_f32_e32 v109, v109, v109
	v_mul_f32_e32 v109, 0x3fb8aa3b, v109
	v_exp_f32_e32 v109, v109
	v_rcp_f32_e32 v107, v108
	s_nop 0
	v_add_f32_e32 v107, v107, v107
	v_sub_f32_e32 v107, 1.0, v107
	v_add_f32_e32 v108, 1.0, v109
	v_add_f32_e32 v107, 1.0, v107
	v_mul_f32_e32 v102, v102, v107
	v_mul_f32_e32 v103, 0.5, v103
	v_mul_f32_e32 v109, 0x3d372713, v104
	v_mul_f32_e32 v109, v104, v109
	v_fma_f32 v109, v104, v109, v104
	v_mul_f32_e32 v109, 0x3f4c422a, v109
	v_add_f32_e32 v109, v109, v109
	v_mul_f32_e32 v109, 0x3fb8aa3b, v109
	v_exp_f32_e32 v109, v109
	v_rcp_f32_e32 v107, v108
	s_nop 0
	v_add_f32_e32 v107, v107, v107
	v_sub_f32_e32 v107, 1.0, v107
; #define LAS __attribute__((address_space(3)))
; __device__ __forceinline__ unsigned cvt_pk_bf16(float lo, float hi) { unsigned r; asm volatile("v_cvt_pk_bf16_f32 %0, %1, %2" : "=v"(r) : "v"(lo), "v"(hi)); return r; }
; __device__ __forceinline__ float gelu_tanh(float x) { const float z = 0.7978845608f * (x + 0.044715f * x * x * x); const float th = 1.0f - 2.0f / (__expf(2.0f * z) + 1.0f); return 0.5f * x * (1.0f + th); }
;     __device__ __forceinline__ void operator()(const f32x4 (&acc)[2][2][4][2], const Unit& u, int ui, const LAS float* rtab, int wr, int wc, int fr, int fq) const {
;         const int g = u.pm; const int n0 = wr * 64 + fr; const int lc0 = (u.pn & 1) * 256 + wc * 32 + 8 * fq;
; #pragma unroll
;         for (int ai = 0; ai < 2; ++ai)
; #pragma unroll
;             for (int m = 0; m < 4; ++m) {
;                 const int n = n0 + ai * HALF + m * 16;
; #pragma unroll
;                 for (int bj = 0; bj < 2; ++bj) {
;                     const int lc = lc0 + bj * HALF, t = lc >> 4, co = lc & 15; const int token = n * 32 + t;
;                     const f32x4 a0 = acc[ai][bj][m][0], a1 = acc[ai][bj][m][1];
;                     u32x4 w; w.x = cvt_pk_bf16(gelu_tanh(a0[0]), gelu_tanh(a0[1])); w.y = cvt_pk_bf16(gelu_tanh(a0[2]), gelu_tanh(a0[3]));
;                     w.z = cvt_pk_bf16(gelu_tanh(a1[0]), gelu_tanh(a1[1])); w.w = cvt_pk_bf16(gelu_tanh(a1[2]), gelu_tanh(a1[3]));
;                     *(u32x4*)(Y + (size_t)token * 1024 + 16 * g + co) = w;
	v_add_f32_e32 v108, 1.0, v109
	v_add_f32_e32 v107, 1.0, v107
	v_mul_f32_e32 v103, v103, v107
	v_cvt_pk_bf16_f32 v102, v102, v103
	v_mul_f32_e32 v109, 0x3d372713, v105
	v_mul_f32_e32 v109, v105, v109
	v_fma_f32 v109, v105, v109, v105
	v_mul_f32_e32 v109, 0x3f4c422a, v109
	v_add_f32_e32 v109, v109, v109
	v_mul_f32_e32 v109, 0x3fb8aa3b, v109
	v_exp_f32_e32 v109, v109
	v_rcp_f32_e32 v103, v108
	s_nop 0
	v_add_f32_e32 v103, v103, v103
	v_sub_f32_e32 v103, 1.0, v103
	v_add_f32_e32 v107, 1.0, v109
	v_mul_f32_e32 v104, 0.5, v104
	v_add_f32_e32 v103, 1.0, v103
	v_mul_f32_e32 v103, v104, v103
	v_mul_f32_e32 v108, 0x3d372713, v98
	v_mul_f32_e32 v108, v98, v108
	v_fma_f32 v108, v98, v108, v98
	v_mul_f32_e32 v108, 0x3f4c422a, v108
	v_add_f32_e32 v108, v108, v108
	v_mul_f32_e32 v108, 0x3fb8aa3b, v108
	v_exp_f32_e32 v108, v108
	v_rcp_f32_e32 v104, v107
	s_nop 0
	v_add_f32_e32 v104, v104, v104
	v_sub_f32_e32 v104, 1.0, v104
	v_add_f32_e32 v107, 1.0, v108
	v_mul_f32_e32 v105, 0.5, v105
	v_add_f32_e32 v104, 1.0, v104
	v_mul_f32_e32 v104, v105, v104
	v_cvt_pk_bf16_f32 v103, v103, v104
	v_mul_f32_e32 v108, 0x3d372713, v99
	v_mul_f32_e32 v108, v99, v108
	v_fma_f32 v108, v99, v108, v99
	v_mul_f32_e32 v108, 0x3f4c422a, v108
	v_add_f32_e32 v108, v108, v108
	v_mul_f32_e32 v108, 0x3fb8aa3b, v108
	v_exp_f32_e32 v108, v108
	v_rcp_f32_e32 v104, v107
	s_nop 0
	v_add_f32_e32 v104, v104, v104
	v_sub_f32_e32 v104, 1.0, v104
	v_add_f32_e32 v105, 1.0, v108
	v_mul_f32_e32 v98, 0.5, v98
	v_add_f32_e32 v104, 1.0, v104
	v_mul_f32_e32 v98, v98, v104
	v_mul_f32_e32 v107, 0x3d372713, v100
	v_mul_f32_e32 v107, v100, v107
	v_fma_f32 v107, v100, v107, v100
	v_mul_f32_e32 v107, 0x3f4c422a, v107
	v_add_f32_e32 v107, v107, v107
	v_mul_f32_e32 v107, 0x3fb8aa3b, v107
	v_exp_f32_e32 v107, v107
	v_rcp_f32_e32 v104, v105
	s_nop 0
	v_add_f32_e32 v104, v104, v104
	v_sub_f32_e32 v104, 1.0, v104
	v_add_f32_e32 v105, 1.0, v107
	v_mul_f32_e32 v99, 0.5, v99
	v_add_f32_e32 v104, 1.0, v104
	v_mul_f32_e32 v99, v99, v104
	v_cvt_pk_bf16_f32 v104, v98, v99
	v_mul_f32_e32 v107, 0x3d372713, v101
	v_mul_f32_e32 v107, v101, v107
	v_fma_f32 v107, v101, v107, v101
	v_mul_f32_e32 v107, 0x3f4c422a, v107
	v_add_f32_e32 v107, v107, v107
	v_mul_f32_e32 v107, 0x3fb8aa3b, v107
	v_exp_f32_e32 v107, v107
	v_rcp_f32_e32 v98, v105
	s_nop 0
	v_add_f32_e32 v98, v98, v98
	v_sub_f32_e32 v98, 1.0, v98
	v_add_f32_e32 v99, 1.0, v107
	v_mul_f32_e32 v100, 0.5, v100
	v_add_f32_e32 v98, 1.0, v98
	v_mul_f32_e32 v98, v100, v98
	v_rcp_f32_e32 v99, v99
	s_nop 0
	v_add_f32_e32 v99, v99, v99
	v_sub_f32_e32 v99, 1.0, v99
	v_mul_f32_e32 v100, 0.5, v101
	v_add_f32_e32 v99, 1.0, v99
	v_mul_f32_e32 v99, v100, v99
	v_mul_f32_e32 v100, 0x3d372713, v94
	v_mul_f32_e32 v100, v94, v100
	v_fma_f32 v100, v94, v100, v94
	v_mul_f32_e32 v100, 0x3f4c422a, v100
	v_add_f32_e32 v100, v100, v100
	v_mul_f32_e32 v100, 0x3fb8aa3b, v100
	v_exp_f32_e32 v100, v100
	v_or_b32_e32 v106, v124, v147
	v_ashrrev_i32_e32 v107, 31, v106
	v_cvt_pk_bf16_f32 v105, v98, v99
	v_add_f32_e32 v100, 1.0, v100
	v_lshlrev_b64 v[98:99], 11, v[106:107]
	v_lshl_add_u64 v[98:99], v[138:139], 0, v[98:99]
	global_store_dwordx4 v[98:99], v[102:105], off
	v_mul_f32_e32 v94, 0.5, v94
	v_mul_f32_e32 v101, 0x3d372713, v95
	v_mul_f32_e32 v101, v95, v101
	v_fma_f32 v101, v95, v101, v95
	v_mul_f32_e32 v101, 0x3f4c422a, v101
	v_add_f32_e32 v101, v101, v101
	v_mul_f32_e32 v101, 0x3fb8aa3b, v101
	v_exp_f32_e32 v101, v101
	v_rcp_f32_e32 v99, v100
	s_nop 0
	v_add_f32_e32 v99, v99, v99
	v_sub_f32_e32 v99, 1.0, v99
	v_add_f32_e32 v100, 1.0, v101
	v_add_f32_e32 v99, 1.0, v99
	v_mul_f32_e32 v94, v94, v99
	v_mul_f32_e32 v95, 0.5, v95
	v_mul_f32_e32 v101, 0x3d372713, v96
	v_mul_f32_e32 v101, v96, v101
	v_fma_f32 v101, v96, v101, v96
	v_mul_f32_e32 v101, 0x3f4c422a, v101
	v_add_f32_e32 v101, v101, v101
	v_mul_f32_e32 v101, 0x3fb8aa3b, v101
	v_exp_f32_e32 v101, v101
	v_rcp_f32_e32 v99, v100
	s_nop 0
	v_add_f32_e32 v99, v99, v99
	v_sub_f32_e32 v99, 1.0, v99
	v_add_f32_e32 v100, 1.0, v101
	v_add_f32_e32 v99, 1.0, v99
	v_mul_f32_e32 v95, v95, v99
	v_cvt_pk_bf16_f32 v94, v94, v95
	v_mul_f32_e32 v101, 0x3d372713, v97
	v_mul_f32_e32 v101, v97, v101
	v_fma_f32 v101, v97, v101, v97
	v_mul_f32_e32 v101, 0x3f4c422a, v101
	v_add_f32_e32 v101, v101, v101
	v_mul_f32_e32 v101, 0x3fb8aa3b, v101
	v_exp_f32_e32 v101, v101
	v_rcp_f32_e32 v95, v100
	s_nop 0
	v_add_f32_e32 v95, v95, v95
	v_sub_f32_e32 v95, 1.0, v95
	v_add_f32_e32 v99, 1.0, v101
	v_mul_f32_e32 v96, 0.5, v96
	v_add_f32_e32 v95, 1.0, v95
	v_mul_f32_e32 v95, v96, v95
	v_mul_f32_e32 v100, 0x3d372713, v90
	v_mul_f32_e32 v100, v90, v100
	v_fma_f32 v100, v90, v100, v90
	v_mul_f32_e32 v100, 0x3f4c422a, v100
	v_add_f32_e32 v100, v100, v100
	v_mul_f32_e32 v100, 0x3fb8aa3b, v100
	v_exp_f32_e32 v100, v100
	v_rcp_f32_e32 v96, v99
	s_nop 0
	v_add_f32_e32 v96, v96, v96
	v_sub_f32_e32 v96, 1.0, v96
	v_add_f32_e32 v99, 1.0, v100
	v_mul_f32_e32 v97, 0.5, v97
	v_add_f32_e32 v96, 1.0, v96
	v_mul_f32_e32 v96, v97, v96
	v_cvt_pk_bf16_f32 v95, v95, v96
	v_mul_f32_e32 v100, 0x3d372713, v91
	v_mul_f32_e32 v100, v91, v100
	v_fma_f32 v100, v91, v100, v91
	v_mul_f32_e32 v100, 0x3f4c422a, v100
	v_add_f32_e32 v100, v100, v100
	v_mul_f32_e32 v100, 0x3fb8aa3b, v100
	v_exp_f32_e32 v100, v100
	v_rcp_f32_e32 v96, v99
	s_nop 0
	v_add_f32_e32 v96, v96, v96
	v_sub_f32_e32 v96, 1.0, v96
	v_add_f32_e32 v97, 1.0, v100
	v_mul_f32_e32 v90, 0.5, v90
	v_add_f32_e32 v96, 1.0, v96
	v_mul_f32_e32 v90, v90, v96
	v_mul_f32_e32 v99, 0x3d372713, v92
	v_mul_f32_e32 v99, v92, v99
	v_fma_f32 v99, v92, v99, v92
	v_mul_f32_e32 v99, 0x3f4c422a, v99
	v_add_f32_e32 v99, v99, v99
	v_mul_f32_e32 v99, 0x3fb8aa3b, v99
; #define LAS __attribute__((address_space(3)))
; __device__ __forceinline__ unsigned cvt_pk_bf16(float lo, float hi) { unsigned r; asm volatile("v_cvt_pk_bf16_f32 %0, %1, %2" : "=v"(r) : "v"(lo), "v"(hi)); return r; }
; __device__ __forceinline__ float gelu_tanh(float x) { const float z = 0.7978845608f * (x + 0.044715f * x * x * x); const float th = 1.0f - 2.0f / (__expf(2.0f * z) + 1.0f); return 0.5f * x * (1.0f + th); }
;     __device__ __forceinline__ void operator()(const f32x4 (&acc)[2][2][4][2], const Unit& u, int ui, const LAS float* rtab, int wr, int wc, int fr, int fq) const {
;         const int g = u.pm; const int n0 = wr * 64 + fr; const int lc0 = (u.pn & 1) * 256 + wc * 32 + 8 * fq;
; #pragma unroll
;         for (int ai = 0; ai < 2; ++ai)
; #pragma unroll
;             for (int m = 0; m < 4; ++m) {
;                 const int n = n0 + ai * HALF + m * 16;
; #pragma unroll
;                 for (int bj = 0; bj < 2; ++bj) {
;                     const int lc = lc0 + bj * HALF, t = lc >> 4, co = lc & 15; const int token = n * 32 + t;
;                     const f32x4 a0 = acc[ai][bj][m][0], a1 = acc[ai][bj][m][1];
;                     u32x4 w; w.x = cvt_pk_bf16(gelu_tanh(a0[0]), gelu_tanh(a0[1])); w.y = cvt_pk_bf16(gelu_tanh(a0[2]), gelu_tanh(a0[3]));
;                     w.z = cvt_pk_bf16(gelu_tanh(a1[0]), gelu_tanh(a1[1])); w.w = cvt_pk_bf16(gelu_tanh(a1[2]), gelu_tanh(a1[3]));
;                     *(u32x4*)(Y + (size_t)token * 1024 + 16 * g + co) = w;
	v_exp_f32_e32 v99, v99
	v_rcp_f32_e32 v96, v97
	s_nop 0
	v_add_f32_e32 v96, v96, v96
	v_sub_f32_e32 v96, 1.0, v96
	v_add_f32_e32 v97, 1.0, v99
	v_mul_f32_e32 v91, 0.5, v91
	v_add_f32_e32 v96, 1.0, v96
	v_mul_f32_e32 v91, v91, v96
	v_cvt_pk_bf16_f32 v96, v90, v91
	v_mul_f32_e32 v99, 0x3d372713, v93
	v_mul_f32_e32 v99, v93, v99
	v_fma_f32 v99, v93, v99, v93
	v_mul_f32_e32 v99, 0x3f4c422a, v99
	v_add_f32_e32 v99, v99, v99
	v_mul_f32_e32 v99, 0x3fb8aa3b, v99
	v_exp_f32_e32 v99, v99
	v_rcp_f32_e32 v90, v97
	s_nop 0
	v_add_f32_e32 v90, v90, v90
	v_sub_f32_e32 v90, 1.0, v90
	v_add_f32_e32 v91, 1.0, v99
	v_mul_f32_e32 v92, 0.5, v92
	v_add_f32_e32 v90, 1.0, v90
	v_mul_f32_e32 v90, v92, v90
	v_rcp_f32_e32 v91, v91
	s_nop 0
	v_add_f32_e32 v91, v91, v91
	v_sub_f32_e32 v91, 1.0, v91
	v_mul_f32_e32 v92, 0.5, v93
	v_add_f32_e32 v91, 1.0, v91
	v_mul_f32_e32 v91, v92, v91
	v_mul_f32_e32 v92, 0x3d372713, v86
	v_mul_f32_e32 v92, v86, v92
	v_fma_f32 v92, v86, v92, v86
	v_mul_f32_e32 v92, 0x3f4c422a, v92
	v_add_f32_e32 v92, v92, v92
	v_mul_f32_e32 v92, 0x3fb8aa3b, v92
	v_exp_f32_e32 v92, v92
	v_or_b32_e32 v98, v171, v148
	v_ashrrev_i32_e32 v99, 31, v98
	v_cvt_pk_bf16_f32 v97, v90, v91
	v_add_f32_e32 v92, 1.0, v92
	v_lshlrev_b64 v[90:91], 11, v[98:99]
	v_lshl_add_u64 v[90:91], v[138:139], 0, v[90:91]
	global_store_dwordx4 v[90:91], v[94:97], off
	v_mul_f32_e32 v86, 0.5, v86
	v_mul_f32_e32 v93, 0x3d372713, v87
	v_mul_f32_e32 v93, v87, v93
	v_fma_f32 v93, v87, v93, v87
	v_mul_f32_e32 v93, 0x3f4c422a, v93
	v_add_f32_e32 v93, v93, v93
	v_mul_f32_e32 v93, 0x3fb8aa3b, v93
	v_exp_f32_e32 v93, v93
	v_rcp_f32_e32 v91, v92
	s_nop 0
	v_add_f32_e32 v91, v91, v91
	v_sub_f32_e32 v91, 1.0, v91
	v_add_f32_e32 v92, 1.0, v93
	v_add_f32_e32 v91, 1.0, v91
	v_mul_f32_e32 v86, v86, v91
	v_mul_f32_e32 v87, 0.5, v87
	v_mul_f32_e32 v93, 0x3d372713, v88
	v_mul_f32_e32 v93, v88, v93
	v_fma_f32 v93, v88, v93, v88
	v_mul_f32_e32 v93, 0x3f4c422a, v93
	v_add_f32_e32 v93, v93, v93
	v_mul_f32_e32 v93, 0x3fb8aa3b, v93
	v_exp_f32_e32 v93, v93
	v_rcp_f32_e32 v91, v92
	s_nop 0
	v_add_f32_e32 v91, v91, v91
	v_sub_f32_e32 v91, 1.0, v91
	v_add_f32_e32 v92, 1.0, v93
	v_add_f32_e32 v91, 1.0, v91
	v_mul_f32_e32 v87, v87, v91
	v_cvt_pk_bf16_f32 v86, v86, v87
	v_mul_f32_e32 v93, 0x3d372713, v89
	v_mul_f32_e32 v93, v89, v93
	v_fma_f32 v93, v89, v93, v89
	v_mul_f32_e32 v93, 0x3f4c422a, v93
	v_add_f32_e32 v93, v93, v93
	v_mul_f32_e32 v93, 0x3fb8aa3b, v93
	v_exp_f32_e32 v93, v93
	v_rcp_f32_e32 v87, v92
	s_nop 0
	v_add_f32_e32 v87, v87, v87
	v_sub_f32_e32 v87, 1.0, v87
	v_add_f32_e32 v91, 1.0, v93
	v_mul_f32_e32 v88, 0.5, v88
	v_add_f32_e32 v87, 1.0, v87
	v_mul_f32_e32 v87, v88, v87
	v_mul_f32_e32 v92, 0x3d372713, v82
	v_mul_f32_e32 v92, v82, v92
	v_fma_f32 v92, v82, v92, v82
	v_mul_f32_e32 v92, 0x3f4c422a, v92
	v_add_f32_e32 v92, v92, v92
	v_mul_f32_e32 v92, 0x3fb8aa3b, v92
	v_exp_f32_e32 v92, v92
	v_rcp_f32_e32 v88, v91
	s_nop 0
	v_add_f32_e32 v88, v88, v88
	v_sub_f32_e32 v88, 1.0, v88
	v_add_f32_e32 v91, 1.0, v92
	v_mul_f32_e32 v89, 0.5, v89
	v_add_f32_e32 v88, 1.0, v88
	v_mul_f32_e32 v88, v89, v88
	v_cvt_pk_bf16_f32 v87, v87, v88
	v_mul_f32_e32 v92, 0x3d372713, v83
	v_mul_f32_e32 v92, v83, v92
	v_fma_f32 v92, v83, v92, v83
	v_mul_f32_e32 v92, 0x3f4c422a, v92
	v_add_f32_e32 v92, v92, v92
	v_mul_f32_e32 v92, 0x3fb8aa3b, v92
	v_exp_f32_e32 v92, v92
	v_rcp_f32_e32 v88, v91
	s_nop 0
	v_add_f32_e32 v88, v88, v88
	v_sub_f32_e32 v88, 1.0, v88
	v_add_f32_e32 v89, 1.0, v92
	v_mul_f32_e32 v82, 0.5, v82
	v_add_f32_e32 v88, 1.0, v88
	v_mul_f32_e32 v82, v82, v88
	v_mul_f32_e32 v91, 0x3d372713, v84
	v_mul_f32_e32 v91, v84, v91
	v_fma_f32 v91, v84, v91, v84
	v_mul_f32_e32 v91, 0x3f4c422a, v91
	v_add_f32_e32 v91, v91, v91
	v_mul_f32_e32 v91, 0x3fb8aa3b, v91
	v_exp_f32_e32 v91, v91
	v_rcp_f32_e32 v88, v89
	s_nop 0
	v_add_f32_e32 v88, v88, v88
	v_sub_f32_e32 v88, 1.0, v88
	v_add_f32_e32 v89, 1.0, v91
	v_mul_f32_e32 v83, 0.5, v83
	v_add_f32_e32 v88, 1.0, v88
	v_mul_f32_e32 v83, v83, v88
	v_cvt_pk_bf16_f32 v88, v82, v83
	v_mul_f32_e32 v91, 0x3d372713, v85
	v_mul_f32_e32 v91, v85, v91
	v_fma_f32 v91, v85, v91, v85
	v_mul_f32_e32 v91, 0x3f4c422a, v91
	v_add_f32_e32 v91, v91, v91
	v_mul_f32_e32 v91, 0x3fb8aa3b, v91
	v_exp_f32_e32 v91, v91
	v_rcp_f32_e32 v82, v89
	s_nop 0
	v_add_f32_e32 v82, v82, v82
	v_sub_f32_e32 v82, 1.0, v82
	v_add_f32_e32 v83, 1.0, v91
	v_mul_f32_e32 v84, 0.5, v84
	v_add_f32_e32 v82, 1.0, v82
	v_mul_f32_e32 v82, v84, v82
	v_rcp_f32_e32 v83, v83
	s_nop 0
	v_add_f32_e32 v83, v83, v83
	v_sub_f32_e32 v83, 1.0, v83
	v_mul_f32_e32 v84, 0.5, v85
	v_add_f32_e32 v83, 1.0, v83
	v_mul_f32_e32 v83, v84, v83
	v_mul_f32_e32 v84, 0x3d372713, v78
	v_mul_f32_e32 v84, v78, v84
	v_fma_f32 v84, v78, v84, v78
	v_mul_f32_e32 v84, 0x3f4c422a, v84
	v_add_f32_e32 v84, v84, v84
	v_mul_f32_e32 v84, 0x3fb8aa3b, v84
	v_exp_f32_e32 v84, v84
	v_or_b32_e32 v90, v124, v148
	v_ashrrev_i32_e32 v91, 31, v90
	v_cvt_pk_bf16_f32 v89, v82, v83
	v_add_f32_e32 v84, 1.0, v84
	v_lshlrev_b64 v[82:83], 11, v[90:91]
	v_lshl_add_u64 v[82:83], v[138:139], 0, v[82:83]
	global_store_dwordx4 v[82:83], v[86:89], off
	v_mul_f32_e32 v78, 0.5, v78
	v_mul_f32_e32 v85, 0x3d372713, v79
	v_mul_f32_e32 v85, v79, v85
	v_fma_f32 v85, v79, v85, v79
	v_mul_f32_e32 v85, 0x3f4c422a, v85
	v_add_f32_e32 v85, v85, v85
	v_mul_f32_e32 v85, 0x3fb8aa3b, v85
	v_exp_f32_e32 v85, v85
	v_rcp_f32_e32 v83, v84
	s_nop 0
	v_add_f32_e32 v83, v83, v83
	v_sub_f32_e32 v83, 1.0, v83
	v_add_f32_e32 v84, 1.0, v85
	v_add_f32_e32 v83, 1.0, v83
	v_mul_f32_e32 v78, v78, v83
	v_mul_f32_e32 v79, 0.5, v79
	v_mul_f32_e32 v85, 0x3d372713, v80
	v_mul_f32_e32 v85, v80, v85
	v_fma_f32 v85, v80, v85, v80
; #define LAS __attribute__((address_space(3)))
; __device__ __forceinline__ unsigned cvt_pk_bf16(float lo, float hi) { unsigned r; asm volatile("v_cvt_pk_bf16_f32 %0, %1, %2" : "=v"(r) : "v"(lo), "v"(hi)); return r; }
; __device__ __forceinline__ float gelu_tanh(float x) { const float z = 0.7978845608f * (x + 0.044715f * x * x * x); const float th = 1.0f - 2.0f / (__expf(2.0f * z) + 1.0f); return 0.5f * x * (1.0f + th); }
;     __device__ __forceinline__ void operator()(const f32x4 (&acc)[2][2][4][2], const Unit& u, int ui, const LAS float* rtab, int wr, int wc, int fr, int fq) const {
;         const int g = u.pm; const int n0 = wr * 64 + fr; const int lc0 = (u.pn & 1) * 256 + wc * 32 + 8 * fq;
; #pragma unroll
;         for (int ai = 0; ai < 2; ++ai)
; #pragma unroll
;             for (int m = 0; m < 4; ++m) {
;                 const int n = n0 + ai * HALF + m * 16;
; #pragma unroll
;                 for (int bj = 0; bj < 2; ++bj) {
;                     const int lc = lc0 + bj * HALF, t = lc >> 4, co = lc & 15; const int token = n * 32 + t;
;                     const f32x4 a0 = acc[ai][bj][m][0], a1 = acc[ai][bj][m][1];
;                     u32x4 w; w.x = cvt_pk_bf16(gelu_tanh(a0[0]), gelu_tanh(a0[1])); w.y = cvt_pk_bf16(gelu_tanh(a0[2]), gelu_tanh(a0[3]));
;                     w.z = cvt_pk_bf16(gelu_tanh(a1[0]), gelu_tanh(a1[1])); w.w = cvt_pk_bf16(gelu_tanh(a1[2]), gelu_tanh(a1[3]));
;                     *(u32x4*)(Y + (size_t)token * 1024 + 16 * g + co) = w;
	v_mul_f32_e32 v85, 0x3f4c422a, v85
	v_add_f32_e32 v85, v85, v85
	v_mul_f32_e32 v85, 0x3fb8aa3b, v85
	v_exp_f32_e32 v85, v85
	v_rcp_f32_e32 v83, v84
	s_nop 0
	v_add_f32_e32 v83, v83, v83
	v_sub_f32_e32 v83, 1.0, v83
	v_add_f32_e32 v84, 1.0, v85
	v_add_f32_e32 v83, 1.0, v83
	v_mul_f32_e32 v79, v79, v83
	v_cvt_pk_bf16_f32 v78, v78, v79
	v_mul_f32_e32 v85, 0x3d372713, v81
	v_mul_f32_e32 v85, v81, v85
	v_fma_f32 v85, v81, v85, v81
	v_mul_f32_e32 v85, 0x3f4c422a, v85
	v_add_f32_e32 v85, v85, v85
	v_mul_f32_e32 v85, 0x3fb8aa3b, v85
	v_exp_f32_e32 v85, v85
	v_rcp_f32_e32 v79, v84
	s_nop 0
	v_add_f32_e32 v79, v79, v79
	v_sub_f32_e32 v79, 1.0, v79
	v_add_f32_e32 v83, 1.0, v85
	v_mul_f32_e32 v80, 0.5, v80
	v_add_f32_e32 v79, 1.0, v79
	v_mul_f32_e32 v79, v80, v79
	v_mul_f32_e32 v84, 0x3d372713, v74
	v_mul_f32_e32 v84, v74, v84
	v_fma_f32 v84, v74, v84, v74
	v_mul_f32_e32 v84, 0x3f4c422a, v84
	v_add_f32_e32 v84, v84, v84
	v_mul_f32_e32 v84, 0x3fb8aa3b, v84
	v_exp_f32_e32 v84, v84
	v_rcp_f32_e32 v80, v83
	s_nop 0
	v_add_f32_e32 v80, v80, v80
	v_sub_f32_e32 v80, 1.0, v80
	v_add_f32_e32 v83, 1.0, v84
	v_mul_f32_e32 v81, 0.5, v81
	v_add_f32_e32 v80, 1.0, v80
	v_mul_f32_e32 v80, v81, v80
	v_cvt_pk_bf16_f32 v79, v79, v80
	v_mul_f32_e32 v84, 0x3d372713, v75
	v_mul_f32_e32 v84, v75, v84
	v_fma_f32 v84, v75, v84, v75
	v_mul_f32_e32 v84, 0x3f4c422a, v84
	v_add_f32_e32 v84, v84, v84
	v_mul_f32_e32 v84, 0x3fb8aa3b, v84
	v_exp_f32_e32 v84, v84
	v_rcp_f32_e32 v80, v83
	s_nop 0
	v_add_f32_e32 v80, v80, v80
	v_sub_f32_e32 v80, 1.0, v80
	v_add_f32_e32 v81, 1.0, v84
	v_mul_f32_e32 v74, 0.5, v74
	v_add_f32_e32 v80, 1.0, v80
	v_mul_f32_e32 v74, v74, v80
	v_mul_f32_e32 v83, 0x3d372713, v76
	v_mul_f32_e32 v83, v76, v83
	v_fma_f32 v83, v76, v83, v76
	v_mul_f32_e32 v83, 0x3f4c422a, v83
	v_add_f32_e32 v83, v83, v83
	v_mul_f32_e32 v83, 0x3fb8aa3b, v83
	v_exp_f32_e32 v83, v83
	v_rcp_f32_e32 v80, v81
	s_nop 0
	v_add_f32_e32 v80, v80, v80
	v_sub_f32_e32 v80, 1.0, v80
	v_add_f32_e32 v81, 1.0, v83
	v_mul_f32_e32 v75, 0.5, v75
	v_add_f32_e32 v80, 1.0, v80
	v_mul_f32_e32 v75, v75, v80
	v_cvt_pk_bf16_f32 v80, v74, v75
	v_mul_f32_e32 v83, 0x3d372713, v77
	v_mul_f32_e32 v83, v77, v83
	v_fma_f32 v83, v77, v83, v77
	v_mul_f32_e32 v83, 0x3f4c422a, v83
	v_add_f32_e32 v83, v83, v83
	v_mul_f32_e32 v83, 0x3fb8aa3b, v83
	v_exp_f32_e32 v83, v83
	v_rcp_f32_e32 v74, v81
	s_nop 0
	v_add_f32_e32 v74, v74, v74
	v_sub_f32_e32 v74, 1.0, v74
	v_add_f32_e32 v75, 1.0, v83
	v_mul_f32_e32 v76, 0.5, v76
	v_add_f32_e32 v74, 1.0, v74
	v_mul_f32_e32 v74, v76, v74
	v_rcp_f32_e32 v75, v75
	s_nop 0
	v_add_f32_e32 v75, v75, v75
	v_sub_f32_e32 v75, 1.0, v75
	v_mul_f32_e32 v76, 0.5, v77
	v_add_f32_e32 v75, 1.0, v75
	v_mul_f32_e32 v75, v76, v75
	v_mul_f32_e32 v76, 0x3d372713, v70
	v_mul_f32_e32 v76, v70, v76
	v_fma_f32 v76, v70, v76, v70
	v_mul_f32_e32 v76, 0x3f4c422a, v76
	v_add_f32_e32 v76, v76, v76
	v_mul_f32_e32 v76, 0x3fb8aa3b, v76
	v_exp_f32_e32 v76, v76
	v_or_b32_e32 v82, v171, v149
	v_ashrrev_i32_e32 v83, 31, v82
	v_cvt_pk_bf16_f32 v81, v74, v75
	v_add_f32_e32 v76, 1.0, v76
	v_lshlrev_b64 v[74:75], 11, v[82:83]
	v_lshl_add_u64 v[74:75], v[138:139], 0, v[74:75]
	global_store_dwordx4 v[74:75], v[78:81], off
	v_mul_f32_e32 v70, 0.5, v70
	v_mul_f32_e32 v77, 0x3d372713, v71
	v_mul_f32_e32 v77, v71, v77
	v_fma_f32 v77, v71, v77, v71
	v_mul_f32_e32 v77, 0x3f4c422a, v77
	v_add_f32_e32 v77, v77, v77
	v_mul_f32_e32 v77, 0x3fb8aa3b, v77
	v_exp_f32_e32 v77, v77
	v_rcp_f32_e32 v75, v76
	s_nop 0
	v_add_f32_e32 v75, v75, v75
	v_sub_f32_e32 v75, 1.0, v75
	v_add_f32_e32 v76, 1.0, v77
	v_add_f32_e32 v75, 1.0, v75
	v_mul_f32_e32 v70, v70, v75
	v_mul_f32_e32 v71, 0.5, v71
	v_mul_f32_e32 v77, 0x3d372713, v72
	v_mul_f32_e32 v77, v72, v77
	v_fma_f32 v77, v72, v77, v72
	v_mul_f32_e32 v77, 0x3f4c422a, v77
	v_add_f32_e32 v77, v77, v77
	v_mul_f32_e32 v77, 0x3fb8aa3b, v77
	v_exp_f32_e32 v77, v77
	v_rcp_f32_e32 v75, v76
	s_nop 0
	v_add_f32_e32 v75, v75, v75
	v_sub_f32_e32 v75, 1.0, v75
	v_add_f32_e32 v76, 1.0, v77
	v_add_f32_e32 v75, 1.0, v75
	v_mul_f32_e32 v71, v71, v75
	v_cvt_pk_bf16_f32 v70, v70, v71
	v_mul_f32_e32 v77, 0x3d372713, v73
	v_mul_f32_e32 v77, v73, v77
	v_fma_f32 v77, v73, v77, v73
	v_mul_f32_e32 v77, 0x3f4c422a, v77
	v_add_f32_e32 v77, v77, v77
	v_mul_f32_e32 v77, 0x3fb8aa3b, v77
	v_exp_f32_e32 v77, v77
	v_rcp_f32_e32 v71, v76
	s_nop 0
	v_add_f32_e32 v71, v71, v71
	v_sub_f32_e32 v71, 1.0, v71
	v_add_f32_e32 v75, 1.0, v77
	v_mul_f32_e32 v72, 0.5, v72
	v_add_f32_e32 v71, 1.0, v71
	v_mul_f32_e32 v71, v72, v71
	v_mul_f32_e32 v76, 0x3d372713, v66
	v_mul_f32_e32 v76, v66, v76
	v_fma_f32 v76, v66, v76, v66
	v_mul_f32_e32 v76, 0x3f4c422a, v76
	v_add_f32_e32 v76, v76, v76
	v_mul_f32_e32 v76, 0x3fb8aa3b, v76
	v_exp_f32_e32 v76, v76
	v_rcp_f32_e32 v72, v75
	s_nop 0
	v_add_f32_e32 v72, v72, v72
	v_sub_f32_e32 v72, 1.0, v72
	v_add_f32_e32 v75, 1.0, v76
	v_mul_f32_e32 v73, 0.5, v73
	v_add_f32_e32 v72, 1.0, v72
	v_mul_f32_e32 v72, v73, v72
	v_cvt_pk_bf16_f32 v71, v71, v72
	v_mul_f32_e32 v76, 0x3d372713, v67
	v_mul_f32_e32 v76, v67, v76
	v_fma_f32 v76, v67, v76, v67
	v_mul_f32_e32 v76, 0x3f4c422a, v76
	v_add_f32_e32 v76, v76, v76
	v_mul_f32_e32 v76, 0x3fb8aa3b, v76
	v_exp_f32_e32 v76, v76
	v_rcp_f32_e32 v72, v75
	s_nop 0
	v_add_f32_e32 v72, v72, v72
	v_sub_f32_e32 v72, 1.0, v72
	v_add_f32_e32 v73, 1.0, v76
	v_mul_f32_e32 v66, 0.5, v66
	v_add_f32_e32 v72, 1.0, v72
	v_mul_f32_e32 v66, v66, v72
	v_mul_f32_e32 v75, 0x3d372713, v68
	v_mul_f32_e32 v75, v68, v75
	v_fma_f32 v75, v68, v75, v68
	v_mul_f32_e32 v75, 0x3f4c422a, v75
	v_add_f32_e32 v75, v75, v75
	v_mul_f32_e32 v75, 0x3fb8aa3b, v75
	v_exp_f32_e32 v75, v75
	v_rcp_f32_e32 v72, v73
; #define LAS __attribute__((address_space(3)))
; __device__ __forceinline__ unsigned cvt_pk_bf16(float lo, float hi) { unsigned r; asm volatile("v_cvt_pk_bf16_f32 %0, %1, %2" : "=v"(r) : "v"(lo), "v"(hi)); return r; }
; __device__ __forceinline__ float gelu_tanh(float x) { const float z = 0.7978845608f * (x + 0.044715f * x * x * x); const float th = 1.0f - 2.0f / (__expf(2.0f * z) + 1.0f); return 0.5f * x * (1.0f + th); }
;     __device__ __forceinline__ void operator()(const f32x4 (&acc)[2][2][4][2], const Unit& u, int ui, const LAS float* rtab, int wr, int wc, int fr, int fq) const {
;         const int g = u.pm; const int n0 = wr * 64 + fr; const int lc0 = (u.pn & 1) * 256 + wc * 32 + 8 * fq;
; #pragma unroll
;         for (int ai = 0; ai < 2; ++ai)
; #pragma unroll
;             for (int m = 0; m < 4; ++m) {
;                 const int n = n0 + ai * HALF + m * 16;
; #pragma unroll
;                 for (int bj = 0; bj < 2; ++bj) {
;                     const int lc = lc0 + bj * HALF, t = lc >> 4, co = lc & 15; const int token = n * 32 + t;
;                     const f32x4 a0 = acc[ai][bj][m][0], a1 = acc[ai][bj][m][1];
;                     u32x4 w; w.x = cvt_pk_bf16(gelu_tanh(a0[0]), gelu_tanh(a0[1])); w.y = cvt_pk_bf16(gelu_tanh(a0[2]), gelu_tanh(a0[3]));
;                     w.z = cvt_pk_bf16(gelu_tanh(a1[0]), gelu_tanh(a1[1])); w.w = cvt_pk_bf16(gelu_tanh(a1[2]), gelu_tanh(a1[3]));
;                     *(u32x4*)(Y + (size_t)token * 1024 + 16 * g + co) = w;
	s_nop 0
	v_add_f32_e32 v72, v72, v72
	v_sub_f32_e32 v72, 1.0, v72
	v_add_f32_e32 v73, 1.0, v75
	v_mul_f32_e32 v67, 0.5, v67
	v_add_f32_e32 v72, 1.0, v72
	v_mul_f32_e32 v67, v67, v72
	v_cvt_pk_bf16_f32 v72, v66, v67
	v_mul_f32_e32 v75, 0x3d372713, v69
	v_mul_f32_e32 v75, v69, v75
	v_fma_f32 v75, v69, v75, v69
	v_mul_f32_e32 v75, 0x3f4c422a, v75
	v_add_f32_e32 v75, v75, v75
	v_mul_f32_e32 v75, 0x3fb8aa3b, v75
	v_exp_f32_e32 v75, v75
	v_rcp_f32_e32 v66, v73
	s_nop 0
	v_add_f32_e32 v66, v66, v66
	v_sub_f32_e32 v66, 1.0, v66
	v_add_f32_e32 v67, 1.0, v75
	v_mul_f32_e32 v68, 0.5, v68
	v_add_f32_e32 v66, 1.0, v66
	v_mul_f32_e32 v66, v68, v66
	v_rcp_f32_e32 v67, v67
	s_nop 0
	v_add_f32_e32 v67, v67, v67
	v_sub_f32_e32 v67, 1.0, v67
	v_mul_f32_e32 v68, 0.5, v69
	v_add_f32_e32 v67, 1.0, v67
	v_mul_f32_e32 v67, v68, v67
	v_mul_f32_e32 v68, 0x3d372713, v62
	v_mul_f32_e32 v68, v62, v68
	v_fma_f32 v68, v62, v68, v62
	v_mul_f32_e32 v68, 0x3f4c422a, v68
	v_add_f32_e32 v68, v68, v68
	v_mul_f32_e32 v68, 0x3fb8aa3b, v68
	v_exp_f32_e32 v68, v68
	v_or_b32_e32 v74, v124, v149
	v_ashrrev_i32_e32 v75, 31, v74
	v_cvt_pk_bf16_f32 v73, v66, v67
	v_add_f32_e32 v68, 1.0, v68
	v_lshlrev_b64 v[66:67], 11, v[74:75]
	v_lshl_add_u64 v[66:67], v[138:139], 0, v[66:67]
	global_store_dwordx4 v[66:67], v[70:73], off
	v_mul_f32_e32 v62, 0.5, v62
	v_mul_f32_e32 v69, 0x3d372713, v63
	v_mul_f32_e32 v69, v63, v69
	v_fma_f32 v69, v63, v69, v63
	v_mul_f32_e32 v69, 0x3f4c422a, v69
	v_add_f32_e32 v69, v69, v69
	v_mul_f32_e32 v69, 0x3fb8aa3b, v69
	v_exp_f32_e32 v69, v69
	v_rcp_f32_e32 v67, v68
	s_nop 0
	v_add_f32_e32 v67, v67, v67
	v_sub_f32_e32 v67, 1.0, v67
	v_add_f32_e32 v68, 1.0, v69
	v_add_f32_e32 v67, 1.0, v67
	v_mul_f32_e32 v62, v62, v67
	v_mul_f32_e32 v63, 0.5, v63
	v_mul_f32_e32 v69, 0x3d372713, v64
	v_mul_f32_e32 v69, v64, v69
	v_fma_f32 v69, v64, v69, v64
	v_mul_f32_e32 v69, 0x3f4c422a, v69
	v_add_f32_e32 v69, v69, v69
	v_mul_f32_e32 v69, 0x3fb8aa3b, v69
	v_exp_f32_e32 v69, v69
	v_rcp_f32_e32 v67, v68
	s_nop 0
	v_add_f32_e32 v67, v67, v67
	v_sub_f32_e32 v67, 1.0, v67
	v_add_f32_e32 v68, 1.0, v69
	v_add_f32_e32 v67, 1.0, v67
	v_mul_f32_e32 v63, v63, v67
	v_cvt_pk_bf16_f32 v62, v62, v63
	v_mul_f32_e32 v69, 0x3d372713, v65
	v_mul_f32_e32 v69, v65, v69
	v_fma_f32 v69, v65, v69, v65
	v_mul_f32_e32 v69, 0x3f4c422a, v69
	v_add_f32_e32 v69, v69, v69
	v_mul_f32_e32 v69, 0x3fb8aa3b, v69
	v_exp_f32_e32 v69, v69
	v_rcp_f32_e32 v63, v68
	s_nop 0
	v_add_f32_e32 v63, v63, v63
	v_sub_f32_e32 v63, 1.0, v63
	v_add_f32_e32 v67, 1.0, v69
	v_mul_f32_e32 v64, 0.5, v64
	v_add_f32_e32 v63, 1.0, v63
	v_mul_f32_e32 v63, v64, v63
	v_mul_f32_e32 v68, 0x3d372713, v58
	v_mul_f32_e32 v68, v58, v68
	v_fma_f32 v68, v58, v68, v58
	v_mul_f32_e32 v68, 0x3f4c422a, v68
	v_add_f32_e32 v68, v68, v68
	v_mul_f32_e32 v68, 0x3fb8aa3b, v68
	v_exp_f32_e32 v68, v68
	v_rcp_f32_e32 v64, v67
	s_nop 0
	v_add_f32_e32 v64, v64, v64
	v_sub_f32_e32 v64, 1.0, v64
	v_add_f32_e32 v67, 1.0, v68
	v_mul_f32_e32 v65, 0.5, v65
	v_add_f32_e32 v64, 1.0, v64
	v_mul_f32_e32 v64, v65, v64
	v_cvt_pk_bf16_f32 v63, v63, v64
	v_mul_f32_e32 v68, 0x3d372713, v59
	v_mul_f32_e32 v68, v59, v68
	v_fma_f32 v68, v59, v68, v59
	v_mul_f32_e32 v68, 0x3f4c422a, v68
	v_add_f32_e32 v68, v68, v68
	v_mul_f32_e32 v68, 0x3fb8aa3b, v68
	v_exp_f32_e32 v68, v68
	v_rcp_f32_e32 v64, v67
	s_nop 0
	v_add_f32_e32 v64, v64, v64
	v_sub_f32_e32 v64, 1.0, v64
	v_add_f32_e32 v65, 1.0, v68
	v_mul_f32_e32 v58, 0.5, v58
	v_add_f32_e32 v64, 1.0, v64
	v_mul_f32_e32 v58, v58, v64
	v_mul_f32_e32 v67, 0x3d372713, v60
	v_mul_f32_e32 v67, v60, v67
	v_fma_f32 v67, v60, v67, v60
	v_mul_f32_e32 v67, 0x3f4c422a, v67
	v_add_f32_e32 v67, v67, v67
	v_mul_f32_e32 v67, 0x3fb8aa3b, v67
	v_exp_f32_e32 v67, v67
	v_rcp_f32_e32 v64, v65
	s_nop 0
	v_add_f32_e32 v64, v64, v64
	v_sub_f32_e32 v64, 1.0, v64
	v_add_f32_e32 v65, 1.0, v67
	v_mul_f32_e32 v59, 0.5, v59
	v_add_f32_e32 v64, 1.0, v64
	v_mul_f32_e32 v59, v59, v64
	v_cvt_pk_bf16_f32 v64, v58, v59
	v_mul_f32_e32 v67, 0x3d372713, v61
	v_mul_f32_e32 v67, v61, v67
	v_fma_f32 v67, v61, v67, v61
	v_mul_f32_e32 v67, 0x3f4c422a, v67
	v_add_f32_e32 v67, v67, v67
	v_mul_f32_e32 v67, 0x3fb8aa3b, v67
	v_exp_f32_e32 v67, v67
	v_rcp_f32_e32 v58, v65
	s_nop 0
	v_add_f32_e32 v58, v58, v58
	v_sub_f32_e32 v58, 1.0, v58
	v_add_f32_e32 v59, 1.0, v67
	v_mul_f32_e32 v60, 0.5, v60
	v_add_f32_e32 v58, 1.0, v58
	v_mul_f32_e32 v58, v60, v58
	v_rcp_f32_e32 v59, v59
	s_nop 0
	v_add_f32_e32 v59, v59, v59
	v_sub_f32_e32 v59, 1.0, v59
	v_mul_f32_e32 v60, 0.5, v61
	v_add_f32_e32 v59, 1.0, v59
	v_mul_f32_e32 v59, v60, v59
	v_mul_f32_e32 v60, 0x3d372713, v54
	v_mul_f32_e32 v60, v54, v60
	v_fma_f32 v60, v54, v60, v54
	v_mul_f32_e32 v60, 0x3f4c422a, v60
	v_add_f32_e32 v60, v60, v60
	v_mul_f32_e32 v60, 0x3fb8aa3b, v60
	v_exp_f32_e32 v60, v60
	v_or_b32_e32 v66, v171, v150
	v_ashrrev_i32_e32 v67, 31, v66
	v_cvt_pk_bf16_f32 v65, v58, v59
	v_add_f32_e32 v60, 1.0, v60
	v_lshlrev_b64 v[58:59], 11, v[66:67]
	v_lshl_add_u64 v[58:59], v[138:139], 0, v[58:59]
	global_store_dwordx4 v[58:59], v[62:65], off
	v_mul_f32_e32 v54, 0.5, v54
	v_mul_f32_e32 v61, 0x3d372713, v55
	v_mul_f32_e32 v61, v55, v61
	v_fma_f32 v61, v55, v61, v55
	v_mul_f32_e32 v61, 0x3f4c422a, v61
	v_add_f32_e32 v61, v61, v61
	v_mul_f32_e32 v61, 0x3fb8aa3b, v61
	v_exp_f32_e32 v61, v61
	v_rcp_f32_e32 v59, v60
	s_nop 0
	v_add_f32_e32 v59, v59, v59
	v_sub_f32_e32 v59, 1.0, v59
	v_add_f32_e32 v60, 1.0, v61
	v_add_f32_e32 v59, 1.0, v59
	v_mul_f32_e32 v54, v54, v59
	v_mul_f32_e32 v55, 0.5, v55
	v_mul_f32_e32 v61, 0x3d372713, v56
	v_mul_f32_e32 v61, v56, v61
	v_fma_f32 v61, v56, v61, v56
	v_mul_f32_e32 v61, 0x3f4c422a, v61
; #define LAS __attribute__((address_space(3)))
; __device__ __forceinline__ unsigned cvt_pk_bf16(float lo, float hi) { unsigned r; asm volatile("v_cvt_pk_bf16_f32 %0, %1, %2" : "=v"(r) : "v"(lo), "v"(hi)); return r; }
; __device__ __forceinline__ float gelu_tanh(float x) { const float z = 0.7978845608f * (x + 0.044715f * x * x * x); const float th = 1.0f - 2.0f / (__expf(2.0f * z) + 1.0f); return 0.5f * x * (1.0f + th); }
;     __device__ __forceinline__ void operator()(const f32x4 (&acc)[2][2][4][2], const Unit& u, int ui, const LAS float* rtab, int wr, int wc, int fr, int fq) const {
;         const int g = u.pm; const int n0 = wr * 64 + fr; const int lc0 = (u.pn & 1) * 256 + wc * 32 + 8 * fq;
; #pragma unroll
;         for (int ai = 0; ai < 2; ++ai)
; #pragma unroll
;             for (int m = 0; m < 4; ++m) {
;                 const int n = n0 + ai * HALF + m * 16;
; #pragma unroll
;                 for (int bj = 0; bj < 2; ++bj) {
;                     const int lc = lc0 + bj * HALF, t = lc >> 4, co = lc & 15; const int token = n * 32 + t;
;                     const f32x4 a0 = acc[ai][bj][m][0], a1 = acc[ai][bj][m][1];
;                     u32x4 w; w.x = cvt_pk_bf16(gelu_tanh(a0[0]), gelu_tanh(a0[1])); w.y = cvt_pk_bf16(gelu_tanh(a0[2]), gelu_tanh(a0[3]));
;                     w.z = cvt_pk_bf16(gelu_tanh(a1[0]), gelu_tanh(a1[1])); w.w = cvt_pk_bf16(gelu_tanh(a1[2]), gelu_tanh(a1[3]));
;                     *(u32x4*)(Y + (size_t)token * 1024 + 16 * g + co) = w;
	v_add_f32_e32 v61, v61, v61
	v_mul_f32_e32 v61, 0x3fb8aa3b, v61
	v_exp_f32_e32 v61, v61
	v_rcp_f32_e32 v59, v60
	s_nop 0
	v_add_f32_e32 v59, v59, v59
	v_sub_f32_e32 v59, 1.0, v59
	v_add_f32_e32 v60, 1.0, v61
	v_add_f32_e32 v59, 1.0, v59
	v_mul_f32_e32 v55, v55, v59
	v_cvt_pk_bf16_f32 v54, v54, v55
	v_mul_f32_e32 v61, 0x3d372713, v57
	v_mul_f32_e32 v61, v57, v61
	v_fma_f32 v61, v57, v61, v57
	v_mul_f32_e32 v61, 0x3f4c422a, v61
	v_add_f32_e32 v61, v61, v61
	v_mul_f32_e32 v61, 0x3fb8aa3b, v61
	v_exp_f32_e32 v61, v61
	v_rcp_f32_e32 v55, v60
	s_nop 0
	v_add_f32_e32 v55, v55, v55
	v_sub_f32_e32 v55, 1.0, v55
	v_add_f32_e32 v59, 1.0, v61
	v_mul_f32_e32 v56, 0.5, v56
	v_add_f32_e32 v55, 1.0, v55
	v_mul_f32_e32 v55, v56, v55
	v_mul_f32_e32 v60, 0x3d372713, v50
	v_mul_f32_e32 v60, v50, v60
	v_fma_f32 v60, v50, v60, v50
	v_mul_f32_e32 v60, 0x3f4c422a, v60
	v_add_f32_e32 v60, v60, v60
	v_mul_f32_e32 v60, 0x3fb8aa3b, v60
	v_exp_f32_e32 v60, v60
	v_rcp_f32_e32 v56, v59
	s_nop 0
	v_add_f32_e32 v56, v56, v56
	v_sub_f32_e32 v56, 1.0, v56
	v_add_f32_e32 v59, 1.0, v60
	v_mul_f32_e32 v57, 0.5, v57
	v_add_f32_e32 v56, 1.0, v56
	v_mul_f32_e32 v56, v57, v56
	v_cvt_pk_bf16_f32 v55, v55, v56
	v_mul_f32_e32 v60, 0x3d372713, v51
	v_mul_f32_e32 v60, v51, v60
	v_fma_f32 v60, v51, v60, v51
	v_mul_f32_e32 v60, 0x3f4c422a, v60
	v_add_f32_e32 v60, v60, v60
	v_mul_f32_e32 v60, 0x3fb8aa3b, v60
	v_exp_f32_e32 v60, v60
	v_rcp_f32_e32 v56, v59
	s_nop 0
	v_add_f32_e32 v56, v56, v56
	v_sub_f32_e32 v56, 1.0, v56
	v_add_f32_e32 v57, 1.0, v60
	v_mul_f32_e32 v50, 0.5, v50
	v_add_f32_e32 v56, 1.0, v56
	v_mul_f32_e32 v50, v50, v56
	v_mul_f32_e32 v59, 0x3d372713, v52
	v_mul_f32_e32 v59, v52, v59
	v_fma_f32 v59, v52, v59, v52
	v_mul_f32_e32 v59, 0x3f4c422a, v59
	v_add_f32_e32 v59, v59, v59
	v_mul_f32_e32 v59, 0x3fb8aa3b, v59
	v_exp_f32_e32 v59, v59
	v_rcp_f32_e32 v56, v57
	s_nop 0
	v_add_f32_e32 v56, v56, v56
	v_sub_f32_e32 v56, 1.0, v56
	v_add_f32_e32 v57, 1.0, v59
	v_mul_f32_e32 v51, 0.5, v51
	v_add_f32_e32 v56, 1.0, v56
	v_mul_f32_e32 v51, v51, v56
	v_cvt_pk_bf16_f32 v56, v50, v51
	v_mul_f32_e32 v59, 0x3d372713, v53
	v_mul_f32_e32 v59, v53, v59
	v_fma_f32 v59, v53, v59, v53
	v_mul_f32_e32 v59, 0x3f4c422a, v59
	v_add_f32_e32 v59, v59, v59
	v_mul_f32_e32 v59, 0x3fb8aa3b, v59
	v_exp_f32_e32 v59, v59
	v_rcp_f32_e32 v50, v57
	s_nop 0
	v_add_f32_e32 v50, v50, v50
	v_sub_f32_e32 v50, 1.0, v50
	v_add_f32_e32 v51, 1.0, v59
	v_mul_f32_e32 v52, 0.5, v52
	v_add_f32_e32 v50, 1.0, v50
	v_mul_f32_e32 v50, v52, v50
	v_rcp_f32_e32 v51, v51
	s_nop 0
	v_add_f32_e32 v51, v51, v51
	v_sub_f32_e32 v51, 1.0, v51
	v_mul_f32_e32 v52, 0.5, v53
	v_add_f32_e32 v51, 1.0, v51
	v_mul_f32_e32 v51, v52, v51
	v_mul_f32_e32 v52, 0x3d372713, v46
	v_mul_f32_e32 v52, v46, v52
	v_fma_f32 v52, v46, v52, v46
	v_mul_f32_e32 v52, 0x3f4c422a, v52
	v_add_f32_e32 v52, v52, v52
	v_mul_f32_e32 v52, 0x3fb8aa3b, v52
	v_exp_f32_e32 v52, v52
	v_or_b32_e32 v58, v124, v150
	v_ashrrev_i32_e32 v59, 31, v58
	v_cvt_pk_bf16_f32 v57, v50, v51
	v_add_f32_e32 v52, 1.0, v52
	v_lshlrev_b64 v[50:51], 11, v[58:59]
	v_lshl_add_u64 v[50:51], v[138:139], 0, v[50:51]
	global_store_dwordx4 v[50:51], v[54:57], off
	v_mul_f32_e32 v46, 0.5, v46
	v_mul_f32_e32 v53, 0x3d372713, v47
	v_mul_f32_e32 v53, v47, v53
	v_fma_f32 v53, v47, v53, v47
	v_mul_f32_e32 v53, 0x3f4c422a, v53
	v_add_f32_e32 v53, v53, v53
	v_mul_f32_e32 v53, 0x3fb8aa3b, v53
	v_exp_f32_e32 v53, v53
	v_rcp_f32_e32 v51, v52
	s_nop 0
	v_add_f32_e32 v51, v51, v51
	v_sub_f32_e32 v51, 1.0, v51
	v_add_f32_e32 v52, 1.0, v53
	v_add_f32_e32 v51, 1.0, v51
	v_mul_f32_e32 v46, v46, v51
	v_mul_f32_e32 v47, 0.5, v47
	v_mul_f32_e32 v53, 0x3d372713, v48
	v_mul_f32_e32 v53, v48, v53
	v_fma_f32 v53, v48, v53, v48
	v_mul_f32_e32 v53, 0x3f4c422a, v53
	v_add_f32_e32 v53, v53, v53
	v_mul_f32_e32 v53, 0x3fb8aa3b, v53
	v_exp_f32_e32 v53, v53
	v_rcp_f32_e32 v51, v52
	s_nop 0
	v_add_f32_e32 v51, v51, v51
	v_sub_f32_e32 v51, 1.0, v51
	v_add_f32_e32 v52, 1.0, v53
	v_add_f32_e32 v51, 1.0, v51
	v_mul_f32_e32 v47, v47, v51
	v_cvt_pk_bf16_f32 v46, v46, v47
	v_mul_f32_e32 v53, 0x3d372713, v49
	v_mul_f32_e32 v53, v49, v53
	v_fma_f32 v53, v49, v53, v49
	v_mul_f32_e32 v53, 0x3f4c422a, v53
	v_add_f32_e32 v53, v53, v53
	v_mul_f32_e32 v53, 0x3fb8aa3b, v53
	v_exp_f32_e32 v53, v53
	v_rcp_f32_e32 v47, v52
	s_nop 0
	v_add_f32_e32 v47, v47, v47
	v_sub_f32_e32 v47, 1.0, v47
	v_add_f32_e32 v51, 1.0, v53
	v_mul_f32_e32 v48, 0.5, v48
	v_add_f32_e32 v47, 1.0, v47
	v_mul_f32_e32 v47, v48, v47
	v_mul_f32_e32 v52, 0x3d372713, v42
	v_mul_f32_e32 v52, v42, v52
	v_fma_f32 v52, v42, v52, v42
	v_mul_f32_e32 v52, 0x3f4c422a, v52
	v_add_f32_e32 v52, v52, v52
	v_mul_f32_e32 v52, 0x3fb8aa3b, v52
	v_exp_f32_e32 v52, v52
	v_rcp_f32_e32 v48, v51
	s_nop 0
	v_add_f32_e32 v48, v48, v48
	v_sub_f32_e32 v48, 1.0, v48
	v_add_f32_e32 v51, 1.0, v52
	v_mul_f32_e32 v49, 0.5, v49
	v_add_f32_e32 v48, 1.0, v48
	v_mul_f32_e32 v48, v49, v48
	v_cvt_pk_bf16_f32 v47, v47, v48
	v_mul_f32_e32 v52, 0x3d372713, v43
	v_mul_f32_e32 v52, v43, v52
	v_fma_f32 v52, v43, v52, v43
	v_mul_f32_e32 v52, 0x3f4c422a, v52
	v_add_f32_e32 v52, v52, v52
	v_mul_f32_e32 v52, 0x3fb8aa3b, v52
	v_exp_f32_e32 v52, v52
	v_rcp_f32_e32 v48, v51
	s_nop 0
	v_add_f32_e32 v48, v48, v48
	v_sub_f32_e32 v48, 1.0, v48
	v_add_f32_e32 v49, 1.0, v52
	v_mul_f32_e32 v42, 0.5, v42
	v_add_f32_e32 v48, 1.0, v48
	v_mul_f32_e32 v42, v42, v48
	v_mul_f32_e32 v51, 0x3d372713, v44
	v_mul_f32_e32 v51, v44, v51
	v_fma_f32 v51, v44, v51, v44
	v_mul_f32_e32 v51, 0x3f4c422a, v51
	v_add_f32_e32 v51, v51, v51
	v_mul_f32_e32 v51, 0x3fb8aa3b, v51
	v_exp_f32_e32 v51, v51
	v_rcp_f32_e32 v48, v49
	s_nop 0
	v_add_f32_e32 v48, v48, v48
; #define LAS __attribute__((address_space(3)))
; __device__ __forceinline__ unsigned cvt_pk_bf16(float lo, float hi) { unsigned r; asm volatile("v_cvt_pk_bf16_f32 %0, %1, %2" : "=v"(r) : "v"(lo), "v"(hi)); return r; }
; __device__ __forceinline__ float gelu_tanh(float x) { const float z = 0.7978845608f * (x + 0.044715f * x * x * x); const float th = 1.0f - 2.0f / (__expf(2.0f * z) + 1.0f); return 0.5f * x * (1.0f + th); }
;     __device__ __forceinline__ void operator()(const f32x4 (&acc)[2][2][4][2], const Unit& u, int ui, const LAS float* rtab, int wr, int wc, int fr, int fq) const {
;         const int g = u.pm; const int n0 = wr * 64 + fr; const int lc0 = (u.pn & 1) * 256 + wc * 32 + 8 * fq;
; #pragma unroll
;         for (int ai = 0; ai < 2; ++ai)
; #pragma unroll
;             for (int m = 0; m < 4; ++m) {
;                 const int n = n0 + ai * HALF + m * 16;
; #pragma unroll
;                 for (int bj = 0; bj < 2; ++bj) {
;                     const int lc = lc0 + bj * HALF, t = lc >> 4, co = lc & 15; const int token = n * 32 + t;
;                     const f32x4 a0 = acc[ai][bj][m][0], a1 = acc[ai][bj][m][1];
;                     u32x4 w; w.x = cvt_pk_bf16(gelu_tanh(a0[0]), gelu_tanh(a0[1])); w.y = cvt_pk_bf16(gelu_tanh(a0[2]), gelu_tanh(a0[3]));
;                     w.z = cvt_pk_bf16(gelu_tanh(a1[0]), gelu_tanh(a1[1])); w.w = cvt_pk_bf16(gelu_tanh(a1[2]), gelu_tanh(a1[3]));
;                     *(u32x4*)(Y + (size_t)token * 1024 + 16 * g + co) = w;
	v_sub_f32_e32 v48, 1.0, v48
	v_add_f32_e32 v49, 1.0, v51
	v_mul_f32_e32 v43, 0.5, v43
	v_add_f32_e32 v48, 1.0, v48
	v_mul_f32_e32 v43, v43, v48
	v_cvt_pk_bf16_f32 v48, v42, v43
	v_mul_f32_e32 v51, 0x3d372713, v45
	v_mul_f32_e32 v51, v45, v51
	v_fma_f32 v51, v45, v51, v45
	v_mul_f32_e32 v51, 0x3f4c422a, v51
	v_add_f32_e32 v51, v51, v51
	v_mul_f32_e32 v51, 0x3fb8aa3b, v51
	v_exp_f32_e32 v51, v51
	v_rcp_f32_e32 v42, v49
	s_nop 0
	v_add_f32_e32 v42, v42, v42
	v_sub_f32_e32 v42, 1.0, v42
	v_add_f32_e32 v43, 1.0, v51
	v_mul_f32_e32 v44, 0.5, v44
	v_add_f32_e32 v42, 1.0, v42
	v_mul_f32_e32 v42, v44, v42
	v_rcp_f32_e32 v43, v43
	s_nop 0
	v_add_f32_e32 v43, v43, v43
	v_sub_f32_e32 v43, 1.0, v43
	v_mul_f32_e32 v44, 0.5, v45
	v_add_f32_e32 v43, 1.0, v43
	v_mul_f32_e32 v43, v44, v43
	v_mul_f32_e32 v44, 0x3d372713, v38
	v_mul_f32_e32 v44, v38, v44
	v_fma_f32 v44, v38, v44, v38
	v_mul_f32_e32 v44, 0x3f4c422a, v44
	v_add_f32_e32 v44, v44, v44
	v_mul_f32_e32 v44, 0x3fb8aa3b, v44
	v_exp_f32_e32 v44, v44
	v_or_b32_e32 v50, v171, v151
	v_ashrrev_i32_e32 v51, 31, v50
	v_cvt_pk_bf16_f32 v49, v42, v43
	v_add_f32_e32 v44, 1.0, v44
	v_lshlrev_b64 v[42:43], 11, v[50:51]
	v_lshl_add_u64 v[42:43], v[138:139], 0, v[42:43]
	global_store_dwordx4 v[42:43], v[46:49], off
	v_mul_f32_e32 v38, 0.5, v38
	v_mul_f32_e32 v45, 0x3d372713, v39
	v_mul_f32_e32 v45, v39, v45
	v_fma_f32 v45, v39, v45, v39
	v_mul_f32_e32 v45, 0x3f4c422a, v45
	v_add_f32_e32 v45, v45, v45
	v_mul_f32_e32 v45, 0x3fb8aa3b, v45
	v_exp_f32_e32 v45, v45
	v_rcp_f32_e32 v43, v44
	s_nop 0
	v_add_f32_e32 v43, v43, v43
	v_sub_f32_e32 v43, 1.0, v43
	v_add_f32_e32 v44, 1.0, v45
	v_add_f32_e32 v43, 1.0, v43
	v_mul_f32_e32 v38, v38, v43
	v_mul_f32_e32 v39, 0.5, v39
	v_mul_f32_e32 v45, 0x3d372713, v40
	v_mul_f32_e32 v45, v40, v45
	v_fma_f32 v45, v40, v45, v40
	v_mul_f32_e32 v45, 0x3f4c422a, v45
	v_add_f32_e32 v45, v45, v45
	v_mul_f32_e32 v45, 0x3fb8aa3b, v45
	v_exp_f32_e32 v45, v45
	v_rcp_f32_e32 v43, v44
	s_nop 0
	v_add_f32_e32 v43, v43, v43
	v_sub_f32_e32 v43, 1.0, v43
	v_add_f32_e32 v44, 1.0, v45
	v_add_f32_e32 v43, 1.0, v43
	v_mul_f32_e32 v39, v39, v43
	v_cvt_pk_bf16_f32 v38, v38, v39
	v_mul_f32_e32 v45, 0x3d372713, v41
	v_mul_f32_e32 v45, v41, v45
	v_fma_f32 v45, v41, v45, v41
	v_mul_f32_e32 v45, 0x3f4c422a, v45
	v_add_f32_e32 v45, v45, v45
	v_mul_f32_e32 v45, 0x3fb8aa3b, v45
	v_exp_f32_e32 v45, v45
	v_rcp_f32_e32 v39, v44
	s_nop 0
	v_add_f32_e32 v39, v39, v39
	v_sub_f32_e32 v39, 1.0, v39
	v_add_f32_e32 v43, 1.0, v45
	v_mul_f32_e32 v40, 0.5, v40
	v_add_f32_e32 v39, 1.0, v39
	v_mul_f32_e32 v39, v40, v39
	v_mul_f32_e32 v44, 0x3d372713, v34
	v_mul_f32_e32 v44, v34, v44
	v_fma_f32 v44, v34, v44, v34
	v_mul_f32_e32 v44, 0x3f4c422a, v44
	v_add_f32_e32 v44, v44, v44
	v_mul_f32_e32 v44, 0x3fb8aa3b, v44
	v_exp_f32_e32 v44, v44
	v_rcp_f32_e32 v40, v43
	s_nop 0
	v_add_f32_e32 v40, v40, v40
	v_sub_f32_e32 v40, 1.0, v40
	v_add_f32_e32 v43, 1.0, v44
	v_mul_f32_e32 v41, 0.5, v41
	v_add_f32_e32 v40, 1.0, v40
	v_mul_f32_e32 v40, v41, v40
	v_cvt_pk_bf16_f32 v39, v39, v40
	v_mul_f32_e32 v44, 0x3d372713, v35
	v_mul_f32_e32 v44, v35, v44
	v_fma_f32 v44, v35, v44, v35
	v_mul_f32_e32 v44, 0x3f4c422a, v44
	v_add_f32_e32 v44, v44, v44
	v_mul_f32_e32 v44, 0x3fb8aa3b, v44
	v_exp_f32_e32 v44, v44
	v_rcp_f32_e32 v40, v43
	s_nop 0
	v_add_f32_e32 v40, v40, v40
	v_sub_f32_e32 v40, 1.0, v40
	v_add_f32_e32 v41, 1.0, v44
	v_mul_f32_e32 v34, 0.5, v34
	v_add_f32_e32 v40, 1.0, v40
	v_mul_f32_e32 v34, v34, v40
	v_mul_f32_e32 v43, 0x3d372713, v36
	v_mul_f32_e32 v43, v36, v43
	v_fma_f32 v43, v36, v43, v36
	v_mul_f32_e32 v43, 0x3f4c422a, v43
	v_add_f32_e32 v43, v43, v43
	v_mul_f32_e32 v43, 0x3fb8aa3b, v43
	v_exp_f32_e32 v43, v43
	v_rcp_f32_e32 v40, v41
	s_nop 0
	v_add_f32_e32 v40, v40, v40
	v_sub_f32_e32 v40, 1.0, v40
	v_add_f32_e32 v41, 1.0, v43
	v_mul_f32_e32 v35, 0.5, v35
	v_add_f32_e32 v40, 1.0, v40
	v_mul_f32_e32 v35, v35, v40
	v_cvt_pk_bf16_f32 v40, v34, v35
	v_mul_f32_e32 v43, 0x3d372713, v37
	v_mul_f32_e32 v43, v37, v43
	v_fma_f32 v43, v37, v43, v37
	v_mul_f32_e32 v43, 0x3f4c422a, v43
	v_add_f32_e32 v43, v43, v43
	v_mul_f32_e32 v43, 0x3fb8aa3b, v43
	v_exp_f32_e32 v43, v43
	v_rcp_f32_e32 v34, v41
	s_nop 0
	v_add_f32_e32 v34, v34, v34
	v_sub_f32_e32 v34, 1.0, v34
	v_add_f32_e32 v35, 1.0, v43
	v_mul_f32_e32 v36, 0.5, v36
	v_add_f32_e32 v34, 1.0, v34
	v_mul_f32_e32 v34, v36, v34
	v_rcp_f32_e32 v35, v35
	s_nop 0
	v_add_f32_e32 v35, v35, v35
	v_sub_f32_e32 v35, 1.0, v35
	v_mul_f32_e32 v36, 0.5, v37
	v_add_f32_e32 v35, 1.0, v35
	v_mul_f32_e32 v35, v36, v35
	v_mul_f32_e32 v36, 0x3d372713, v30
	v_mul_f32_e32 v36, v30, v36
	v_fma_f32 v36, v30, v36, v30
	v_mul_f32_e32 v36, 0x3f4c422a, v36
	v_add_f32_e32 v36, v36, v36
	v_mul_f32_e32 v36, 0x3fb8aa3b, v36
	v_exp_f32_e32 v36, v36
	v_or_b32_e32 v42, v124, v151
	v_ashrrev_i32_e32 v43, 31, v42
	v_cvt_pk_bf16_f32 v41, v34, v35
	v_add_f32_e32 v36, 1.0, v36
	v_lshlrev_b64 v[34:35], 11, v[42:43]
	v_lshl_add_u64 v[34:35], v[138:139], 0, v[34:35]
	global_store_dwordx4 v[34:35], v[38:41], off
	v_mul_f32_e32 v30, 0.5, v30
	v_mul_f32_e32 v37, 0x3d372713, v31
	v_mul_f32_e32 v37, v31, v37
	v_fma_f32 v37, v31, v37, v31
	v_mul_f32_e32 v37, 0x3f4c422a, v37
	v_add_f32_e32 v37, v37, v37
	v_mul_f32_e32 v37, 0x3fb8aa3b, v37
	v_exp_f32_e32 v37, v37
	v_rcp_f32_e32 v35, v36
	s_nop 0
	v_add_f32_e32 v35, v35, v35
	v_sub_f32_e32 v35, 1.0, v35
	v_add_f32_e32 v36, 1.0, v37
	v_add_f32_e32 v35, 1.0, v35
	v_mul_f32_e32 v30, v30, v35
	v_mul_f32_e32 v31, 0.5, v31
	v_mul_f32_e32 v37, 0x3d372713, v32
	v_mul_f32_e32 v37, v32, v37
	v_fma_f32 v37, v32, v37, v32
	v_mul_f32_e32 v37, 0x3f4c422a, v37
	v_add_f32_e32 v37, v37, v37
	v_mul_f32_e32 v37, 0x3fb8aa3b, v37
; #define LAS __attribute__((address_space(3)))
; __device__ __forceinline__ unsigned cvt_pk_bf16(float lo, float hi) { unsigned r; asm volatile("v_cvt_pk_bf16_f32 %0, %1, %2" : "=v"(r) : "v"(lo), "v"(hi)); return r; }
; __device__ __forceinline__ float gelu_tanh(float x) { const float z = 0.7978845608f * (x + 0.044715f * x * x * x); const float th = 1.0f - 2.0f / (__expf(2.0f * z) + 1.0f); return 0.5f * x * (1.0f + th); }
;     __device__ __forceinline__ void operator()(const f32x4 (&acc)[2][2][4][2], const Unit& u, int ui, const LAS float* rtab, int wr, int wc, int fr, int fq) const {
;         const int g = u.pm; const int n0 = wr * 64 + fr; const int lc0 = (u.pn & 1) * 256 + wc * 32 + 8 * fq;
; #pragma unroll
;         for (int ai = 0; ai < 2; ++ai)
; #pragma unroll
;             for (int m = 0; m < 4; ++m) {
;                 const int n = n0 + ai * HALF + m * 16;
; #pragma unroll
;                 for (int bj = 0; bj < 2; ++bj) {
;                     const int lc = lc0 + bj * HALF, t = lc >> 4, co = lc & 15; const int token = n * 32 + t;
;                     const f32x4 a0 = acc[ai][bj][m][0], a1 = acc[ai][bj][m][1];
;                     u32x4 w; w.x = cvt_pk_bf16(gelu_tanh(a0[0]), gelu_tanh(a0[1])); w.y = cvt_pk_bf16(gelu_tanh(a0[2]), gelu_tanh(a0[3]));
;                     w.z = cvt_pk_bf16(gelu_tanh(a1[0]), gelu_tanh(a1[1])); w.w = cvt_pk_bf16(gelu_tanh(a1[2]), gelu_tanh(a1[3]));
;                     *(u32x4*)(Y + (size_t)token * 1024 + 16 * g + co) = w;
	v_exp_f32_e32 v37, v37
	v_rcp_f32_e32 v35, v36
	s_nop 0
	v_add_f32_e32 v35, v35, v35
	v_sub_f32_e32 v35, 1.0, v35
	v_add_f32_e32 v36, 1.0, v37
	v_add_f32_e32 v35, 1.0, v35
	v_mul_f32_e32 v31, v31, v35
	v_cvt_pk_bf16_f32 v30, v30, v31
	v_mul_f32_e32 v37, 0x3d372713, v33
	v_mul_f32_e32 v37, v33, v37
	v_fma_f32 v37, v33, v37, v33
	v_mul_f32_e32 v37, 0x3f4c422a, v37
	v_add_f32_e32 v37, v37, v37
	v_mul_f32_e32 v37, 0x3fb8aa3b, v37
	v_exp_f32_e32 v37, v37
	v_rcp_f32_e32 v31, v36
	s_nop 0
	v_add_f32_e32 v31, v31, v31
	v_sub_f32_e32 v31, 1.0, v31
	v_add_f32_e32 v35, 1.0, v37
	v_mul_f32_e32 v32, 0.5, v32
	v_add_f32_e32 v31, 1.0, v31
	v_mul_f32_e32 v31, v32, v31
	v_mul_f32_e32 v36, 0x3d372713, v26
	v_mul_f32_e32 v36, v26, v36
	v_fma_f32 v36, v26, v36, v26
	v_mul_f32_e32 v36, 0x3f4c422a, v36
	v_add_f32_e32 v36, v36, v36
	v_mul_f32_e32 v36, 0x3fb8aa3b, v36
	v_exp_f32_e32 v36, v36
	v_rcp_f32_e32 v32, v35
	s_nop 0
	v_add_f32_e32 v32, v32, v32
	v_sub_f32_e32 v32, 1.0, v32
	v_add_f32_e32 v35, 1.0, v36
	v_mul_f32_e32 v33, 0.5, v33
	v_add_f32_e32 v32, 1.0, v32
	v_mul_f32_e32 v32, v33, v32
	v_cvt_pk_bf16_f32 v31, v31, v32
	v_mul_f32_e32 v36, 0x3d372713, v27
	v_mul_f32_e32 v36, v27, v36
	v_fma_f32 v36, v27, v36, v27
	v_mul_f32_e32 v36, 0x3f4c422a, v36
	v_add_f32_e32 v36, v36, v36
	v_mul_f32_e32 v36, 0x3fb8aa3b, v36
	v_exp_f32_e32 v36, v36
	v_rcp_f32_e32 v32, v35
	s_nop 0
	v_add_f32_e32 v32, v32, v32
	v_sub_f32_e32 v32, 1.0, v32
	v_add_f32_e32 v33, 1.0, v36
	v_mul_f32_e32 v26, 0.5, v26
	v_add_f32_e32 v32, 1.0, v32
	v_mul_f32_e32 v26, v26, v32
	v_mul_f32_e32 v35, 0x3d372713, v28
	v_mul_f32_e32 v35, v28, v35
	v_fma_f32 v35, v28, v35, v28
	v_mul_f32_e32 v35, 0x3f4c422a, v35
	v_add_f32_e32 v35, v35, v35
	v_mul_f32_e32 v35, 0x3fb8aa3b, v35
	v_exp_f32_e32 v35, v35
	v_rcp_f32_e32 v32, v33
	s_nop 0
	v_add_f32_e32 v32, v32, v32
	v_sub_f32_e32 v32, 1.0, v32
	v_add_f32_e32 v33, 1.0, v35
	v_mul_f32_e32 v27, 0.5, v27
	v_add_f32_e32 v32, 1.0, v32
	v_mul_f32_e32 v27, v27, v32
	v_cvt_pk_bf16_f32 v32, v26, v27
	v_mul_f32_e32 v35, 0x3d372713, v29
	v_mul_f32_e32 v35, v29, v35
	v_fma_f32 v35, v29, v35, v29
	v_mul_f32_e32 v35, 0x3f4c422a, v35
	v_add_f32_e32 v35, v35, v35
	v_mul_f32_e32 v35, 0x3fb8aa3b, v35
	v_exp_f32_e32 v35, v35
	v_rcp_f32_e32 v26, v33
	s_nop 0
	v_add_f32_e32 v26, v26, v26
	v_sub_f32_e32 v26, 1.0, v26
	v_add_f32_e32 v27, 1.0, v35
	v_mul_f32_e32 v28, 0.5, v28
	v_add_f32_e32 v26, 1.0, v26
	v_mul_f32_e32 v26, v28, v26
	v_rcp_f32_e32 v27, v27
	s_nop 0
	v_add_f32_e32 v27, v27, v27
	v_sub_f32_e32 v27, 1.0, v27
	v_mul_f32_e32 v28, 0.5, v29
	v_add_f32_e32 v27, 1.0, v27
	v_mul_f32_e32 v27, v28, v27
	v_mul_f32_e32 v28, 0x3d372713, v22
	v_mul_f32_e32 v28, v22, v28
	v_fma_f32 v28, v22, v28, v22
	v_mul_f32_e32 v28, 0x3f4c422a, v28
	v_add_f32_e32 v28, v28, v28
	v_mul_f32_e32 v28, 0x3fb8aa3b, v28
	v_exp_f32_e32 v28, v28
	v_or_b32_e32 v34, v171, v152
	v_ashrrev_i32_e32 v35, 31, v34
	v_cvt_pk_bf16_f32 v33, v26, v27
	v_add_f32_e32 v28, 1.0, v28
	v_lshlrev_b64 v[26:27], 11, v[34:35]
	v_lshl_add_u64 v[26:27], v[138:139], 0, v[26:27]
	global_store_dwordx4 v[26:27], v[30:33], off
	v_mul_f32_e32 v22, 0.5, v22
	v_mul_f32_e32 v29, 0x3d372713, v23
	v_mul_f32_e32 v29, v23, v29
	v_fma_f32 v29, v23, v29, v23
	v_mul_f32_e32 v29, 0x3f4c422a, v29
	v_add_f32_e32 v29, v29, v29
	v_mul_f32_e32 v29, 0x3fb8aa3b, v29
	v_exp_f32_e32 v29, v29
	v_rcp_f32_e32 v27, v28
	s_nop 0
	v_add_f32_e32 v27, v27, v27
	v_sub_f32_e32 v27, 1.0, v27
	v_add_f32_e32 v28, 1.0, v29
	v_add_f32_e32 v27, 1.0, v27
	v_mul_f32_e32 v22, v22, v27
	v_mul_f32_e32 v23, 0.5, v23
	v_mul_f32_e32 v29, 0x3d372713, v24
	v_mul_f32_e32 v29, v24, v29
	v_fma_f32 v29, v24, v29, v24
	v_mul_f32_e32 v29, 0x3f4c422a, v29
	v_add_f32_e32 v29, v29, v29
	v_mul_f32_e32 v29, 0x3fb8aa3b, v29
	v_exp_f32_e32 v29, v29
	v_rcp_f32_e32 v27, v28
	s_nop 0
	v_add_f32_e32 v27, v27, v27
	v_sub_f32_e32 v27, 1.0, v27
	v_add_f32_e32 v28, 1.0, v29
	v_add_f32_e32 v27, 1.0, v27
	v_mul_f32_e32 v23, v23, v27
	v_cvt_pk_bf16_f32 v22, v22, v23
	v_mul_f32_e32 v29, 0x3d372713, v25
	v_mul_f32_e32 v29, v25, v29
	v_fma_f32 v29, v25, v29, v25
	v_mul_f32_e32 v29, 0x3f4c422a, v29
	v_add_f32_e32 v29, v29, v29
	v_mul_f32_e32 v29, 0x3fb8aa3b, v29
	v_exp_f32_e32 v29, v29
	v_rcp_f32_e32 v23, v28
	s_nop 0
	v_add_f32_e32 v23, v23, v23
	v_sub_f32_e32 v23, 1.0, v23
	v_add_f32_e32 v27, 1.0, v29
	v_mul_f32_e32 v24, 0.5, v24
	v_add_f32_e32 v23, 1.0, v23
	v_mul_f32_e32 v23, v24, v23
	v_mul_f32_e32 v28, 0x3d372713, v18
	v_mul_f32_e32 v28, v18, v28
	v_fma_f32 v28, v18, v28, v18
	v_mul_f32_e32 v28, 0x3f4c422a, v28
	v_add_f32_e32 v28, v28, v28
	v_mul_f32_e32 v28, 0x3fb8aa3b, v28
	v_exp_f32_e32 v28, v28
	v_rcp_f32_e32 v24, v27
	s_nop 0
	v_add_f32_e32 v24, v24, v24
	v_sub_f32_e32 v24, 1.0, v24
	v_add_f32_e32 v27, 1.0, v28
	v_mul_f32_e32 v25, 0.5, v25
	v_add_f32_e32 v24, 1.0, v24
	v_mul_f32_e32 v24, v25, v24
	v_cvt_pk_bf16_f32 v23, v23, v24
	v_mul_f32_e32 v28, 0x3d372713, v19
	v_mul_f32_e32 v28, v19, v28
	v_fma_f32 v28, v19, v28, v19
	v_mul_f32_e32 v28, 0x3f4c422a, v28
	v_add_f32_e32 v28, v28, v28
	v_mul_f32_e32 v28, 0x3fb8aa3b, v28
	v_exp_f32_e32 v28, v28
	v_rcp_f32_e32 v24, v27
	s_nop 0
	v_add_f32_e32 v24, v24, v24
	v_sub_f32_e32 v24, 1.0, v24
	v_add_f32_e32 v25, 1.0, v28
	v_mul_f32_e32 v18, 0.5, v18
	v_add_f32_e32 v24, 1.0, v24
	v_mul_f32_e32 v18, v18, v24
	v_mul_f32_e32 v27, 0x3d372713, v20
	v_mul_f32_e32 v27, v20, v27
	v_fma_f32 v27, v20, v27, v20
	v_mul_f32_e32 v27, 0x3f4c422a, v27
	v_add_f32_e32 v27, v27, v27
	v_mul_f32_e32 v27, 0x3fb8aa3b, v27
	v_exp_f32_e32 v27, v27
	v_rcp_f32_e32 v24, v25
	s_nop 0
	v_add_f32_e32 v24, v24, v24
	v_sub_f32_e32 v24, 1.0, v24
	v_add_f32_e32 v25, 1.0, v27
; #define LAS __attribute__((address_space(3)))
; __device__ __forceinline__ unsigned cvt_pk_bf16(float lo, float hi) { unsigned r; asm volatile("v_cvt_pk_bf16_f32 %0, %1, %2" : "=v"(r) : "v"(lo), "v"(hi)); return r; }
; __device__ __forceinline__ float gelu_tanh(float x) { const float z = 0.7978845608f * (x + 0.044715f * x * x * x); const float th = 1.0f - 2.0f / (__expf(2.0f * z) + 1.0f); return 0.5f * x * (1.0f + th); }
;     __device__ __forceinline__ void operator()(const f32x4 (&acc)[2][2][4][2], const Unit& u, int ui, const LAS float* rtab, int wr, int wc, int fr, int fq) const {
;         const int g = u.pm; const int n0 = wr * 64 + fr; const int lc0 = (u.pn & 1) * 256 + wc * 32 + 8 * fq;
; #pragma unroll
;         for (int ai = 0; ai < 2; ++ai)
; #pragma unroll
;             for (int m = 0; m < 4; ++m) {
;                 const int n = n0 + ai * HALF + m * 16;
; #pragma unroll
;                 for (int bj = 0; bj < 2; ++bj) {
;                     const int lc = lc0 + bj * HALF, t = lc >> 4, co = lc & 15; const int token = n * 32 + t;
;                     const f32x4 a0 = acc[ai][bj][m][0], a1 = acc[ai][bj][m][1];
;                     u32x4 w; w.x = cvt_pk_bf16(gelu_tanh(a0[0]), gelu_tanh(a0[1])); w.y = cvt_pk_bf16(gelu_tanh(a0[2]), gelu_tanh(a0[3]));
;                     w.z = cvt_pk_bf16(gelu_tanh(a1[0]), gelu_tanh(a1[1])); w.w = cvt_pk_bf16(gelu_tanh(a1[2]), gelu_tanh(a1[3]));
;                     *(u32x4*)(Y + (size_t)token * 1024 + 16 * g + co) = w;
	v_mul_f32_e32 v19, 0.5, v19
	v_add_f32_e32 v24, 1.0, v24
	v_mul_f32_e32 v19, v19, v24
	v_cvt_pk_bf16_f32 v24, v18, v19
	v_mul_f32_e32 v27, 0x3d372713, v21
	v_mul_f32_e32 v27, v21, v27
	v_fma_f32 v27, v21, v27, v21
	v_mul_f32_e32 v27, 0x3f4c422a, v27
	v_add_f32_e32 v27, v27, v27
	v_mul_f32_e32 v27, 0x3fb8aa3b, v27
	v_exp_f32_e32 v27, v27
	v_rcp_f32_e32 v18, v25
	s_nop 0
	v_add_f32_e32 v18, v18, v18
	v_sub_f32_e32 v18, 1.0, v18
	v_add_f32_e32 v19, 1.0, v27
	v_mul_f32_e32 v20, 0.5, v20
	v_add_f32_e32 v18, 1.0, v18
	v_mul_f32_e32 v18, v20, v18
	v_rcp_f32_e32 v19, v19
	s_nop 0
	v_add_f32_e32 v19, v19, v19
	v_sub_f32_e32 v19, 1.0, v19
	v_mul_f32_e32 v20, 0.5, v21
	v_add_f32_e32 v19, 1.0, v19
	v_mul_f32_e32 v19, v20, v19
	v_mul_f32_e32 v20, 0x3d372713, v14
	v_mul_f32_e32 v20, v14, v20
	v_fma_f32 v20, v14, v20, v14
	v_mul_f32_e32 v20, 0x3f4c422a, v20
	v_add_f32_e32 v20, v20, v20
	v_mul_f32_e32 v20, 0x3fb8aa3b, v20
	v_exp_f32_e32 v20, v20
	v_or_b32_e32 v26, v124, v152
	v_ashrrev_i32_e32 v27, 31, v26
	v_cvt_pk_bf16_f32 v25, v18, v19
	v_add_f32_e32 v20, 1.0, v20
	v_lshlrev_b64 v[18:19], 11, v[26:27]
	v_lshl_add_u64 v[18:19], v[138:139], 0, v[18:19]
	global_store_dwordx4 v[18:19], v[22:25], off
	v_mul_f32_e32 v14, 0.5, v14
	v_mul_f32_e32 v21, 0x3d372713, v15
	v_mul_f32_e32 v21, v15, v21
	v_fma_f32 v21, v15, v21, v15
	v_mul_f32_e32 v21, 0x3f4c422a, v21
	v_add_f32_e32 v21, v21, v21
	v_mul_f32_e32 v21, 0x3fb8aa3b, v21
	v_exp_f32_e32 v21, v21
	v_rcp_f32_e32 v19, v20
	s_nop 0
	v_add_f32_e32 v19, v19, v19
	v_sub_f32_e32 v19, 1.0, v19
	v_add_f32_e32 v20, 1.0, v21
	v_add_f32_e32 v19, 1.0, v19
	v_mul_f32_e32 v14, v14, v19
	v_mul_f32_e32 v15, 0.5, v15
	v_mul_f32_e32 v21, 0x3d372713, v16
	v_mul_f32_e32 v21, v16, v21
	v_fma_f32 v21, v16, v21, v16
	v_mul_f32_e32 v21, 0x3f4c422a, v21
	v_add_f32_e32 v21, v21, v21
	v_mul_f32_e32 v21, 0x3fb8aa3b, v21
	v_exp_f32_e32 v21, v21
	v_rcp_f32_e32 v19, v20
	s_nop 0
	v_add_f32_e32 v19, v19, v19
	v_sub_f32_e32 v19, 1.0, v19
	v_add_f32_e32 v20, 1.0, v21
	v_add_f32_e32 v19, 1.0, v19
	v_mul_f32_e32 v15, v15, v19
	v_cvt_pk_bf16_f32 v14, v14, v15
	v_mul_f32_e32 v21, 0x3d372713, v17
	v_mul_f32_e32 v21, v17, v21
	v_fma_f32 v21, v17, v21, v17
	v_mul_f32_e32 v21, 0x3f4c422a, v21
	v_add_f32_e32 v21, v21, v21
	v_mul_f32_e32 v21, 0x3fb8aa3b, v21
	v_exp_f32_e32 v21, v21
	v_rcp_f32_e32 v15, v20
	s_nop 0
	v_add_f32_e32 v15, v15, v15
	v_sub_f32_e32 v15, 1.0, v15
	v_add_f32_e32 v19, 1.0, v21
	v_mul_f32_e32 v16, 0.5, v16
	v_add_f32_e32 v15, 1.0, v15
	v_mul_f32_e32 v15, v16, v15
	v_mul_f32_e32 v20, 0x3d372713, v10
	v_mul_f32_e32 v20, v10, v20
	v_fma_f32 v20, v10, v20, v10
	v_mul_f32_e32 v20, 0x3f4c422a, v20
	v_add_f32_e32 v20, v20, v20
	v_mul_f32_e32 v20, 0x3fb8aa3b, v20
	v_exp_f32_e32 v20, v20
	v_rcp_f32_e32 v16, v19
	s_nop 0
	v_add_f32_e32 v16, v16, v16
	v_sub_f32_e32 v16, 1.0, v16
	v_add_f32_e32 v19, 1.0, v20
	v_mul_f32_e32 v17, 0.5, v17
	v_add_f32_e32 v16, 1.0, v16
	v_mul_f32_e32 v16, v17, v16
	v_cvt_pk_bf16_f32 v15, v15, v16
	v_mul_f32_e32 v20, 0x3d372713, v11
	v_mul_f32_e32 v20, v11, v20
	v_fma_f32 v20, v11, v20, v11
	v_mul_f32_e32 v20, 0x3f4c422a, v20
	v_add_f32_e32 v20, v20, v20
	v_mul_f32_e32 v20, 0x3fb8aa3b, v20
	v_exp_f32_e32 v20, v20
	v_rcp_f32_e32 v16, v19
	s_nop 0
	v_add_f32_e32 v16, v16, v16
	v_sub_f32_e32 v16, 1.0, v16
	v_add_f32_e32 v17, 1.0, v20
	v_mul_f32_e32 v10, 0.5, v10
	v_add_f32_e32 v16, 1.0, v16
	v_mul_f32_e32 v10, v10, v16
	v_mul_f32_e32 v19, 0x3d372713, v12
	v_mul_f32_e32 v19, v12, v19
	v_fma_f32 v19, v12, v19, v12
	v_mul_f32_e32 v19, 0x3f4c422a, v19
	v_add_f32_e32 v19, v19, v19
	v_mul_f32_e32 v19, 0x3fb8aa3b, v19
	v_exp_f32_e32 v19, v19
	v_rcp_f32_e32 v16, v17
	s_nop 0
	v_add_f32_e32 v16, v16, v16
	v_sub_f32_e32 v16, 1.0, v16
	v_add_f32_e32 v17, 1.0, v19
	v_mul_f32_e32 v11, 0.5, v11
	v_add_f32_e32 v16, 1.0, v16
	v_mul_f32_e32 v11, v11, v16
	v_cvt_pk_bf16_f32 v16, v10, v11
	v_mul_f32_e32 v19, 0x3d372713, v13
	v_mul_f32_e32 v19, v13, v19
	v_fma_f32 v19, v13, v19, v13
	v_mul_f32_e32 v19, 0x3f4c422a, v19
	v_add_f32_e32 v19, v19, v19
	v_mul_f32_e32 v19, 0x3fb8aa3b, v19
	v_exp_f32_e32 v19, v19
	v_rcp_f32_e32 v10, v17
	s_nop 0
	v_add_f32_e32 v10, v10, v10
	v_sub_f32_e32 v10, 1.0, v10
	v_add_f32_e32 v11, 1.0, v19
	v_mul_f32_e32 v12, 0.5, v12
	v_add_f32_e32 v10, 1.0, v10
	v_mul_f32_e32 v10, v12, v10
; #define LAS __attribute__((address_space(3)))
; __device__ __forceinline__ unsigned cvt_pk_bf16(float lo, float hi) { unsigned r; asm volatile("v_cvt_pk_bf16_f32 %0, %1, %2" : "=v"(r) : "v"(lo), "v"(hi)); return r; }
; __device__ __forceinline__ float gelu_tanh(float x) { const float z = 0.7978845608f * (x + 0.044715f * x * x * x); const float th = 1.0f - 2.0f / (__expf(2.0f * z) + 1.0f); return 0.5f * x * (1.0f + th); }
;     __device__ __forceinline__ void operator()(const f32x4 (&acc)[2][2][4][2], const Unit& u, int ui, const LAS float* rtab, int wr, int wc, int fr, int fq) const {
;         const int g = u.pm; const int n0 = wr * 64 + fr; const int lc0 = (u.pn & 1) * 256 + wc * 32 + 8 * fq;
; #pragma unroll
;         for (int ai = 0; ai < 2; ++ai)
; #pragma unroll
;             for (int m = 0; m < 4; ++m) {
;                 const int n = n0 + ai * HALF + m * 16;
; #pragma unroll
;                 for (int bj = 0; bj < 2; ++bj) {
;                     const int lc = lc0 + bj * HALF, t = lc >> 4, co = lc & 15; const int token = n * 32 + t;
;                     const f32x4 a0 = acc[ai][bj][m][0], a1 = acc[ai][bj][m][1];
;                     u32x4 w; w.x = cvt_pk_bf16(gelu_tanh(a0[0]), gelu_tanh(a0[1])); w.y = cvt_pk_bf16(gelu_tanh(a0[2]), gelu_tanh(a0[3]));
;                     w.z = cvt_pk_bf16(gelu_tanh(a1[0]), gelu_tanh(a1[1])); w.w = cvt_pk_bf16(gelu_tanh(a1[2]), gelu_tanh(a1[3]));
;                     *(u32x4*)(Y + (size_t)token * 1024 + 16 * g + co) = w;
;                 }
;             }
;     }
	v_rcp_f32_e32 v11, v11
	s_nop 0
	v_add_f32_e32 v11, v11, v11
	v_sub_f32_e32 v11, 1.0, v11
	v_mul_f32_e32 v12, 0.5, v13
	v_add_f32_e32 v11, 1.0, v11
	v_mul_f32_e32 v11, v12, v11
	v_mul_f32_e32 v12, 0x3d372713, v6
	v_mul_f32_e32 v12, v6, v12
	v_fma_f32 v12, v6, v12, v6
	v_mul_f32_e32 v12, 0x3f4c422a, v12
	v_add_f32_e32 v12, v12, v12
	v_mul_f32_e32 v12, 0x3fb8aa3b, v12
	v_exp_f32_e32 v12, v12
	v_or_b32_e32 v18, v171, v153
	v_ashrrev_i32_e32 v19, 31, v18
	v_cvt_pk_bf16_f32 v17, v10, v11
	v_add_f32_e32 v12, 1.0, v12
	v_lshlrev_b64 v[10:11], 11, v[18:19]
	v_lshl_add_u64 v[10:11], v[138:139], 0, v[10:11]
	global_store_dwordx4 v[10:11], v[14:17], off
	v_mul_f32_e32 v6, 0.5, v6
	v_mul_f32_e32 v13, 0x3d372713, v7
	v_mul_f32_e32 v13, v7, v13
	v_fma_f32 v13, v7, v13, v7
	v_mul_f32_e32 v13, 0x3f4c422a, v13
	v_add_f32_e32 v13, v13, v13
	v_mul_f32_e32 v13, 0x3fb8aa3b, v13
	v_exp_f32_e32 v13, v13
	v_rcp_f32_e32 v11, v12
	s_nop 0
	v_add_f32_e32 v11, v11, v11
	v_sub_f32_e32 v11, 1.0, v11
	v_add_f32_e32 v12, 1.0, v13
	v_add_f32_e32 v11, 1.0, v11
	v_mul_f32_e32 v6, v6, v11
	v_mul_f32_e32 v7, 0.5, v7
	v_mul_f32_e32 v13, 0x3d372713, v8
	v_mul_f32_e32 v13, v8, v13
	v_fma_f32 v13, v8, v13, v8
	v_mul_f32_e32 v13, 0x3f4c422a, v13
	v_add_f32_e32 v13, v13, v13
	v_mul_f32_e32 v13, 0x3fb8aa3b, v13
	v_exp_f32_e32 v13, v13
	v_rcp_f32_e32 v11, v12
	s_nop 0
	v_add_f32_e32 v11, v11, v11
	v_sub_f32_e32 v11, 1.0, v11
	v_add_f32_e32 v12, 1.0, v13
	v_add_f32_e32 v11, 1.0, v11
	v_mul_f32_e32 v7, v7, v11
	v_cvt_pk_bf16_f32 v6, v6, v7
	v_mul_f32_e32 v13, 0x3d372713, v9
	v_mul_f32_e32 v13, v9, v13
	v_fma_f32 v13, v9, v13, v9
	v_mul_f32_e32 v13, 0x3f4c422a, v13
	v_add_f32_e32 v13, v13, v13
	v_mul_f32_e32 v13, 0x3fb8aa3b, v13
	v_exp_f32_e32 v13, v13
	v_rcp_f32_e32 v7, v12
	s_nop 0
	v_add_f32_e32 v7, v7, v7
	v_sub_f32_e32 v7, 1.0, v7
	v_add_f32_e32 v11, 1.0, v13
	v_mul_f32_e32 v8, 0.5, v8
	v_add_f32_e32 v7, 1.0, v7
	v_mul_f32_e32 v7, v8, v7
	v_mul_f32_e32 v12, 0x3d372713, v2
	v_mul_f32_e32 v12, v2, v12
	v_fma_f32 v12, v2, v12, v2
	v_mul_f32_e32 v12, 0x3f4c422a, v12
	v_add_f32_e32 v12, v12, v12
	v_mul_f32_e32 v12, 0x3fb8aa3b, v12
	v_exp_f32_e32 v12, v12
	v_rcp_f32_e32 v8, v11
	s_nop 0
	v_add_f32_e32 v8, v8, v8
	v_sub_f32_e32 v8, 1.0, v8
	v_add_f32_e32 v11, 1.0, v12
	v_mul_f32_e32 v9, 0.5, v9
	v_add_f32_e32 v8, 1.0, v8
	v_mul_f32_e32 v8, v9, v8
	v_cvt_pk_bf16_f32 v7, v7, v8
	v_mul_f32_e32 v12, 0x3d372713, v3
	v_mul_f32_e32 v12, v3, v12
	v_fma_f32 v12, v3, v12, v3
	v_mul_f32_e32 v12, 0x3f4c422a, v12
	v_add_f32_e32 v12, v12, v12
	v_mul_f32_e32 v12, 0x3fb8aa3b, v12
	v_exp_f32_e32 v12, v12
	v_rcp_f32_e32 v8, v11
	s_nop 0
	v_add_f32_e32 v8, v8, v8
	v_sub_f32_e32 v8, 1.0, v8
	v_add_f32_e32 v9, 1.0, v12
	v_mul_f32_e32 v2, 0.5, v2
	v_add_f32_e32 v8, 1.0, v8
	v_mul_f32_e32 v2, v2, v8
	v_mul_f32_e32 v11, 0x3d372713, v4
	v_mul_f32_e32 v11, v4, v11
	v_fma_f32 v11, v4, v11, v4
	v_mul_f32_e32 v11, 0x3f4c422a, v11
	v_add_f32_e32 v11, v11, v11
	v_mul_f32_e32 v11, 0x3fb8aa3b, v11
	v_exp_f32_e32 v11, v11
	v_rcp_f32_e32 v8, v9
	s_nop 0
	v_add_f32_e32 v8, v8, v8
	v_sub_f32_e32 v8, 1.0, v8
	v_add_f32_e32 v9, 1.0, v11
	v_mul_f32_e32 v3, 0.5, v3
	v_add_f32_e32 v8, 1.0, v8
	v_mul_f32_e32 v3, v3, v8
	v_cvt_pk_bf16_f32 v8, v2, v3
	v_mul_f32_e32 v11, 0x3d372713, v5
	v_mul_f32_e32 v11, v5, v11
	v_fma_f32 v11, v5, v11, v5
	v_mul_f32_e32 v11, 0x3f4c422a, v11
	v_add_f32_e32 v11, v11, v11
	v_mul_f32_e32 v11, 0x3fb8aa3b, v11
	v_exp_f32_e32 v11, v11
	v_rcp_f32_e32 v2, v9
	s_nop 0
	v_add_f32_e32 v2, v2, v2
	v_sub_f32_e32 v2, 1.0, v2
	v_add_f32_e32 v3, 1.0, v11
	v_div_scale_f32 v9, s[28:29], v3, v3, 2.0
	v_mul_f32_e32 v4, 0.5, v4
	v_add_f32_e32 v2, 1.0, v2
	v_mul_f32_e32 v2, v4, v2
	v_div_scale_f32 v4, vcc, 2.0, v3, 2.0
	v_rcp_f32_e32 v3, v3
	s_nop 0
	v_add_f32_e32 v3, v3, v3
	v_sub_f32_e32 v3, 1.0, v3
	v_or_b32_e32 v10, v124, v153
	v_mul_f32_e32 v4, 0.5, v5
	v_add_f32_e32 v3, 1.0, v3
	v_mul_f32_e32 v3, v4, v3
	v_ashrrev_i32_e32 v11, 31, v10
	v_cvt_pk_bf16_f32 v9, v2, v3
	v_lshlrev_b64 v[2:3], 11, v[10:11]
	v_lshl_add_u64 v[2:3], v[138:139], 0, v[2:3]
	s_mov_b64 s[42:43], 0
	s_and_b64 vcc, exec, s[40:41]
	v_readlane_b32 s26, v254, 32
	global_store_dwordx4 v[2:3], v[6:9], off
	s_cbranch_vccz .LBB0_594
	s_waitcnt vmcnt(0)
	s_cmpk_gt_u32 s12, 0xff
	s_cbranch_scc1 .LBB0_599
	s_barrier

; #define PG8_STAGE(bufoff, gbase, voff) do { _Pragma("unroll") for (int _i = 0; _i < 2; ++_i) \
;         __builtin_amdgcn_global_load_lds((const unsigned*)((const char*)(gbase) + (voff)[_i]), (LAS unsigned*)(lds + (bufoff) + ldsw + _i * 8192), 16, 0, 0); } while (0)
; #define PG8_LDA(dst, b, h) do { _Pragma("unroll") for (int m = 0; m < 4; ++m) _Pragma("unroll") for (int k = 0; k < 2; ++k) dst[m][k] = *(const LAS bf16x8*)(lds + PG8_SA(b, h) + aoff + m * 2048 + k * 1024); } while (0)
; #define PG8_LDB(dst, b, h) do { _Pragma("unroll") for (int n = 0; n < 2; ++n) _Pragma("unroll") for (int k = 0; k < 2; ++k) dst[n][k] = *(const LAS bf16x8*)(lds + PG8_SB(b, h) + boff + n * 2048 + k * 1024); } while (0)
; #define PG8_MMA(ai, bj, At, Bt) do { __builtin_amdgcn_s_setprio(1); _Pragma("unroll") for (int m = 0; m < 4; ++m) _Pragma("unroll") for (int n = 0; n < 2; ++n) _Pragma("unroll") for (int k = 0; k < 2; ++k) \
;         acc[ai][bj][m][n] = __builtin_amdgcn_mfma_f32_16x16x32_bf16(Bt[n][k], At[m][k], acc[ai][bj][m][n], 0, 0, 0); __builtin_amdgcn_s_setprio(0); } while (0)
; #define PG8_WAIT_L(n) asm volatile("s_waitcnt lgkmcnt(" #n ")" ::: "memory")
; #define PG8_BAR __builtin_amdgcn_s_barrier()
; #define PG8_SCHED __builtin_amdgcn_sched_barrier(0)
; template <class Epi, class Sched>
; __device__ __forceinline__ void gemm_phase(LAS unsigned char* lds, const Gemm g, const Sched& S, const Epi& E) {
;     ...
;             PG8_LDB(B0, 0, 0); PG8_SCHED; PG8_LDA(At, 0, 0); PG8_STAGE(PG8_SA(1, 1), a1 + hstepA, voffA);
;             PG8_WAIT_L(8); PG8_BAR; PG8_WAIT_L(0); PG8_MMA(0, 0, At, B0); PG8_BAR; PG8_SCHED;
;             PG8_LDB(B1, 0, 1); PG8_STAGE(PG8_SB(0, 0), b2, voffB);
;             PG8_BAR; PG8_WAIT_L(0); PG8_MMA(0, 1, At, B1); PG8_BAR;
;             PG8_LDA(At, 0, 1); PG8_STAGE(PG8_SA(0, 0), a2, voffA);
;             PG8_BAR; PG8_WAIT_L(0); PG8_MMA(1, 0, At, B0); PG8_BAR; PG8_SCHED;
.LBB0_668:
	s_add_u32 s23, s20, 0xfffc0080
	s_addc_u32 s34, s21, -1
	s_add_i32 s43, 0, 0x10000
	v_add_u32_e32 v153, s43, v150
	ds_read_b128 v[142:145], v153
	ds_read_b128 v[146:149], v153 offset:1024
	ds_read_b128 v[170:173], v153 offset:2048
	ds_read_b128 v[174:177], v153 offset:3072
	s_cmp_eq_u32 s31, 12
	s_cselect_b32 s49, s24, s34
	s_cselect_b32 s48, s25, s23
	s_cselect_b32 s37, s1, s29
	s_cselect_b32 s36, s26, s28
	v_lshl_add_u64 v[198:199], s[20:21], 0, v[138:139]
	s_add_i32 m0, s52, 0xc000
	ds_read_b128 v[178:181], v152
	ds_read_b128 v[182:185], v152 offset:1024
	ds_read_b128 v[186:189], v152 offset:2048
	ds_read_b128 v[190:193], v152 offset:3072
	ds_read_b128 v[194:197], v152 offset:4096
	ds_read_b128 v[210:213], v152 offset:5120
	ds_read_b128 v[214:217], v152 offset:6144
	ds_read_b128 v[218:221], v152 offset:7168
	global_load_lds_dwordx4 v[198:199], off
	v_lshl_add_u64 v[198:199], s[20:21], 0, v[140:141]
	s_add_i32 m0, s52, 0xe000
	s_nop 0
	global_load_lds_dwordx4 v[198:199], off
	s_waitcnt lgkmcnt(8)
	s_barrier
	s_waitcnt lgkmcnt(0)
	s_setprio 1
	s_waitcnt lgkmcnt(0)
	v_mfma_f32_16x16x32_bf16 v[126:129], v[142:145], v[178:181], v[126:129]
	v_mfma_f32_16x16x32_bf16 v[122:125], v[170:173], v[178:181], v[122:125]
	v_mfma_f32_16x16x32_bf16 v[110:113], v[142:145], v[186:189], v[110:113]
	v_mfma_f32_16x16x32_bf16 v[106:109], v[170:173], v[186:189], v[106:109]
	v_mfma_f32_16x16x32_bf16 v[94:97], v[142:145], v[194:197], v[94:97]
	v_mfma_f32_16x16x32_bf16 v[90:93], v[170:173], v[194:197], v[90:93]
	v_mfma_f32_16x16x32_bf16 v[78:81], v[142:145], v[214:217], v[78:81]
	v_mfma_f32_16x16x32_bf16 v[74:77], v[170:173], v[214:217], v[74:77]
	v_mfma_f32_16x16x32_bf16 v[126:129], v[146:149], v[182:185], v[126:129]
	v_mfma_f32_16x16x32_bf16 v[122:125], v[174:177], v[182:185], v[122:125]
	v_mfma_f32_16x16x32_bf16 v[110:113], v[146:149], v[190:193], v[110:113]
	v_mfma_f32_16x16x32_bf16 v[106:109], v[174:177], v[190:193], v[106:109]
	v_mfma_f32_16x16x32_bf16 v[94:97], v[146:149], v[210:213], v[94:97]
	v_mfma_f32_16x16x32_bf16 v[90:93], v[174:177], v[210:213], v[90:93]
	v_mfma_f32_16x16x32_bf16 v[78:81], v[146:149], v[218:221], v[78:81]
	v_mfma_f32_16x16x32_bf16 v[74:77], v[174:177], v[218:221], v[74:77]
	s_setprio 0
	s_barrier
	s_add_i32 s23, 0, 0x14000
	s_add_i32 s34, s43, s51
	v_add_u32_e32 v153, s23, v150
	v_lshl_add_u64 v[198:199], s[36:37], 0, v[134:135]
	s_mov_b32 m0, s34
	ds_read_b128 v[222:225], v153
	ds_read_b128 v[226:229], v153 offset:1024
	ds_read_b128 v[230:233], v153 offset:2048
	ds_read_b128 v[234:237], v153 offset:3072
	global_load_lds_dwordx4 v[198:199], off
	v_lshl_add_u64 v[238:239], s[36:37], 0, v[130:131]
	s_add_i32 m0, s34, 0x2000
	s_nop 0
	global_load_lds_dwordx4 v[238:239], off
	s_barrier
	s_waitcnt lgkmcnt(0)
	s_setprio 1
	s_waitcnt lgkmcnt(0)
	v_mfma_f32_16x16x32_bf16 v[118:121], v[222:225], v[178:181], v[118:121]
	v_mfma_f32_16x16x32_bf16 v[114:117], v[230:233], v[178:181], v[114:117]
	v_mfma_f32_16x16x32_bf16 v[102:105], v[222:225], v[186:189], v[102:105]
	v_mfma_f32_16x16x32_bf16 v[98:101], v[230:233], v[186:189], v[98:101]
	v_mfma_f32_16x16x32_bf16 v[86:89], v[222:225], v[194:197], v[86:89]
	v_mfma_f32_16x16x32_bf16 v[82:85], v[230:233], v[194:197], v[82:85]
	v_mfma_f32_16x16x32_bf16 v[70:73], v[222:225], v[214:217], v[70:73]
	v_mfma_f32_16x16x32_bf16 v[66:69], v[230:233], v[214:217], v[66:69]
	v_mfma_f32_16x16x32_bf16 v[118:121], v[226:229], v[182:185], v[118:121]
	v_mfma_f32_16x16x32_bf16 v[114:117], v[234:237], v[182:185], v[114:117]
	v_mfma_f32_16x16x32_bf16 v[102:105], v[226:229], v[190:193], v[102:105]
	v_mfma_f32_16x16x32_bf16 v[98:101], v[234:237], v[190:193], v[98:101]
	v_mfma_f32_16x16x32_bf16 v[86:89], v[226:229], v[210:213], v[86:89]
	v_mfma_f32_16x16x32_bf16 v[82:85], v[234:237], v[210:213], v[82:85]
	v_mfma_f32_16x16x32_bf16 v[70:73], v[226:229], v[218:221], v[70:73]
	v_mfma_f32_16x16x32_bf16 v[66:69], v[234:237], v[218:221], v[66:69]
	s_setprio 0
	s_mov_b32 m0, s52
	v_lshl_add_u64 v[240:241], s[48:49], 0, v[136:137]
	s_barrier
	ds_read_b128 v[178:181], v152 offset:16384
	ds_read_b128 v[182:185], v152 offset:17408
	ds_read_b128 v[186:189], v152 offset:18432
	ds_read_b128 v[190:193], v152 offset:19456
	ds_read_b128 v[194:197], v152 offset:20480
	ds_read_b128 v[210:213], v152 offset:21504
	ds_read_b128 v[214:217], v152 offset:22528
	ds_read_b128 v[218:221], v152 offset:23552
	global_load_lds_dwordx4 v[240:241], off
	v_lshl_add_u64 v[242:243], s[48:49], 0, v[132:133]
	s_mov_b32 m0, s53
	s_nop 0
	global_load_lds_dwordx4 v[242:243], off
	s_barrier
	s_waitcnt lgkmcnt(0)
	s_setprio 1
	s_waitcnt lgkmcnt(0)
	v_mfma_f32_16x16x32_bf16 v[62:65], v[142:145], v[178:181], v[62:65]
	v_mfma_f32_16x16x32_bf16 v[58:61], v[170:173], v[178:181], v[58:61]
	v_mfma_f32_16x16x32_bf16 v[46:49], v[142:145], v[186:189], v[46:49]
	v_mfma_f32_16x16x32_bf16 v[42:45], v[170:173], v[186:189], v[42:45]
	v_mfma_f32_16x16x32_bf16 v[30:33], v[142:145], v[194:197], v[30:33]
	v_mfma_f32_16x16x32_bf16 v[26:29], v[170:173], v[194:197], v[26:29]
	v_mfma_f32_16x16x32_bf16 v[14:17], v[142:145], v[214:217], v[14:17]
	v_mfma_f32_16x16x32_bf16 v[10:13], v[170:173], v[214:217], v[10:13]
	v_mfma_f32_16x16x32_bf16 v[62:65], v[146:149], v[182:185], v[62:65]
	v_mfma_f32_16x16x32_bf16 v[58:61], v[174:177], v[182:185], v[58:61]
	v_mfma_f32_16x16x32_bf16 v[46:49], v[146:149], v[190:193], v[46:49]
	v_mfma_f32_16x16x32_bf16 v[42:45], v[174:177], v[190:193], v[42:45]
	v_mfma_f32_16x16x32_bf16 v[30:33], v[146:149], v[210:213], v[30:33]
	v_mfma_f32_16x16x32_bf16 v[26:29], v[174:177], v[210:213], v[26:29]
	v_mfma_f32_16x16x32_bf16 v[14:17], v[146:149], v[218:221], v[14:17]
	v_mfma_f32_16x16x32_bf16 v[10:13], v[174:177], v[218:221], v[10:13]
	s_setprio 0
	s_barrier
; #define PG8_STAGE(bufoff, gbase, voff) do { _Pragma("unroll") for (int _i = 0; _i < 2; ++_i) \
;         __builtin_amdgcn_global_load_lds((const unsigned*)((const char*)(gbase) + (voff)[_i]), (LAS unsigned*)(lds + (bufoff) + ldsw + _i * 8192), 16, 0, 0); } while (0)
; #define PG8_LDA(dst, b, h) do { _Pragma("unroll") for (int m = 0; m < 4; ++m) _Pragma("unroll") for (int k = 0; k < 2; ++k) dst[m][k] = *(const LAS bf16x8*)(lds + PG8_SA(b, h) + aoff + m * 2048 + k * 1024); } while (0)
; #define PG8_LDB(dst, b, h) do { _Pragma("unroll") for (int n = 0; n < 2; ++n) _Pragma("unroll") for (int k = 0; k < 2; ++k) dst[n][k] = *(const LAS bf16x8*)(lds + PG8_SB(b, h) + boff + n * 2048 + k * 1024); } while (0)
; #define PG8_MMA(ai, bj, At, Bt) do { __builtin_amdgcn_s_setprio(1); _Pragma("unroll") for (int m = 0; m < 4; ++m) _Pragma("unroll") for (int n = 0; n < 2; ++n) _Pragma("unroll") for (int k = 0; k < 2; ++k) \
;         acc[ai][bj][m][n] = __builtin_amdgcn_mfma_f32_16x16x32_bf16(Bt[n][k], At[m][k], acc[ai][bj][m][n], 0, 0, 0); __builtin_amdgcn_s_setprio(0); } while (0)
; #define PG8_WAIT_V(n) asm volatile("s_waitcnt vmcnt(" #n ")" ::: "memory")
; #define PG8_WAIT_L(n) asm volatile("s_waitcnt lgkmcnt(" #n ")" ::: "memory")
; #define PG8_BAR __builtin_amdgcn_s_barrier()
; #define PG8_SCHED __builtin_amdgcn_sched_barrier(0)
; template <class Epi, class Sched>
; __device__ __forceinline__ void gemm_phase(LAS unsigned char* lds, const Gemm g, const Sched& S, const Epi& E) {
;     ...
;             PG8_BAR; PG8_WAIT_L(0); PG8_MMA(1, 0, At, B0); PG8_BAR; PG8_SCHED;
;             PG8_STAGE(PG8_SB(0, 1), b2 + hstepB, voffB);
;             PG8_WAIT_V(6); PG8_BAR; PG8_MMA(1, 1, At, B1); PG8_BAR;
;             PG8_LDB(B0, 1, 0); PG8_SCHED; PG8_LDA(At, 1, 0); PG8_STAGE(PG8_SA(0, 1), a2 + hstepA, voffA);
;             PG8_WAIT_L(8); PG8_BAR; PG8_WAIT_L(0); PG8_MMA(0, 0, At, B0); PG8_BAR; PG8_SCHED;
;             PG8_LDB(B1, 1, 1); PG8_STAGE(PG8_SB(1, 0), b3, voffB);
;             PG8_BAR; PG8_WAIT_L(0); PG8_MMA(0, 1, At, B1); PG8_BAR;
;             PG8_LDA(At, 1, 1); PG8_STAGE(PG8_SA(1, 0), a3, voffA);
;             PG8_BAR; PG8_WAIT_L(0); PG8_MMA(1, 0, At, B0); PG8_BAR; PG8_SCHED;
	s_add_u32 s66, s36, 0x40000
	s_addc_u32 s67, s37, 0
	s_add_i32 s23, s23, s51
	v_lshl_add_u64 v[142:143], s[66:67], 0, v[134:135]
	s_mov_b32 m0, s23
	s_nop 0
	global_load_lds_dwordx4 v[142:143], off
	v_lshl_add_u64 v[142:143], s[66:67], 0, v[130:131]
	s_add_i32 m0, s23, 0x2000
	s_nop 0
	global_load_lds_dwordx4 v[142:143], off
	s_waitcnt vmcnt(6)
	s_barrier
	s_setprio 1
	v_mfma_f32_16x16x32_bf16 v[54:57], v[222:225], v[178:181], v[54:57]
	v_mfma_f32_16x16x32_bf16 v[50:53], v[230:233], v[178:181], v[50:53]
	v_mfma_f32_16x16x32_bf16 v[38:41], v[222:225], v[186:189], v[38:41]
	v_mfma_f32_16x16x32_bf16 v[34:37], v[230:233], v[186:189], v[34:37]
	v_mfma_f32_16x16x32_bf16 v[22:25], v[222:225], v[194:197], v[22:25]
	v_mfma_f32_16x16x32_bf16 v[18:21], v[230:233], v[194:197], v[18:21]
	v_mfma_f32_16x16x32_bf16 v[6:9], v[222:225], v[214:217], v[6:9]
	v_mfma_f32_16x16x32_bf16 v[2:5], v[230:233], v[214:217], v[2:5]
	v_mfma_f32_16x16x32_bf16 v[54:57], v[226:229], v[182:185], v[54:57]
	v_mfma_f32_16x16x32_bf16 v[50:53], v[234:237], v[182:185], v[50:53]
	v_mfma_f32_16x16x32_bf16 v[38:41], v[226:229], v[190:193], v[38:41]
	v_mfma_f32_16x16x32_bf16 v[34:37], v[234:237], v[190:193], v[34:37]
	v_mfma_f32_16x16x32_bf16 v[22:25], v[226:229], v[210:213], v[22:25]
	v_mfma_f32_16x16x32_bf16 v[18:21], v[234:237], v[210:213], v[18:21]
	v_mfma_f32_16x16x32_bf16 v[6:9], v[226:229], v[218:221], v[6:9]
	v_mfma_f32_16x16x32_bf16 v[2:5], v[234:237], v[218:221], v[2:5]
	s_setprio 0
	s_add_i32 s23, 0, 0x18000
	v_add_u32_e32 v153, s23, v150
	s_barrier
	ds_read_b128 v[142:145], v153
	ds_read_b128 v[146:149], v153 offset:1024
	ds_read_b128 v[170:173], v153 offset:2048
	ds_read_b128 v[174:177], v153 offset:3072
	s_add_u32 s48, s48, 0x40000
	s_addc_u32 s49, s49, 0
	s_mov_b32 m0, s54
	v_lshl_add_u64 v[222:223], s[48:49], 0, v[136:137]
	ds_read_b128 v[178:181], v152 offset:32768
	ds_read_b128 v[182:185], v152 offset:33792
	ds_read_b128 v[186:189], v152 offset:34816
	ds_read_b128 v[190:193], v152 offset:35840
	ds_read_b128 v[194:197], v152 offset:36864
	ds_read_b128 v[210:213], v152 offset:37888
	ds_read_b128 v[214:217], v152 offset:38912
	ds_read_b128 v[218:221], v152 offset:39936
	global_load_lds_dwordx4 v[222:223], off
	v_lshl_add_u64 v[222:223], s[48:49], 0, v[132:133]
	s_mov_b32 m0, s55
	s_nop 0
	global_load_lds_dwordx4 v[222:223], off
	s_waitcnt lgkmcnt(8)
	s_barrier
	s_waitcnt lgkmcnt(0)
	s_setprio 1
	s_waitcnt lgkmcnt(0)
	v_mfma_f32_16x16x32_bf16 v[126:129], v[142:145], v[178:181], v[126:129]
	v_mfma_f32_16x16x32_bf16 v[122:125], v[170:173], v[178:181], v[122:125]
	v_mfma_f32_16x16x32_bf16 v[110:113], v[142:145], v[186:189], v[110:113]
	v_mfma_f32_16x16x32_bf16 v[106:109], v[170:173], v[186:189], v[106:109]
	v_mfma_f32_16x16x32_bf16 v[94:97], v[142:145], v[194:197], v[94:97]
	v_mfma_f32_16x16x32_bf16 v[90:93], v[170:173], v[194:197], v[90:93]
	v_mfma_f32_16x16x32_bf16 v[78:81], v[142:145], v[214:217], v[78:81]
	v_mfma_f32_16x16x32_bf16 v[74:77], v[170:173], v[214:217], v[74:77]
	v_mfma_f32_16x16x32_bf16 v[126:129], v[146:149], v[182:185], v[126:129]
	v_mfma_f32_16x16x32_bf16 v[122:125], v[174:177], v[182:185], v[122:125]
	v_mfma_f32_16x16x32_bf16 v[110:113], v[146:149], v[190:193], v[110:113]
	v_mfma_f32_16x16x32_bf16 v[106:109], v[174:177], v[190:193], v[106:109]
	v_mfma_f32_16x16x32_bf16 v[94:97], v[146:149], v[210:213], v[94:97]
	v_mfma_f32_16x16x32_bf16 v[90:93], v[174:177], v[210:213], v[90:93]
	v_mfma_f32_16x16x32_bf16 v[78:81], v[146:149], v[218:221], v[78:81]
	v_mfma_f32_16x16x32_bf16 v[74:77], v[174:177], v[218:221], v[74:77]
	s_setprio 0
	s_barrier
	s_add_i32 s34, 0, 0x1c000
	s_add_i32 s23, s23, s51
	v_add_u32_e32 v153, s34, v150
	v_lshl_add_u64 v[198:199], v[198:199], 0, s[10:11]
	s_mov_b32 m0, s23
	ds_read_b128 v[222:225], v153
	ds_read_b128 v[226:229], v153 offset:1024
	ds_read_b128 v[230:233], v153 offset:2048
	ds_read_b128 v[234:237], v153 offset:3072
	global_load_lds_dwordx4 v[198:199], off
	v_lshl_add_u64 v[198:199], v[238:239], 0, s[10:11]
	s_add_i32 m0, s23, 0x2000
	s_nop 0
	global_load_lds_dwordx4 v[198:199], off
	s_barrier
	s_waitcnt lgkmcnt(0)
	s_setprio 1
	s_waitcnt lgkmcnt(0)
	v_mfma_f32_16x16x32_bf16 v[118:121], v[222:225], v[178:181], v[118:121]
	v_mfma_f32_16x16x32_bf16 v[114:117], v[230:233], v[178:181], v[114:117]
	v_mfma_f32_16x16x32_bf16 v[102:105], v[222:225], v[186:189], v[102:105]
	v_mfma_f32_16x16x32_bf16 v[98:101], v[230:233], v[186:189], v[98:101]
	v_mfma_f32_16x16x32_bf16 v[86:89], v[222:225], v[194:197], v[86:89]
	v_mfma_f32_16x16x32_bf16 v[82:85], v[230:233], v[194:197], v[82:85]
	v_mfma_f32_16x16x32_bf16 v[70:73], v[222:225], v[214:217], v[70:73]
	v_mfma_f32_16x16x32_bf16 v[66:69], v[230:233], v[214:217], v[66:69]
	v_mfma_f32_16x16x32_bf16 v[118:121], v[226:229], v[182:185], v[118:121]
	v_mfma_f32_16x16x32_bf16 v[114:117], v[234:237], v[182:185], v[114:117]
	v_mfma_f32_16x16x32_bf16 v[102:105], v[226:229], v[190:193], v[102:105]
	v_mfma_f32_16x16x32_bf16 v[98:101], v[234:237], v[190:193], v[98:101]
	v_mfma_f32_16x16x32_bf16 v[86:89], v[226:229], v[210:213], v[86:89]
	v_mfma_f32_16x16x32_bf16 v[82:85], v[234:237], v[210:213], v[82:85]
	v_mfma_f32_16x16x32_bf16 v[70:73], v[226:229], v[218:221], v[70:73]
	v_mfma_f32_16x16x32_bf16 v[66:69], v[234:237], v[218:221], v[66:69]
	s_setprio 0
	s_mov_b32 m0, s56
	v_lshl_add_u64 v[198:199], v[240:241], 0, s[10:11]
	s_barrier
	ds_read_b128 v[178:181], v152 offset:49152
	ds_read_b128 v[182:185], v152 offset:50176
	ds_read_b128 v[186:189], v152 offset:51200
	ds_read_b128 v[190:193], v152 offset:52224
	ds_read_b128 v[194:197], v152 offset:53248
	ds_read_b128 v[210:213], v152 offset:54272
	ds_read_b128 v[214:217], v152 offset:55296
	ds_read_b128 v[218:221], v152 offset:56320
	global_load_lds_dwordx4 v[198:199], off
	v_lshl_add_u64 v[198:199], v[242:243], 0, s[10:11]
	s_mov_b32 m0, s57
	s_nop 0
	global_load_lds_dwordx4 v[198:199], off
	s_barrier
; __device__ __forceinline__ float bf_lo(unsigned w) { return __uint_as_float(w << 16); }
; __device__ __forceinline__ float bf_hi(unsigned w) { return __uint_as_float(w & 0xffff0000u); }
; #define PG8_STAGE(bufoff, gbase, voff) do { _Pragma("unroll") for (int _i = 0; _i < 2; ++_i) \
;         __builtin_amdgcn_global_load_lds((const unsigned*)((const char*)(gbase) + (voff)[_i]), (LAS unsigned*)(lds + (bufoff) + ldsw + _i * 8192), 16, 0, 0); } while (0)
; #define PG8_MMA(ai, bj, At, Bt) do { __builtin_amdgcn_s_setprio(1); _Pragma("unroll") for (int m = 0; m < 4; ++m) _Pragma("unroll") for (int n = 0; n < 2; ++n) _Pragma("unroll") for (int k = 0; k < 2; ++k) \
;         acc[ai][bj][m][n] = __builtin_amdgcn_mfma_f32_16x16x32_bf16(Bt[n][k], At[m][k], acc[ai][bj][m][n], 0, 0, 0); __builtin_amdgcn_s_setprio(0); } while (0)
; #define PG8_WAIT_V(n) asm volatile("s_waitcnt vmcnt(" #n ")" ::: "memory")
; #define PG8_WAIT_L(n) asm volatile("s_waitcnt lgkmcnt(" #n ")" ::: "memory")
;     __device__ __forceinline__ void operator()(const f32x4 (&acc)[2][2][4][2], const Unit& u, int ui, const LAS float* rtab, int wr, int wc, int fr, int fq) const {
;         const int row0 = u.pm * BM + wr * 64 + fr, col0 = u.pn * BM + wc * 32 + 8 * fq;
; #pragma unroll
;         for (int ai = 0; ai < 2; ++ai)
; #pragma unroll
;             for (int m = 0; m < 4; ++m) {
;                 const int row = row0 + ai * HALF + m * 16;
; #pragma unroll
;                 for (int bj = 0; bj < 2; ++bj) {
;                     const int col = col0 + bj * HALF; const u32x4 yv = *(const u32x4*)(Y + (size_t)row * 1024 + col);
;                     const f32x4 a0 = acc[ai][bj][m][0], a1 = acc[ai][bj][m][1]; float o[8];
;                     const float yy[8] = {bf_lo(yv.x), bf_hi(yv.x), bf_lo(yv.y), bf_hi(yv.y), bf_lo(yv.z), bf_hi(yv.z), bf_lo(yv.w), bf_hi(yv.w)};
; #pragma unroll
;                     for (int e = 0; e < 4; ++e) { o[e] = yy[e] / (1.0f + __expf(-a0[e])); o[4 + e] = yy[4 + e] / (1.0f + __expf(-a1[e])); }
; template <class Epi, class Sched>
; __device__ __forceinline__ void gemm_phase(LAS unsigned char* lds, const Gemm g, const Sched& S, const Epi& E) {
;     ...
;             PG8_BAR; PG8_WAIT_L(0); PG8_MMA(1, 0, At, B0); PG8_BAR; PG8_SCHED;
;             PG8_STAGE(PG8_SB(1, 1), b3 + hstepB, voffB);
;             PG8_WAIT_V(6); PG8_BAR; PG8_MMA(1, 1, At, B1); PG8_BAR;
;         }
	s_waitcnt lgkmcnt(0)
	s_setprio 1
	s_waitcnt lgkmcnt(0)
	v_mfma_f32_16x16x32_bf16 v[62:65], v[142:145], v[178:181], v[62:65]
	v_mfma_f32_16x16x32_bf16 v[58:61], v[170:173], v[178:181], v[58:61]
	v_mfma_f32_16x16x32_bf16 v[46:49], v[142:145], v[186:189], v[46:49]
	v_mfma_f32_16x16x32_bf16 v[42:45], v[170:173], v[186:189], v[42:45]
	v_mfma_f32_16x16x32_bf16 v[30:33], v[142:145], v[194:197], v[30:33]
	v_mfma_f32_16x16x32_bf16 v[26:29], v[170:173], v[194:197], v[26:29]
	v_mfma_f32_16x16x32_bf16 v[14:17], v[142:145], v[214:217], v[14:17]
	v_mfma_f32_16x16x32_bf16 v[10:13], v[170:173], v[214:217], v[10:13]
	v_mfma_f32_16x16x32_bf16 v[62:65], v[146:149], v[182:185], v[62:65]
	v_mfma_f32_16x16x32_bf16 v[58:61], v[174:177], v[182:185], v[58:61]
	v_mfma_f32_16x16x32_bf16 v[46:49], v[146:149], v[190:193], v[46:49]
	v_mfma_f32_16x16x32_bf16 v[42:45], v[174:177], v[190:193], v[42:45]
	v_mfma_f32_16x16x32_bf16 v[30:33], v[146:149], v[210:213], v[30:33]
	v_mfma_f32_16x16x32_bf16 v[26:29], v[174:177], v[210:213], v[26:29]
	v_mfma_f32_16x16x32_bf16 v[14:17], v[146:149], v[218:221], v[14:17]
	v_mfma_f32_16x16x32_bf16 v[10:13], v[174:177], v[218:221], v[10:13]
	s_setprio 0
	s_barrier
	s_add_u32 s36, s36, 0x40080
	s_addc_u32 s37, s37, 0
	s_add_i32 s23, s34, s51
	v_lshl_add_u64 v[142:143], s[36:37], 0, v[134:135]
	s_mov_b32 m0, s23
	s_nop 0
	global_load_lds_dwordx4 v[142:143], off
	v_lshl_add_u64 v[142:143], s[36:37], 0, v[130:131]
	s_add_i32 m0, s23, 0x2000
	s_nop 0
	global_load_lds_dwordx4 v[142:143], off
	s_waitcnt vmcnt(6)
	s_barrier
	s_setprio 1
	v_mfma_f32_16x16x32_bf16 v[54:57], v[222:225], v[178:181], v[54:57]
	v_mfma_f32_16x16x32_bf16 v[50:53], v[230:233], v[178:181], v[50:53]
	v_mfma_f32_16x16x32_bf16 v[38:41], v[222:225], v[186:189], v[38:41]
	v_mfma_f32_16x16x32_bf16 v[34:37], v[230:233], v[186:189], v[34:37]
	v_mfma_f32_16x16x32_bf16 v[22:25], v[222:225], v[194:197], v[22:25]
	v_mfma_f32_16x16x32_bf16 v[18:21], v[230:233], v[194:197], v[18:21]
	v_mfma_f32_16x16x32_bf16 v[6:9], v[222:225], v[214:217], v[6:9]
	v_mfma_f32_16x16x32_bf16 v[2:5], v[230:233], v[214:217], v[2:5]
	v_mfma_f32_16x16x32_bf16 v[54:57], v[226:229], v[182:185], v[54:57]
	v_mfma_f32_16x16x32_bf16 v[50:53], v[234:237], v[182:185], v[50:53]
	v_mfma_f32_16x16x32_bf16 v[38:41], v[226:229], v[190:193], v[38:41]
	v_mfma_f32_16x16x32_bf16 v[34:37], v[234:237], v[190:193], v[34:37]
	v_mfma_f32_16x16x32_bf16 v[22:25], v[226:229], v[210:213], v[22:25]
	v_mfma_f32_16x16x32_bf16 v[18:21], v[234:237], v[210:213], v[18:21]
	v_mfma_f32_16x16x32_bf16 v[6:9], v[226:229], v[218:221], v[6:9]
	v_mfma_f32_16x16x32_bf16 v[2:5], v[234:237], v[218:221], v[2:5]
	s_setprio 0
	s_add_i32 s31, s31, 2
	s_add_u32 s20, s20, 0x100
	s_addc_u32 s21, s21, 0
	s_add_u32 s28, s28, 0x100
	s_addc_u32 s29, s29, 0
	s_cmp_gt_u32 s31, 13
	s_barrier
	s_cbranch_scc0 .LBB0_668
	v_lshl_add_u32 v144, s13, 8, v1
	v_lshl_or_b32 v142, s12, 8, v151
	v_ashrrev_i32_e32 v145, 31, v144
	v_lshlrev_b64 v[146:147], 11, v[144:145]
	v_ashrrev_i32_e32 v143, 31, v142
	v_lshl_add_u64 v[146:147], s[86:87], 0, v[146:147]
	v_lshlrev_b64 v[142:143], 1, v[142:143]
	v_lshl_add_u64 v[146:147], v[146:147], 0, v[142:143]
	global_load_dwordx4 v[170:173], v[146:147], off
	v_mul_f32_e32 v126, 0xbfb8aa3b, v126
	v_exp_f32_e32 v126, v126
	v_lshlrev_b64 v[148:149], 12, v[144:145]
	v_mul_f32_e32 v122, 0xbfb8aa3b, v122
	v_exp_f32_e32 v122, v122
	v_add_f32_e32 v126, 1.0, v126
	v_mul_f32_e32 v127, 0xbfb8aa3b, v127
	v_exp_f32_e32 v127, v127
	v_add_f32_e32 v122, 1.0, v122
	v_mul_f32_e32 v123, 0xbfb8aa3b, v123
	v_exp_f32_e32 v123, v123
	v_add_f32_e32 v127, 1.0, v127
	v_mul_f32_e32 v128, 0xbfb8aa3b, v128
	v_exp_f32_e32 v128, v128
	v_add_f32_e32 v123, 1.0, v123
	v_mul_f32_e32 v124, 0xbfb8aa3b, v124
	v_exp_f32_e32 v124, v124
	v_add_f32_e32 v128, 1.0, v128
	v_mul_f32_e32 v118, 0xbfb8aa3b, v118
	v_exp_f32_e32 v118, v118
	v_add_f32_e32 v124, 1.0, v124
	v_mul_f32_e32 v114, 0xbfb8aa3b, v114
	v_exp_f32_e32 v114, v114
	v_add_f32_e32 v118, 1.0, v118
	v_mul_f32_e32 v119, 0xbfb8aa3b, v119
	v_exp_f32_e32 v119, v119
	v_add_f32_e32 v114, 1.0, v114
	v_mul_f32_e32 v115, 0xbfb8aa3b, v115
	v_exp_f32_e32 v115, v115
	v_add_f32_e32 v119, 1.0, v119
	v_mul_f32_e32 v120, 0xbfb8aa3b, v120
	v_exp_f32_e32 v120, v120
	v_add_f32_e32 v115, 1.0, v115
	v_mul_f32_e32 v116, 0xbfb8aa3b, v116
	v_exp_f32_e32 v116, v116
	v_add_f32_e32 v120, 1.0, v120
	v_mul_f32_e32 v110, 0xbfb8aa3b, v110
	v_exp_f32_e32 v110, v110
	v_add_f32_e32 v116, 1.0, v116
	v_mul_f32_e32 v106, 0xbfb8aa3b, v106
	v_exp_f32_e32 v106, v106
	v_add_f32_e32 v110, 1.0, v110
	v_mul_f32_e32 v111, 0xbfb8aa3b, v111
	v_exp_f32_e32 v111, v111
	v_add_f32_e32 v106, 1.0, v106
	v_mul_f32_e32 v107, 0xbfb8aa3b, v107
	v_exp_f32_e32 v107, v107
	v_add_f32_e32 v111, 1.0, v111
	v_mul_f32_e32 v112, 0xbfb8aa3b, v112
	v_exp_f32_e32 v112, v112
	v_add_f32_e32 v107, 1.0, v107
	v_mul_f32_e32 v108, 0xbfb8aa3b, v108
	v_exp_f32_e32 v108, v108
	v_add_f32_e32 v112, 1.0, v112
	v_mul_f32_e32 v102, 0xbfb8aa3b, v102
	v_exp_f32_e32 v102, v102
	v_add_f32_e32 v108, 1.0, v108
	v_mul_f32_e32 v98, 0xbfb8aa3b, v98
	v_exp_f32_e32 v98, v98
	v_add_f32_e32 v102, 1.0, v102
	v_mul_f32_e32 v99, 0xbfb8aa3b, v99
	v_exp_f32_e32 v99, v99
	v_add_f32_e32 v98, 1.0, v98
	v_mul_f32_e32 v100, 0xbfb8aa3b, v100
	v_exp_f32_e32 v100, v100
	v_add_f32_e32 v99, 1.0, v99
	v_mul_f32_e32 v101, 0xbfb8aa3b, v101
	v_exp_f32_e32 v101, v101
	v_add_f32_e32 v100, 1.0, v100
	v_mul_f32_e32 v94, 0xbfb8aa3b, v94
	v_exp_f32_e32 v94, v94
	v_add_f32_e32 v101, 1.0, v101
	v_mul_f32_e32 v90, 0xbfb8aa3b, v90
	v_exp_f32_e32 v90, v90
	v_add_f32_e32 v94, 1.0, v94
	v_mul_f32_e32 v95, 0xbfb8aa3b, v95
	v_exp_f32_e32 v95, v95
	v_add_f32_e32 v90, 1.0, v90
	v_mul_f32_e32 v91, 0xbfb8aa3b, v91
	s_waitcnt vmcnt(0)
; __device__ __forceinline__ unsigned cvt_pk_bf16(float lo, float hi) { unsigned r; asm volatile("v_cvt_pk_bf16_f32 %0, %1, %2" : "=v"(r) : "v"(lo), "v"(hi)); return r; }
; __device__ __forceinline__ float bf_lo(unsigned w) { return __uint_as_float(w << 16); }
; __device__ __forceinline__ float bf_hi(unsigned w) { return __uint_as_float(w & 0xffff0000u); }
;     __device__ __forceinline__ void operator()(const f32x4 (&acc)[2][2][4][2], const Unit& u, int ui, const LAS float* rtab, int wr, int wc, int fr, int fq) const {
;         const int row0 = u.pm * BM + wr * 64 + fr, col0 = u.pn * BM + wc * 32 + 8 * fq;
; #pragma unroll
;         for (int ai = 0; ai < 2; ++ai)
; #pragma unroll
;             for (int m = 0; m < 4; ++m) {
;                 const int row = row0 + ai * HALF + m * 16;
; #pragma unroll
;                 for (int bj = 0; bj < 2; ++bj) {
;                     const int col = col0 + bj * HALF; const u32x4 yv = *(const u32x4*)(Y + (size_t)row * 1024 + col);
;                     const f32x4 a0 = acc[ai][bj][m][0], a1 = acc[ai][bj][m][1]; float o[8];
;                     const float yy[8] = {bf_lo(yv.x), bf_hi(yv.x), bf_lo(yv.y), bf_hi(yv.y), bf_lo(yv.z), bf_hi(yv.z), bf_lo(yv.w), bf_hi(yv.w)};
; #pragma unroll
;                     for (int e = 0; e < 4; ++e) { o[e] = yy[e] / (1.0f + __expf(-a0[e])); o[4 + e] = yy[4 + e] / (1.0f + __expf(-a1[e])); }
;                     u32x4 w; w.x = cvt_pk_bf16(o[0], o[1]); w.y = cvt_pk_bf16(o[2], o[3]); w.z = cvt_pk_bf16(o[4], o[5]); w.w = cvt_pk_bf16(o[6], o[7]);
;                     *(u32x4*)(MG + (size_t)row * DM + 1024 + col) = w;
	v_lshlrev_b32_e32 v174, 16, v170
	v_lshlrev_b32_e32 v162, 16, v173
	v_and_b32_e32 v145, 0xffff0000, v173
	v_div_scale_f32 v173, s[12:13], v126, v126, v174
	v_rcp_f32_e32 v176, v173
	v_lshlrev_b32_e32 v175, 16, v171
	v_and_b32_e32 v153, 0xffff0000, v171
	v_lshlrev_b32_e32 v171, 16, v172
	v_fma_f32 v177, -v173, v176, 1.0
	v_fmac_f32_e32 v176, v177, v176
	v_div_scale_f32 v177, vcc, v174, v126, v174
	v_mul_f32_e32 v178, v177, v176
	v_fma_f32 v179, -v173, v178, v177
	v_rcp_f32_e32 v126, v126
	s_nop 0
	v_mul_f32_e32 v126, v174, v126
	v_div_scale_f32 v173, s[12:13], v122, v122, v171
	v_rcp_f32_e32 v174, v173
	v_and_b32_e32 v170, 0xffff0000, v170
	v_and_b32_e32 v172, 0xffff0000, v172
	v_add_f32_e32 v95, 1.0, v95
	v_fma_f32 v176, -v173, v174, 1.0
	v_fmac_f32_e32 v174, v176, v174
	v_div_scale_f32 v176, vcc, v171, v122, v171
	v_mul_f32_e32 v177, v176, v174
	v_fma_f32 v178, -v173, v177, v176
	v_rcp_f32_e32 v122, v122
	s_nop 0
	v_mul_f32_e32 v122, v171, v122
	v_exp_f32_e32 v91, v91
	v_mul_f32_e32 v96, 0xbfb8aa3b, v96
	v_exp_f32_e32 v96, v96
	v_rcp_f32_e32 v127, v127
	s_nop 0
	v_mul_f32_e32 v127, v170, v127
	v_add_f32_e32 v91, 1.0, v91
	v_add_f32_e32 v96, 1.0, v96
	v_mul_f32_e32 v92, 0xbfb8aa3b, v92
	v_rcp_f32_e32 v123, v123
	s_nop 0
	v_mul_f32_e32 v123, v172, v123
	v_exp_f32_e32 v92, v92
	v_mul_f32_e32 v86, 0xbfb8aa3b, v86
	v_exp_f32_e32 v86, v86
	v_rcp_f32_e32 v128, v128
	s_nop 0
	v_mul_f32_e32 v128, v175, v128
	v_add_f32_e32 v92, 1.0, v92
	v_add_f32_e32 v86, 1.0, v86
	v_mul_f32_e32 v82, 0xbfb8aa3b, v82
	v_rcp_f32_e32 v170, v124
	s_nop 0
	v_mul_f32_e32 v162, v162, v170
	v_mul_f32_e32 v124, 0xbfb8aa3b, v129
	v_exp_f32_e32 v124, v124
	v_exp_f32_e32 v82, v82
	v_mul_f32_e32 v83, 0xbfb8aa3b, v83
	v_exp_f32_e32 v83, v83
	v_add_f32_e32 v124, 1.0, v124
	v_add_f32_e32 v82, 1.0, v82
	v_add_f32_e32 v83, 1.0, v83
	v_mul_f32_e32 v84, 0xbfb8aa3b, v84
	v_rcp_f32_e32 v129, v124
	s_nop 0
	v_mul_f32_e32 v129, v153, v129
	v_mul_f32_e32 v124, 0xbfb8aa3b, v125
	v_exp_f32_e32 v124, v124
	v_exp_f32_e32 v84, v84
	v_mul_f32_e32 v85, 0xbfb8aa3b, v85
	v_exp_f32_e32 v85, v85
	v_add_f32_e32 v124, 1.0, v124
	v_add_f32_e32 v84, 1.0, v84
	v_add_f32_e32 v85, 1.0, v85
	v_mul_f32_e32 v78, 0xbfb8aa3b, v78
	v_rcp_f32_e32 v125, v124
	s_nop 0
	v_mul_f32_e32 v145, v145, v125
	v_cvt_pk_bf16_f32 v124, v126, v127
	v_cvt_pk_bf16_f32 v125, v128, v129
	v_cvt_pk_bf16_f32 v126, v122, v123
	v_lshl_add_u64 v[122:123], s[88:89], 0, v[148:149]
	v_cvt_pk_bf16_f32 v127, v162, v145
	v_lshl_add_u64 v[122:123], v[122:123], 0, v[142:143]
	global_store_dwordx4 v[122:123], v[124:127], off offset:2048
	global_load_dwordx4 v[124:127], v[146:147], off offset:256
	v_exp_f32_e32 v78, v78
	v_mul_f32_e32 v74, 0xbfb8aa3b, v74
	v_exp_f32_e32 v74, v74
	v_mul_f32_e32 v79, 0xbfb8aa3b, v79
	v_add_f32_e32 v78, 1.0, v78
	v_exp_f32_e32 v79, v79
	v_add_f32_e32 v74, 1.0, v74
	v_mul_f32_e32 v75, 0xbfb8aa3b, v75
	v_exp_f32_e32 v75, v75
	v_add_f32_e32 v79, 1.0, v79
	v_mul_f32_e32 v80, 0xbfb8aa3b, v80
	v_exp_f32_e32 v80, v80
	v_add_f32_e32 v75, 1.0, v75
	v_mul_f32_e32 v76, 0xbfb8aa3b, v76
	v_exp_f32_e32 v76, v76
	v_add_f32_e32 v80, 1.0, v80
	v_mul_f32_e32 v70, 0xbfb8aa3b, v70
	v_exp_f32_e32 v70, v70
	v_add_f32_e32 v76, 1.0, v76
	v_mul_f32_e32 v66, 0xbfb8aa3b, v66
	v_exp_f32_e32 v66, v66
	v_add_f32_e32 v70, 1.0, v70
	v_mul_f32_e32 v67, 0xbfb8aa3b, v67
	v_exp_f32_e32 v67, v67
	v_add_f32_e32 v66, 1.0, v66
	v_mul_f32_e32 v68, 0xbfb8aa3b, v68
	v_exp_f32_e32 v68, v68
	v_add_f32_e32 v67, 1.0, v67
	v_mul_f32_e32 v69, 0xbfb8aa3b, v69
	v_exp_f32_e32 v69, v69
	v_add_f32_e32 v68, 1.0, v68
	v_mul_f32_e32 v62, 0xbfb8aa3b, v62
	v_exp_f32_e32 v62, v62
	v_add_f32_e32 v69, 1.0, v69
	v_mul_f32_e32 v58, 0xbfb8aa3b, v58
	v_exp_f32_e32 v58, v58
	v_add_f32_e32 v62, 1.0, v62
	v_mul_f32_e32 v63, 0xbfb8aa3b, v63
	v_exp_f32_e32 v63, v63
	v_add_f32_e32 v58, 1.0, v58
	v_mul_f32_e32 v59, 0xbfb8aa3b, v59
	v_exp_f32_e32 v59, v59
	v_add_f32_e32 v63, 1.0, v63
	v_mul_f32_e32 v64, 0xbfb8aa3b, v64
	v_exp_f32_e32 v64, v64
	v_add_f32_e32 v59, 1.0, v59
	v_mul_f32_e32 v60, 0xbfb8aa3b, v60
	v_exp_f32_e32 v60, v60
	v_add_f32_e32 v64, 1.0, v64
	v_mul_f32_e32 v54, 0xbfb8aa3b, v54
	v_exp_f32_e32 v54, v54
	v_add_f32_e32 v60, 1.0, v60
	v_mul_f32_e32 v50, 0xbfb8aa3b, v50
	v_exp_f32_e32 v50, v50
	v_add_f32_e32 v54, 1.0, v54
	v_mul_f32_e32 v51, 0xbfb8aa3b, v51
	v_exp_f32_e32 v51, v51
	v_add_f32_e32 v50, 1.0, v50
	v_mul_f32_e32 v52, 0xbfb8aa3b, v52
	v_exp_f32_e32 v52, v52
	v_add_f32_e32 v51, 1.0, v51
	v_mul_f32_e32 v53, 0xbfb8aa3b, v53
	v_exp_f32_e32 v53, v53
	v_add_f32_e32 v52, 1.0, v52
	v_mul_f32_e32 v46, 0xbfb8aa3b, v46
	v_exp_f32_e32 v46, v46
	v_add_f32_e32 v53, 1.0, v53
	v_mul_f32_e32 v42, 0xbfb8aa3b, v42
	v_exp_f32_e32 v42, v42
	v_add_f32_e32 v46, 1.0, v46
	v_mul_f32_e32 v47, 0xbfb8aa3b, v47
	v_exp_f32_e32 v47, v47
	v_add_f32_e32 v42, 1.0, v42
	v_mul_f32_e32 v43, 0xbfb8aa3b, v43
	v_exp_f32_e32 v43, v43
	v_add_f32_e32 v47, 1.0, v47
	v_mul_f32_e32 v48, 0xbfb8aa3b, v48
	v_exp_f32_e32 v48, v48
	v_add_f32_e32 v43, 1.0, v43
	s_waitcnt vmcnt(0)
; __device__ __forceinline__ unsigned cvt_pk_bf16(float lo, float hi) { unsigned r; asm volatile("v_cvt_pk_bf16_f32 %0, %1, %2" : "=v"(r) : "v"(lo), "v"(hi)); return r; }
; __device__ __forceinline__ float bf_lo(unsigned w) { return __uint_as_float(w << 16); }
; __device__ __forceinline__ float bf_hi(unsigned w) { return __uint_as_float(w & 0xffff0000u); }
;     __device__ __forceinline__ void operator()(const f32x4 (&acc)[2][2][4][2], const Unit& u, int ui, const LAS float* rtab, int wr, int wc, int fr, int fq) const {
;         const int row0 = u.pm * BM + wr * 64 + fr, col0 = u.pn * BM + wc * 32 + 8 * fq;
; #pragma unroll
;         for (int ai = 0; ai < 2; ++ai)
; #pragma unroll
;             for (int m = 0; m < 4; ++m) {
;                 const int row = row0 + ai * HALF + m * 16;
; #pragma unroll
;                 for (int bj = 0; bj < 2; ++bj) {
;                     const int col = col0 + bj * HALF; const u32x4 yv = *(const u32x4*)(Y + (size_t)row * 1024 + col);
;                     const f32x4 a0 = acc[ai][bj][m][0], a1 = acc[ai][bj][m][1]; float o[8];
;                     const float yy[8] = {bf_lo(yv.x), bf_hi(yv.x), bf_lo(yv.y), bf_hi(yv.y), bf_lo(yv.z), bf_hi(yv.z), bf_lo(yv.w), bf_hi(yv.w)};
; #pragma unroll
;                     for (int e = 0; e < 4; ++e) { o[e] = yy[e] / (1.0f + __expf(-a0[e])); o[4 + e] = yy[4 + e] / (1.0f + __expf(-a1[e])); }
;                     u32x4 w; w.x = cvt_pk_bf16(o[0], o[1]); w.y = cvt_pk_bf16(o[2], o[3]); w.z = cvt_pk_bf16(o[4], o[5]); w.w = cvt_pk_bf16(o[6], o[7]);
;                     *(u32x4*)(MG + (size_t)row * DM + 1024 + col) = w;
	v_lshlrev_b32_e32 v128, 16, v124
	v_and_b32_e32 v129, 0xffff0000, v124
	v_lshlrev_b32_e32 v146, 16, v126
	v_and_b32_e32 v147, 0xffff0000, v126
	v_lshlrev_b32_e32 v126, 16, v127
	v_and_b32_e32 v124, 0xffff0000, v127
	v_div_scale_f32 v127, s[12:13], v118, v118, v128
	v_rcp_f32_e32 v148, v127
	v_lshlrev_b32_e32 v145, 16, v125
	v_and_b32_e32 v125, 0xffff0000, v125
	v_add_f32_e32 v48, 1.0, v48
	v_fma_f32 v149, -v127, v148, 1.0
	v_fmac_f32_e32 v148, v149, v148
	v_div_scale_f32 v149, vcc, v128, v118, v128
	v_mul_f32_e32 v153, v149, v148
	v_fma_f32 v162, -v127, v153, v149
	v_rcp_f32_e32 v118, v118
	s_nop 0
	v_mul_f32_e32 v118, v128, v118
	v_div_scale_f32 v127, s[12:13], v114, v114, v146
	v_rcp_f32_e32 v128, v127
	v_mul_f32_e32 v44, 0xbfb8aa3b, v44
	v_exp_f32_e32 v44, v44
	v_mul_f32_e32 v38, 0xbfb8aa3b, v38
	v_fma_f32 v148, -v127, v128, 1.0
	v_fmac_f32_e32 v128, v148, v128
	v_div_scale_f32 v148, vcc, v146, v114, v146
	v_mul_f32_e32 v149, v148, v128
	v_fma_f32 v153, -v127, v149, v148
	v_rcp_f32_e32 v114, v114
	s_nop 0
	v_mul_f32_e32 v114, v146, v114
	v_add_f32_e32 v44, 1.0, v44
	v_exp_f32_e32 v38, v38
	v_mul_f32_e32 v34, 0xbfb8aa3b, v34
	v_rcp_f32_e32 v119, v119
	s_nop 0
	v_mul_f32_e32 v119, v129, v119
	v_add_f32_e32 v38, 1.0, v38
	v_exp_f32_e32 v34, v34
	v_mul_f32_e32 v35, 0xbfb8aa3b, v35
	v_rcp_f32_e32 v115, v115
	s_nop 0
	v_mul_f32_e32 v115, v147, v115
	v_div_scale_f32 v127, s[12:13], v120, v120, v145
	v_rcp_f32_e32 v128, v127
	v_add_f32_e32 v34, 1.0, v34
	v_exp_f32_e32 v35, v35
	v_mul_f32_e32 v36, 0xbfb8aa3b, v36
	v_fma_f32 v129, -v127, v128, 1.0
	v_fmac_f32_e32 v128, v129, v128
	v_div_scale_f32 v129, vcc, v145, v120, v145
	v_mul_f32_e32 v146, v129, v128
	v_fma_f32 v147, -v127, v146, v129
	v_rcp_f32_e32 v120, v120
	s_nop 0
	v_mul_f32_e32 v120, v145, v120
	v_add_f32_e32 v35, 1.0, v35
	v_exp_f32_e32 v36, v36
	v_mul_f32_e32 v37, 0xbfb8aa3b, v37
	v_rcp_f32_e32 v127, v116
	s_nop 0
	v_mul_f32_e32 v126, v126, v127
	v_mul_f32_e32 v116, 0xbfb8aa3b, v121
	v_exp_f32_e32 v116, v116
	v_add_f32_e32 v36, 1.0, v36
	v_exp_f32_e32 v37, v37
	v_mul_f32_e32 v30, 0xbfb8aa3b, v30
	v_add_f32_e32 v116, 1.0, v116
	v_add_f32_e32 v37, 1.0, v37
	v_exp_f32_e32 v30, v30
	v_mul_f32_e32 v26, 0xbfb8aa3b, v26
	v_rcp_f32_e32 v121, v116
	s_nop 0
	v_mul_f32_e32 v121, v125, v121
	v_mul_f32_e32 v116, 0xbfb8aa3b, v117
	v_exp_f32_e32 v116, v116
	v_add_f32_e32 v30, 1.0, v30
	v_exp_f32_e32 v26, v26
	v_mul_f32_e32 v31, 0xbfb8aa3b, v31
	v_add_f32_e32 v116, 1.0, v116
	v_add_f32_e32 v26, 1.0, v26
	v_exp_f32_e32 v31, v31
	v_mul_f32_e32 v27, 0xbfb8aa3b, v27
	v_rcp_f32_e32 v117, v116
	s_nop 0
	v_mul_f32_e32 v124, v124, v117
	v_cvt_pk_bf16_f32 v116, v118, v119
	v_cvt_pk_bf16_f32 v117, v120, v121
	v_cvt_pk_bf16_f32 v118, v114, v115
	v_or_b32_e32 v114, 16, v144
	v_cvt_pk_bf16_f32 v119, v126, v124
	v_ashrrev_i32_e32 v115, 31, v114
	global_store_dwordx4 v[122:123], v[116:119], off offset:2304
	v_add_f32_e32 v31, 1.0, v31
	v_exp_f32_e32 v27, v27
	v_lshlrev_b64 v[118:119], 11, v[114:115]
	v_lshlrev_b64 v[116:117], 12, v[114:115]
	v_lshl_add_u64 v[114:115], s[86:87], 0, v[118:119]
	v_lshl_add_u64 v[114:115], v[114:115], 0, v[142:143]
	global_load_dwordx4 v[118:121], v[114:115], off
	v_add_f32_e32 v27, 1.0, v27
	v_mul_f32_e32 v32, 0xbfb8aa3b, v32
	v_exp_f32_e32 v32, v32
	v_mul_f32_e32 v28, 0xbfb8aa3b, v28
	v_exp_f32_e32 v28, v28
	v_mul_f32_e32 v22, 0xbfb8aa3b, v22
	v_add_f32_e32 v32, 1.0, v32
	v_exp_f32_e32 v22, v22
	v_add_f32_e32 v28, 1.0, v28
	v_mul_f32_e32 v18, 0xbfb8aa3b, v18
	v_exp_f32_e32 v18, v18
	v_add_f32_e32 v22, 1.0, v22
	v_mul_f32_e32 v19, 0xbfb8aa3b, v19
	v_exp_f32_e32 v19, v19
	v_add_f32_e32 v18, 1.0, v18
	v_mul_f32_e32 v20, 0xbfb8aa3b, v20
	v_exp_f32_e32 v20, v20
	v_add_f32_e32 v19, 1.0, v19
	v_mul_f32_e32 v21, 0xbfb8aa3b, v21
	v_exp_f32_e32 v21, v21
	v_add_f32_e32 v20, 1.0, v20
	v_mul_f32_e32 v14, 0xbfb8aa3b, v14
	v_exp_f32_e32 v14, v14
	v_add_f32_e32 v21, 1.0, v21
	v_mul_f32_e32 v10, 0xbfb8aa3b, v10
	v_exp_f32_e32 v10, v10
	v_add_f32_e32 v14, 1.0, v14
	v_mul_f32_e32 v15, 0xbfb8aa3b, v15
	v_exp_f32_e32 v15, v15
	v_add_f32_e32 v10, 1.0, v10
	v_mul_f32_e32 v11, 0xbfb8aa3b, v11
	v_exp_f32_e32 v11, v11
	v_add_f32_e32 v15, 1.0, v15
	v_mul_f32_e32 v16, 0xbfb8aa3b, v16
	v_exp_f32_e32 v16, v16
	v_add_f32_e32 v11, 1.0, v11
	v_mul_f32_e32 v12, 0xbfb8aa3b, v12
	v_exp_f32_e32 v12, v12
	v_add_f32_e32 v16, 1.0, v16
	v_mul_f32_e32 v6, 0xbfb8aa3b, v6
	v_exp_f32_e32 v6, v6
	v_add_f32_e32 v12, 1.0, v12
	v_mul_f32_e32 v2, 0xbfb8aa3b, v2
	v_exp_f32_e32 v2, v2
	v_add_f32_e32 v6, 1.0, v6
	v_mul_f32_e32 v3, 0xbfb8aa3b, v3
	v_exp_f32_e32 v3, v3
	v_add_f32_e32 v2, 1.0, v2
	v_mul_f32_e32 v4, 0xbfb8aa3b, v4
	v_exp_f32_e32 v4, v4
	v_add_f32_e32 v3, 1.0, v3
	v_mul_f32_e32 v5, 0xbfb8aa3b, v5
	v_exp_f32_e32 v5, v5
	v_add_f32_e32 v4, 1.0, v4
	s_mov_b64 s[36:37], s[46:47]
	s_mov_b64 s[20:21], s[44:45]
	v_add_f32_e32 v5, 1.0, v5
	s_waitcnt vmcnt(0)
; __device__ __forceinline__ unsigned cvt_pk_bf16(float lo, float hi) { unsigned r; asm volatile("v_cvt_pk_bf16_f32 %0, %1, %2" : "=v"(r) : "v"(lo), "v"(hi)); return r; }
; __device__ __forceinline__ float bf_lo(unsigned w) { return __uint_as_float(w << 16); }
; __device__ __forceinline__ float bf_hi(unsigned w) { return __uint_as_float(w & 0xffff0000u); }
;     __device__ __forceinline__ void operator()(const f32x4 (&acc)[2][2][4][2], const Unit& u, int ui, const LAS float* rtab, int wr, int wc, int fr, int fq) const {
;         const int row0 = u.pm * BM + wr * 64 + fr, col0 = u.pn * BM + wc * 32 + 8 * fq;
; #pragma unroll
;         for (int ai = 0; ai < 2; ++ai)
; #pragma unroll
;             for (int m = 0; m < 4; ++m) {
;                 const int row = row0 + ai * HALF + m * 16;
; #pragma unroll
;                 for (int bj = 0; bj < 2; ++bj) {
;                     const int col = col0 + bj * HALF; const u32x4 yv = *(const u32x4*)(Y + (size_t)row * 1024 + col);
;                     const f32x4 a0 = acc[ai][bj][m][0], a1 = acc[ai][bj][m][1]; float o[8];
;                     const float yy[8] = {bf_lo(yv.x), bf_hi(yv.x), bf_lo(yv.y), bf_hi(yv.y), bf_lo(yv.z), bf_hi(yv.z), bf_lo(yv.w), bf_hi(yv.w)};
; #pragma unroll
;                     for (int e = 0; e < 4; ++e) { o[e] = yy[e] / (1.0f + __expf(-a0[e])); o[4 + e] = yy[4 + e] / (1.0f + __expf(-a1[e])); }
;                     u32x4 w; w.x = cvt_pk_bf16(o[0], o[1]); w.y = cvt_pk_bf16(o[2], o[3]); w.z = cvt_pk_bf16(o[4], o[5]); w.w = cvt_pk_bf16(o[6], o[7]);
;                     *(u32x4*)(MG + (size_t)row * DM + 1024 + col) = w;
	v_lshlrev_b32_e32 v122, 16, v118
	v_and_b32_e32 v123, 0xffff0000, v118
	v_lshlrev_b32_e32 v126, 16, v121
	v_and_b32_e32 v118, 0xffff0000, v121
	v_div_scale_f32 v121, s[12:13], v110, v110, v122
	v_rcp_f32_e32 v127, v121
	v_lshlrev_b32_e32 v125, 16, v120
	v_and_b32_e32 v120, 0xffff0000, v120
	v_lshlrev_b32_e32 v124, 16, v119
	v_fma_f32 v128, -v121, v127, 1.0
	v_fmac_f32_e32 v127, v128, v127
	v_div_scale_f32 v128, vcc, v122, v110, v122
	v_mul_f32_e32 v129, v128, v127
	v_fma_f32 v145, -v121, v129, v128
	v_rcp_f32_e32 v110, v110
	s_nop 0
	v_mul_f32_e32 v110, v122, v110
	v_and_b32_e32 v119, 0xffff0000, v119
	v_rcp_f32_e32 v106, v106
	s_nop 0
	v_mul_f32_e32 v106, v125, v106
	s_nop 0
	v_rcp_f32_e32 v111, v111
	s_nop 0
	v_mul_f32_e32 v111, v123, v111
	s_nop 0
	v_rcp_f32_e32 v107, v107
	s_nop 0
	v_mul_f32_e32 v107, v120, v107
	s_nop 0
	v_rcp_f32_e32 v112, v112
	s_nop 0
	v_mul_f32_e32 v112, v124, v112
	s_nop 0
	v_rcp_f32_e32 v120, v108
	s_nop 0
	v_mul_f32_e32 v120, v126, v120
	v_mul_f32_e32 v108, 0xbfb8aa3b, v113
	v_exp_f32_e32 v108, v108
	s_nop 0
	v_add_f32_e32 v108, 1.0, v108
	s_nop 0
	v_rcp_f32_e32 v113, v108
	s_nop 0
	v_mul_f32_e32 v113, v119, v113
	v_mul_f32_e32 v108, 0xbfb8aa3b, v109
	v_exp_f32_e32 v108, v108
	s_nop 0
	v_add_f32_e32 v108, 1.0, v108
	s_nop 0
	v_rcp_f32_e32 v109, v108
	s_nop 0
	v_mul_f32_e32 v118, v118, v109
	v_cvt_pk_bf16_f32 v108, v110, v111
	v_cvt_pk_bf16_f32 v109, v112, v113
	v_cvt_pk_bf16_f32 v110, v106, v107
	v_lshl_add_u64 v[106:107], s[88:89], 0, v[116:117]
	v_cvt_pk_bf16_f32 v111, v120, v118
	v_lshl_add_u64 v[106:107], v[106:107], 0, v[142:143]
	global_store_dwordx4 v[106:107], v[108:111], off offset:2048
	global_load_dwordx4 v[108:111], v[114:115], off offset:256
	s_waitcnt vmcnt(0)
	v_lshlrev_b32_e32 v112, 16, v108
	v_and_b32_e32 v113, 0xffff0000, v108
	v_lshlrev_b32_e32 v116, 16, v111
	v_and_b32_e32 v108, 0xffff0000, v111
	v_lshlrev_b32_e32 v115, 16, v110
	v_and_b32_e32 v110, 0xffff0000, v110
	v_lshlrev_b32_e32 v114, 16, v109
	v_rcp_f32_e32 v102, v102
	s_nop 0
	v_mul_f32_e32 v102, v112, v102
	v_and_b32_e32 v109, 0xffff0000, v109
	v_rcp_f32_e32 v111, v98
	s_nop 0
	v_mul_f32_e32 v111, v115, v111
	v_mul_f32_e32 v98, 0xbfb8aa3b, v103
	v_exp_f32_e32 v98, v98
	s_nop 0
	v_add_f32_e32 v98, 1.0, v98
	s_nop 0
	v_rcp_f32_e32 v98, v98
	s_nop 0
	v_mul_f32_e32 v98, v113, v98
	v_cvt_pk_bf16_f32 v98, v102, v98
	s_nop 0
	v_rcp_f32_e32 v103, v99
	s_nop 0
	v_mul_f32_e32 v103, v110, v103
	v_mul_f32_e32 v99, 0xbfb8aa3b, v104
	v_exp_f32_e32 v99, v99
	s_nop 0
	v_add_f32_e32 v99, 1.0, v99
	s_nop 0
	v_rcp_f32_e32 v99, v99
	s_nop 0
	v_mul_f32_e32 v99, v114, v99
	s_nop 0
	v_rcp_f32_e32 v104, v100
	s_nop 0
	v_mul_f32_e32 v104, v116, v104
	v_mul_f32_e32 v100, 0xbfb8aa3b, v105
	v_exp_f32_e32 v100, v100
	s_nop 0
	v_add_f32_e32 v100, 1.0, v100
	s_nop 0
	v_rcp_f32_e32 v100, v100
	s_nop 0
	v_mul_f32_e32 v100, v109, v100
	v_cvt_pk_bf16_f32 v99, v99, v100
	v_cvt_pk_bf16_f32 v100, v111, v103
	s_nop 0
	v_rcp_f32_e32 v101, v101
	s_nop 0
	v_mul_f32_e32 v101, v108, v101
	v_cvt_pk_bf16_f32 v101, v104, v101
	global_store_dwordx4 v[106:107], v[98:101], off offset:2304
	s_nop 1
	v_or_b32_e32 v98, 32, v144
	v_ashrrev_i32_e32 v99, 31, v98
	v_lshlrev_b64 v[102:103], 11, v[98:99]
	v_lshlrev_b64 v[100:101], 12, v[98:99]
	v_lshl_add_u64 v[98:99], s[86:87], 0, v[102:103]
	v_lshl_add_u64 v[98:99], v[98:99], 0, v[142:143]
	global_load_dwordx4 v[102:105], v[98:99], off
	s_waitcnt vmcnt(0)
	v_lshlrev_b32_e32 v106, 16, v102
	v_and_b32_e32 v107, 0xffff0000, v102
	v_lshlrev_b32_e32 v110, 16, v105
	v_and_b32_e32 v102, 0xffff0000, v105
	v_lshlrev_b32_e32 v109, 16, v104
	v_and_b32_e32 v104, 0xffff0000, v104
	v_lshlrev_b32_e32 v108, 16, v103
	v_rcp_f32_e32 v94, v94
	s_nop 0
	v_mul_f32_e32 v94, v106, v94
	v_and_b32_e32 v103, 0xffff0000, v103
	v_rcp_f32_e32 v90, v90
	s_nop 0
	v_mul_f32_e32 v90, v109, v90
	s_nop 0
	v_rcp_f32_e32 v95, v95
	s_nop 0
	v_mul_f32_e32 v95, v107, v95
	s_nop 0
	v_rcp_f32_e32 v91, v91
	s_nop 0
	v_mul_f32_e32 v91, v104, v91
	s_nop 0
	v_rcp_f32_e32 v96, v96
	s_nop 0
	v_mul_f32_e32 v96, v108, v96
	s_nop 0
	v_rcp_f32_e32 v104, v92
	s_nop 0
	v_mul_f32_e32 v104, v110, v104
	v_mul_f32_e32 v92, 0xbfb8aa3b, v97
	v_exp_f32_e32 v92, v92
	s_nop 0
	v_add_f32_e32 v92, 1.0, v92
	s_nop 0
	v_rcp_f32_e32 v97, v92
	s_nop 0
	v_mul_f32_e32 v97, v103, v97
	v_mul_f32_e32 v92, 0xbfb8aa3b, v93
	v_exp_f32_e32 v92, v92
	s_nop 0
	v_add_f32_e32 v92, 1.0, v92
	s_nop 0
	v_rcp_f32_e32 v93, v92
	s_nop 0
	v_mul_f32_e32 v102, v102, v93
	v_cvt_pk_bf16_f32 v92, v94, v95
	v_cvt_pk_bf16_f32 v93, v96, v97
	v_cvt_pk_bf16_f32 v94, v90, v91
	v_lshl_add_u64 v[90:91], s[88:89], 0, v[100:101]
	v_cvt_pk_bf16_f32 v95, v104, v102
	v_lshl_add_u64 v[90:91], v[90:91], 0, v[142:143]
	global_store_dwordx4 v[90:91], v[92:95], off offset:2048
	global_load_dwordx4 v[92:95], v[98:99], off offset:256
	s_waitcnt vmcnt(0)
; __device__ __forceinline__ unsigned cvt_pk_bf16(float lo, float hi) { unsigned r; asm volatile("v_cvt_pk_bf16_f32 %0, %1, %2" : "=v"(r) : "v"(lo), "v"(hi)); return r; }
; __device__ __forceinline__ float bf_lo(unsigned w) { return __uint_as_float(w << 16); }
; __device__ __forceinline__ float bf_hi(unsigned w) { return __uint_as_float(w & 0xffff0000u); }
;     __device__ __forceinline__ void operator()(const f32x4 (&acc)[2][2][4][2], const Unit& u, int ui, const LAS float* rtab, int wr, int wc, int fr, int fq) const {
;         const int row0 = u.pm * BM + wr * 64 + fr, col0 = u.pn * BM + wc * 32 + 8 * fq;
; #pragma unroll
;         for (int ai = 0; ai < 2; ++ai)
; #pragma unroll
;             for (int m = 0; m < 4; ++m) {
;                 const int row = row0 + ai * HALF + m * 16;
; #pragma unroll
;                 for (int bj = 0; bj < 2; ++bj) {
;                     const int col = col0 + bj * HALF; const u32x4 yv = *(const u32x4*)(Y + (size_t)row * 1024 + col);
;                     const f32x4 a0 = acc[ai][bj][m][0], a1 = acc[ai][bj][m][1]; float o[8];
;                     const float yy[8] = {bf_lo(yv.x), bf_hi(yv.x), bf_lo(yv.y), bf_hi(yv.y), bf_lo(yv.z), bf_hi(yv.z), bf_lo(yv.w), bf_hi(yv.w)};
; #pragma unroll
;                     for (int e = 0; e < 4; ++e) { o[e] = yy[e] / (1.0f + __expf(-a0[e])); o[4 + e] = yy[4 + e] / (1.0f + __expf(-a1[e])); }
;                     u32x4 w; w.x = cvt_pk_bf16(o[0], o[1]); w.y = cvt_pk_bf16(o[2], o[3]); w.z = cvt_pk_bf16(o[4], o[5]); w.w = cvt_pk_bf16(o[6], o[7]);
;                     *(u32x4*)(MG + (size_t)row * DM + 1024 + col) = w;
	v_lshlrev_b32_e32 v96, 16, v92
	v_and_b32_e32 v97, 0xffff0000, v92
	v_lshlrev_b32_e32 v100, 16, v95
	v_and_b32_e32 v92, 0xffff0000, v95
	v_lshlrev_b32_e32 v99, 16, v94
	v_and_b32_e32 v94, 0xffff0000, v94
	v_lshlrev_b32_e32 v98, 16, v93
	v_rcp_f32_e32 v86, v86
	s_nop 0
	v_mul_f32_e32 v86, v96, v86
	v_and_b32_e32 v93, 0xffff0000, v93
	v_rcp_f32_e32 v95, v82
	s_nop 0
	v_mul_f32_e32 v95, v99, v95
	v_mul_f32_e32 v82, 0xbfb8aa3b, v87
	v_exp_f32_e32 v82, v82
	s_nop 0
	v_add_f32_e32 v82, 1.0, v82
	s_nop 0
	v_rcp_f32_e32 v82, v82
	s_nop 0
	v_mul_f32_e32 v82, v97, v82
	v_cvt_pk_bf16_f32 v82, v86, v82
	s_nop 0
	v_rcp_f32_e32 v87, v83
	s_nop 0
	v_mul_f32_e32 v87, v94, v87
	v_mul_f32_e32 v83, 0xbfb8aa3b, v88
	v_exp_f32_e32 v83, v83
	s_nop 0
	v_add_f32_e32 v83, 1.0, v83
	s_nop 0
	v_rcp_f32_e32 v83, v83
	s_nop 0
	v_mul_f32_e32 v83, v98, v83
	s_nop 0
	v_rcp_f32_e32 v88, v84
	s_nop 0
	v_mul_f32_e32 v88, v100, v88
	v_mul_f32_e32 v84, 0xbfb8aa3b, v89
	v_exp_f32_e32 v84, v84
	s_nop 0
	v_add_f32_e32 v84, 1.0, v84
	s_nop 0
	v_rcp_f32_e32 v84, v84
	s_nop 0
	v_mul_f32_e32 v84, v93, v84
	v_cvt_pk_bf16_f32 v83, v83, v84
	v_cvt_pk_bf16_f32 v84, v95, v87
	s_nop 0
	v_rcp_f32_e32 v85, v85
	s_nop 0
	v_mul_f32_e32 v85, v92, v85
	v_cvt_pk_bf16_f32 v85, v88, v85
	global_store_dwordx4 v[90:91], v[82:85], off offset:2304
	s_nop 1
	v_or_b32_e32 v82, 48, v144
	v_ashrrev_i32_e32 v83, 31, v82
	v_lshlrev_b64 v[86:87], 11, v[82:83]
	v_lshlrev_b64 v[84:85], 12, v[82:83]
	v_lshl_add_u64 v[82:83], s[86:87], 0, v[86:87]
	v_lshl_add_u64 v[82:83], v[82:83], 0, v[142:143]
	global_load_dwordx4 v[86:89], v[82:83], off
	s_waitcnt vmcnt(0)
	v_lshlrev_b32_e32 v90, 16, v86
	v_and_b32_e32 v91, 0xffff0000, v86
	v_lshlrev_b32_e32 v94, 16, v89
	v_and_b32_e32 v86, 0xffff0000, v89
	v_lshlrev_b32_e32 v93, 16, v88
	v_and_b32_e32 v88, 0xffff0000, v88
	v_lshlrev_b32_e32 v92, 16, v87
	v_rcp_f32_e32 v78, v78
	s_nop 0
	v_mul_f32_e32 v78, v90, v78
	v_and_b32_e32 v87, 0xffff0000, v87
	v_rcp_f32_e32 v74, v74
	s_nop 0
	v_mul_f32_e32 v74, v93, v74
	s_nop 0
	v_rcp_f32_e32 v79, v79
	s_nop 0
	v_mul_f32_e32 v79, v91, v79
	s_nop 0
	v_rcp_f32_e32 v75, v75
	s_nop 0
	v_mul_f32_e32 v75, v88, v75
	s_nop 0
	v_rcp_f32_e32 v80, v80
	s_nop 0
	v_mul_f32_e32 v80, v92, v80
	s_nop 0
	v_rcp_f32_e32 v88, v76
	s_nop 0
	v_mul_f32_e32 v88, v94, v88
	v_mul_f32_e32 v76, 0xbfb8aa3b, v81
	v_exp_f32_e32 v76, v76
	s_nop 0
	v_add_f32_e32 v76, 1.0, v76
	s_nop 0
	v_rcp_f32_e32 v81, v76
	s_nop 0
	v_mul_f32_e32 v81, v87, v81
	v_mul_f32_e32 v76, 0xbfb8aa3b, v77
	v_exp_f32_e32 v76, v76
	s_nop 0
	v_add_f32_e32 v76, 1.0, v76
	s_nop 0
	v_rcp_f32_e32 v77, v76
	s_nop 0
	v_mul_f32_e32 v86, v86, v77
	v_cvt_pk_bf16_f32 v76, v78, v79
	v_cvt_pk_bf16_f32 v77, v80, v81
	v_cvt_pk_bf16_f32 v78, v74, v75
	v_lshl_add_u64 v[74:75], s[88:89], 0, v[84:85]
	v_cvt_pk_bf16_f32 v79, v88, v86
	v_lshl_add_u64 v[74:75], v[74:75], 0, v[142:143]
	global_store_dwordx4 v[74:75], v[76:79], off offset:2048
	global_load_dwordx4 v[76:79], v[82:83], off offset:256
	s_waitcnt vmcnt(0)
	v_lshlrev_b32_e32 v80, 16, v76
	v_and_b32_e32 v81, 0xffff0000, v76
	v_lshlrev_b32_e32 v84, 16, v79
	v_and_b32_e32 v76, 0xffff0000, v79
	v_lshlrev_b32_e32 v83, 16, v78
	v_and_b32_e32 v78, 0xffff0000, v78
	v_lshlrev_b32_e32 v82, 16, v77
	v_rcp_f32_e32 v70, v70
	s_nop 0
	v_mul_f32_e32 v70, v80, v70
	v_and_b32_e32 v77, 0xffff0000, v77
	v_rcp_f32_e32 v79, v66
	s_nop 0
	v_mul_f32_e32 v79, v83, v79
	v_mul_f32_e32 v66, 0xbfb8aa3b, v71
	v_exp_f32_e32 v66, v66
	s_nop 0
	v_add_f32_e32 v66, 1.0, v66
	s_nop 0
	v_rcp_f32_e32 v66, v66
	s_nop 0
	v_mul_f32_e32 v66, v81, v66
	v_cvt_pk_bf16_f32 v66, v70, v66
	s_nop 0
	v_rcp_f32_e32 v71, v67
	s_nop 0
	v_mul_f32_e32 v71, v78, v71
	v_mul_f32_e32 v67, 0xbfb8aa3b, v72
	v_exp_f32_e32 v67, v67
	s_nop 0
	v_add_f32_e32 v67, 1.0, v67
	s_nop 0
	v_rcp_f32_e32 v67, v67
	s_nop 0
	v_mul_f32_e32 v67, v82, v67
	s_nop 0
	v_rcp_f32_e32 v72, v68
	s_nop 0
	v_mul_f32_e32 v72, v84, v72
	v_mul_f32_e32 v68, 0xbfb8aa3b, v73
	v_exp_f32_e32 v68, v68
	s_nop 0
	v_add_f32_e32 v68, 1.0, v68
	s_nop 0
	v_rcp_f32_e32 v68, v68
	s_nop 0
	v_mul_f32_e32 v68, v77, v68
	v_cvt_pk_bf16_f32 v67, v67, v68
	v_cvt_pk_bf16_f32 v68, v79, v71
	s_nop 0
	v_rcp_f32_e32 v69, v69
	s_nop 0
	v_mul_f32_e32 v69, v76, v69
	v_cvt_pk_bf16_f32 v69, v72, v69
	global_store_dwordx4 v[74:75], v[66:69], off offset:2304
	s_nop 1
	v_add_u32_e32 v66, 0x80, v144
	v_ashrrev_i32_e32 v67, 31, v66
	v_lshlrev_b64 v[70:71], 11, v[66:67]
	v_lshlrev_b64 v[68:69], 12, v[66:67]
	v_lshl_add_u64 v[66:67], s[86:87], 0, v[70:71]
	v_lshl_add_u64 v[66:67], v[66:67], 0, v[142:143]
	global_load_dwordx4 v[70:73], v[66:67], off
	s_waitcnt vmcnt(0)
	v_lshlrev_b32_e32 v74, 16, v70
	v_and_b32_e32 v75, 0xffff0000, v70
	v_lshlrev_b32_e32 v78, 16, v73
	v_and_b32_e32 v70, 0xffff0000, v73
	v_lshlrev_b32_e32 v77, 16, v72
	v_and_b32_e32 v72, 0xffff0000, v72
	v_lshlrev_b32_e32 v76, 16, v71
	v_rcp_f32_e32 v62, v62
	s_nop 0
	v_mul_f32_e32 v62, v74, v62
	v_and_b32_e32 v71, 0xffff0000, v71
	v_rcp_f32_e32 v58, v58
	s_nop 0
	v_mul_f32_e32 v58, v77, v58
	s_nop 0
	v_rcp_f32_e32 v63, v63
	s_nop 0
	v_mul_f32_e32 v63, v75, v63
	s_nop 0
	v_rcp_f32_e32 v59, v59
	s_nop 0
	v_mul_f32_e32 v59, v72, v59
	s_nop 0
	v_rcp_f32_e32 v64, v64
	s_nop 0
	v_mul_f32_e32 v64, v76, v64
	s_nop 0
	v_rcp_f32_e32 v72, v60
	s_nop 0
	v_mul_f32_e32 v72, v78, v72
	v_mul_f32_e32 v60, 0xbfb8aa3b, v65
	v_exp_f32_e32 v60, v60
	s_nop 0
	v_add_f32_e32 v60, 1.0, v60
	s_nop 0
	v_rcp_f32_e32 v65, v60
	s_nop 0
	v_mul_f32_e32 v65, v71, v65
	v_mul_f32_e32 v60, 0xbfb8aa3b, v61
	v_exp_f32_e32 v60, v60
	s_nop 0
	v_add_f32_e32 v60, 1.0, v60
	s_nop 0
	v_rcp_f32_e32 v61, v60
	s_nop 0
	v_mul_f32_e32 v70, v70, v61
	v_cvt_pk_bf16_f32 v60, v62, v63
	v_cvt_pk_bf16_f32 v61, v64, v65
	v_cvt_pk_bf16_f32 v62, v58, v59
	v_lshl_add_u64 v[58:59], s[88:89], 0, v[68:69]
	v_cvt_pk_bf16_f32 v63, v72, v70
	v_lshl_add_u64 v[58:59], v[58:59], 0, v[142:143]
	global_store_dwordx4 v[58:59], v[60:63], off offset:2048
	global_load_dwordx4 v[60:63], v[66:67], off offset:256
	s_waitcnt vmcnt(0)
; __device__ __forceinline__ unsigned cvt_pk_bf16(float lo, float hi) { unsigned r; asm volatile("v_cvt_pk_bf16_f32 %0, %1, %2" : "=v"(r) : "v"(lo), "v"(hi)); return r; }
; __device__ __forceinline__ float bf_lo(unsigned w) { return __uint_as_float(w << 16); }
; __device__ __forceinline__ float bf_hi(unsigned w) { return __uint_as_float(w & 0xffff0000u); }
;     __device__ __forceinline__ void operator()(const f32x4 (&acc)[2][2][4][2], const Unit& u, int ui, const LAS float* rtab, int wr, int wc, int fr, int fq) const {
;         const int row0 = u.pm * BM + wr * 64 + fr, col0 = u.pn * BM + wc * 32 + 8 * fq;
; #pragma unroll
;         for (int ai = 0; ai < 2; ++ai)
; #pragma unroll
;             for (int m = 0; m < 4; ++m) {
;                 const int row = row0 + ai * HALF + m * 16;
; #pragma unroll
;                 for (int bj = 0; bj < 2; ++bj) {
;                     const int col = col0 + bj * HALF; const u32x4 yv = *(const u32x4*)(Y + (size_t)row * 1024 + col);
;                     const f32x4 a0 = acc[ai][bj][m][0], a1 = acc[ai][bj][m][1]; float o[8];
;                     const float yy[8] = {bf_lo(yv.x), bf_hi(yv.x), bf_lo(yv.y), bf_hi(yv.y), bf_lo(yv.z), bf_hi(yv.z), bf_lo(yv.w), bf_hi(yv.w)};
; #pragma unroll
;                     for (int e = 0; e < 4; ++e) { o[e] = yy[e] / (1.0f + __expf(-a0[e])); o[4 + e] = yy[4 + e] / (1.0f + __expf(-a1[e])); }
;                     u32x4 w; w.x = cvt_pk_bf16(o[0], o[1]); w.y = cvt_pk_bf16(o[2], o[3]); w.z = cvt_pk_bf16(o[4], o[5]); w.w = cvt_pk_bf16(o[6], o[7]);
;                     *(u32x4*)(MG + (size_t)row * DM + 1024 + col) = w;
	v_lshlrev_b32_e32 v64, 16, v60
	v_and_b32_e32 v65, 0xffff0000, v60
	v_lshlrev_b32_e32 v68, 16, v63
	v_and_b32_e32 v60, 0xffff0000, v63
	v_lshlrev_b32_e32 v67, 16, v62
	v_and_b32_e32 v62, 0xffff0000, v62
	v_lshlrev_b32_e32 v66, 16, v61
	v_rcp_f32_e32 v54, v54
	s_nop 0
	v_mul_f32_e32 v54, v64, v54
	v_and_b32_e32 v61, 0xffff0000, v61
	v_rcp_f32_e32 v63, v50
	s_nop 0
	v_mul_f32_e32 v63, v67, v63
	v_mul_f32_e32 v50, 0xbfb8aa3b, v55
	v_exp_f32_e32 v50, v50
	s_nop 0
	v_add_f32_e32 v50, 1.0, v50
	s_nop 0
	v_rcp_f32_e32 v50, v50
	s_nop 0
	v_mul_f32_e32 v50, v65, v50
	v_cvt_pk_bf16_f32 v50, v54, v50
	s_nop 0
	v_rcp_f32_e32 v55, v51
	s_nop 0
	v_mul_f32_e32 v55, v62, v55
	v_mul_f32_e32 v51, 0xbfb8aa3b, v56
	v_exp_f32_e32 v51, v51
	s_nop 0
	v_add_f32_e32 v51, 1.0, v51
	s_nop 0
	v_rcp_f32_e32 v51, v51
	s_nop 0
	v_mul_f32_e32 v51, v66, v51
	s_nop 0
	v_rcp_f32_e32 v56, v52
	s_nop 0
	v_mul_f32_e32 v56, v68, v56
	v_mul_f32_e32 v52, 0xbfb8aa3b, v57
	v_exp_f32_e32 v52, v52
	s_nop 0
	v_add_f32_e32 v52, 1.0, v52
	s_nop 0
	v_rcp_f32_e32 v52, v52
	s_nop 0
	v_mul_f32_e32 v52, v61, v52
	v_cvt_pk_bf16_f32 v51, v51, v52
	v_cvt_pk_bf16_f32 v52, v63, v55
	s_nop 0
	v_rcp_f32_e32 v53, v53
	s_nop 0
	v_mul_f32_e32 v53, v60, v53
	v_cvt_pk_bf16_f32 v53, v56, v53
	global_store_dwordx4 v[58:59], v[50:53], off offset:2304
	s_nop 1
	v_add_u32_e32 v50, 0x90, v144
	v_ashrrev_i32_e32 v51, 31, v50
	v_lshlrev_b64 v[54:55], 11, v[50:51]
	v_lshlrev_b64 v[52:53], 12, v[50:51]
	v_lshl_add_u64 v[50:51], s[86:87], 0, v[54:55]
	v_lshl_add_u64 v[50:51], v[50:51], 0, v[142:143]
	global_load_dwordx4 v[54:57], v[50:51], off
	s_waitcnt vmcnt(0)
	v_lshlrev_b32_e32 v58, 16, v54
	v_and_b32_e32 v59, 0xffff0000, v54
	v_lshlrev_b32_e32 v62, 16, v57
	v_and_b32_e32 v54, 0xffff0000, v57
	v_lshlrev_b32_e32 v61, 16, v56
	v_and_b32_e32 v56, 0xffff0000, v56
	v_lshlrev_b32_e32 v60, 16, v55
	v_rcp_f32_e32 v46, v46
	s_nop 0
	v_mul_f32_e32 v46, v58, v46
	v_and_b32_e32 v55, 0xffff0000, v55
	v_rcp_f32_e32 v42, v42
	s_nop 0
	v_mul_f32_e32 v42, v61, v42
	s_nop 0
	v_rcp_f32_e32 v47, v47
	s_nop 0
	v_mul_f32_e32 v47, v59, v47
	s_nop 0
	v_rcp_f32_e32 v43, v43
	s_nop 0
	v_mul_f32_e32 v43, v56, v43
	s_nop 0
	v_rcp_f32_e32 v48, v48
	s_nop 0
	v_mul_f32_e32 v48, v60, v48
	s_nop 0
	v_rcp_f32_e32 v56, v44
	s_nop 0
	v_mul_f32_e32 v56, v62, v56
	v_mul_f32_e32 v44, 0xbfb8aa3b, v49
	v_exp_f32_e32 v44, v44
	s_nop 0
	v_add_f32_e32 v44, 1.0, v44
	s_nop 0
	v_rcp_f32_e32 v49, v44
	s_nop 0
	v_mul_f32_e32 v49, v55, v49
	v_mul_f32_e32 v44, 0xbfb8aa3b, v45
	v_exp_f32_e32 v44, v44
	s_nop 0
	v_add_f32_e32 v44, 1.0, v44
	s_nop 0
	v_rcp_f32_e32 v45, v44
	s_nop 0
	v_mul_f32_e32 v54, v54, v45
	v_cvt_pk_bf16_f32 v44, v46, v47
	v_cvt_pk_bf16_f32 v45, v48, v49
	v_cvt_pk_bf16_f32 v46, v42, v43
	v_lshl_add_u64 v[42:43], s[88:89], 0, v[52:53]
	v_cvt_pk_bf16_f32 v47, v56, v54
	v_lshl_add_u64 v[42:43], v[42:43], 0, v[142:143]
	global_store_dwordx4 v[42:43], v[44:47], off offset:2048
	global_load_dwordx4 v[44:47], v[50:51], off offset:256
	s_waitcnt vmcnt(0)
	v_lshlrev_b32_e32 v48, 16, v44
	v_and_b32_e32 v49, 0xffff0000, v44
	v_lshlrev_b32_e32 v52, 16, v47
	v_and_b32_e32 v44, 0xffff0000, v47
	v_lshlrev_b32_e32 v51, 16, v46
	v_and_b32_e32 v46, 0xffff0000, v46
	v_lshlrev_b32_e32 v50, 16, v45
	v_rcp_f32_e32 v38, v38
	s_nop 0
	v_mul_f32_e32 v38, v48, v38
	v_and_b32_e32 v45, 0xffff0000, v45
	v_rcp_f32_e32 v47, v34
	s_nop 0
	v_mul_f32_e32 v47, v51, v47
	v_mul_f32_e32 v34, 0xbfb8aa3b, v39
	v_exp_f32_e32 v34, v34
	s_nop 0
	v_add_f32_e32 v34, 1.0, v34
	s_nop 0
	v_rcp_f32_e32 v34, v34
	s_nop 0
	v_mul_f32_e32 v34, v49, v34
	v_cvt_pk_bf16_f32 v34, v38, v34
	s_nop 0
	v_rcp_f32_e32 v39, v35
	s_nop 0
	v_mul_f32_e32 v39, v46, v39
	v_mul_f32_e32 v35, 0xbfb8aa3b, v40
	v_exp_f32_e32 v35, v35
	s_nop 0
	v_add_f32_e32 v35, 1.0, v35
	s_nop 0
	v_rcp_f32_e32 v35, v35
	s_nop 0
	v_mul_f32_e32 v35, v50, v35
	s_nop 0
	v_rcp_f32_e32 v40, v36
	s_nop 0
	v_mul_f32_e32 v40, v52, v40
	v_mul_f32_e32 v36, 0xbfb8aa3b, v41
	v_exp_f32_e32 v36, v36
	s_nop 0
	v_add_f32_e32 v36, 1.0, v36
	s_nop 0
	v_rcp_f32_e32 v36, v36
	s_nop 0
	v_mul_f32_e32 v36, v45, v36
	v_cvt_pk_bf16_f32 v35, v35, v36
	v_cvt_pk_bf16_f32 v36, v47, v39
	s_nop 0
	v_rcp_f32_e32 v37, v37
	s_nop 0
	v_mul_f32_e32 v37, v44, v37
	v_cvt_pk_bf16_f32 v37, v40, v37
	global_store_dwordx4 v[42:43], v[34:37], off offset:2304
	s_nop 1
	v_add_u32_e32 v34, 0xa0, v144
	v_ashrrev_i32_e32 v35, 31, v34
	v_lshlrev_b64 v[38:39], 11, v[34:35]
	v_lshlrev_b64 v[36:37], 12, v[34:35]
	v_lshl_add_u64 v[34:35], s[86:87], 0, v[38:39]
	v_lshl_add_u64 v[34:35], v[34:35], 0, v[142:143]
	global_load_dwordx4 v[38:41], v[34:35], off
	s_waitcnt vmcnt(0)
; __device__ __forceinline__ unsigned cvt_pk_bf16(float lo, float hi) { unsigned r; asm volatile("v_cvt_pk_bf16_f32 %0, %1, %2" : "=v"(r) : "v"(lo), "v"(hi)); return r; }
; __device__ __forceinline__ float bf_lo(unsigned w) { return __uint_as_float(w << 16); }
; __device__ __forceinline__ float bf_hi(unsigned w) { return __uint_as_float(w & 0xffff0000u); }
;     __device__ __forceinline__ void operator()(const f32x4 (&acc)[2][2][4][2], const Unit& u, int ui, const LAS float* rtab, int wr, int wc, int fr, int fq) const {
;         const int row0 = u.pm * BM + wr * 64 + fr, col0 = u.pn * BM + wc * 32 + 8 * fq;
; #pragma unroll
;         for (int ai = 0; ai < 2; ++ai)
; #pragma unroll
;             for (int m = 0; m < 4; ++m) {
;                 const int row = row0 + ai * HALF + m * 16;
; #pragma unroll
;                 for (int bj = 0; bj < 2; ++bj) {
;                     const int col = col0 + bj * HALF; const u32x4 yv = *(const u32x4*)(Y + (size_t)row * 1024 + col);
;                     const f32x4 a0 = acc[ai][bj][m][0], a1 = acc[ai][bj][m][1]; float o[8];
;                     const float yy[8] = {bf_lo(yv.x), bf_hi(yv.x), bf_lo(yv.y), bf_hi(yv.y), bf_lo(yv.z), bf_hi(yv.z), bf_lo(yv.w), bf_hi(yv.w)};
; #pragma unroll
;                     for (int e = 0; e < 4; ++e) { o[e] = yy[e] / (1.0f + __expf(-a0[e])); o[4 + e] = yy[4 + e] / (1.0f + __expf(-a1[e])); }
;                     u32x4 w; w.x = cvt_pk_bf16(o[0], o[1]); w.y = cvt_pk_bf16(o[2], o[3]); w.z = cvt_pk_bf16(o[4], o[5]); w.w = cvt_pk_bf16(o[6], o[7]);
;                     *(u32x4*)(MG + (size_t)row * DM + 1024 + col) = w;
;                 }
;             }
	v_lshlrev_b32_e32 v42, 16, v38
	v_and_b32_e32 v43, 0xffff0000, v38
	v_lshlrev_b32_e32 v46, 16, v41
	v_and_b32_e32 v38, 0xffff0000, v41
	v_lshlrev_b32_e32 v45, 16, v40
	v_and_b32_e32 v40, 0xffff0000, v40
	v_lshlrev_b32_e32 v44, 16, v39
	v_rcp_f32_e32 v30, v30
	s_nop 0
	v_mul_f32_e32 v30, v42, v30
	v_and_b32_e32 v39, 0xffff0000, v39
	v_rcp_f32_e32 v26, v26
	s_nop 0
	v_mul_f32_e32 v26, v45, v26
	s_nop 0
	v_rcp_f32_e32 v31, v31
	s_nop 0
	v_mul_f32_e32 v31, v43, v31
	s_nop 0
	v_rcp_f32_e32 v27, v27
	s_nop 0
	v_mul_f32_e32 v27, v40, v27
	s_nop 0
	v_rcp_f32_e32 v32, v32
	s_nop 0
	v_mul_f32_e32 v32, v44, v32
	s_nop 0
	v_rcp_f32_e32 v40, v28
	s_nop 0
	v_mul_f32_e32 v40, v46, v40
	v_mul_f32_e32 v28, 0xbfb8aa3b, v33
	v_exp_f32_e32 v28, v28
	s_nop 0
	v_add_f32_e32 v28, 1.0, v28
	s_nop 0
	v_rcp_f32_e32 v33, v28
	s_nop 0
	v_mul_f32_e32 v33, v39, v33
	v_mul_f32_e32 v28, 0xbfb8aa3b, v29
	v_exp_f32_e32 v28, v28
	s_nop 0
	v_add_f32_e32 v28, 1.0, v28
	s_nop 0
	v_rcp_f32_e32 v29, v28
	s_nop 0
	v_mul_f32_e32 v38, v38, v29
	v_cvt_pk_bf16_f32 v28, v30, v31
	v_cvt_pk_bf16_f32 v29, v32, v33
	v_cvt_pk_bf16_f32 v30, v26, v27
	v_lshl_add_u64 v[26:27], s[88:89], 0, v[36:37]
	v_cvt_pk_bf16_f32 v31, v40, v38
	v_lshl_add_u64 v[26:27], v[26:27], 0, v[142:143]
	global_store_dwordx4 v[26:27], v[28:31], off offset:2048
	global_load_dwordx4 v[28:31], v[34:35], off offset:256
	s_waitcnt vmcnt(0)
	v_lshlrev_b32_e32 v32, 16, v28
	v_and_b32_e32 v33, 0xffff0000, v28
	v_lshlrev_b32_e32 v36, 16, v31
	v_and_b32_e32 v28, 0xffff0000, v31
	v_lshlrev_b32_e32 v35, 16, v30
	v_and_b32_e32 v30, 0xffff0000, v30
	v_lshlrev_b32_e32 v34, 16, v29
	v_rcp_f32_e32 v22, v22
	s_nop 0
	v_mul_f32_e32 v22, v32, v22
	v_and_b32_e32 v29, 0xffff0000, v29
	v_rcp_f32_e32 v31, v18
	s_nop 0
	v_mul_f32_e32 v31, v35, v31
	v_mul_f32_e32 v18, 0xbfb8aa3b, v23
	v_exp_f32_e32 v18, v18
	s_nop 0
	v_add_f32_e32 v18, 1.0, v18
	s_nop 0
	v_rcp_f32_e32 v18, v18
	s_nop 0
	v_mul_f32_e32 v18, v33, v18
	v_cvt_pk_bf16_f32 v18, v22, v18
	s_nop 0
	v_rcp_f32_e32 v23, v19
	s_nop 0
	v_mul_f32_e32 v23, v30, v23
	v_mul_f32_e32 v19, 0xbfb8aa3b, v24
	v_exp_f32_e32 v19, v19
	s_nop 0
	v_add_f32_e32 v19, 1.0, v19
	s_nop 0
	v_rcp_f32_e32 v19, v19
	s_nop 0
	v_mul_f32_e32 v19, v34, v19
	s_nop 0
	v_rcp_f32_e32 v24, v20
	s_nop 0
	v_mul_f32_e32 v24, v36, v24
	v_mul_f32_e32 v20, 0xbfb8aa3b, v25
	v_exp_f32_e32 v20, v20
	s_nop 0
	v_add_f32_e32 v20, 1.0, v20
	s_nop 0
	v_rcp_f32_e32 v20, v20
	s_nop 0
	v_mul_f32_e32 v20, v29, v20
	v_cvt_pk_bf16_f32 v19, v19, v20
	v_cvt_pk_bf16_f32 v20, v31, v23
	s_nop 0
	v_rcp_f32_e32 v21, v21
	s_nop 0
	v_mul_f32_e32 v21, v28, v21
	v_cvt_pk_bf16_f32 v21, v24, v21
	global_store_dwordx4 v[26:27], v[18:21], off offset:2304
	s_nop 1
	v_add_u32_e32 v18, 0xb0, v144
	v_ashrrev_i32_e32 v19, 31, v18
	v_lshlrev_b64 v[22:23], 11, v[18:19]
	v_lshlrev_b64 v[20:21], 12, v[18:19]
	v_lshl_add_u64 v[18:19], s[86:87], 0, v[22:23]
	v_lshl_add_u64 v[18:19], v[18:19], 0, v[142:143]
	global_load_dwordx4 v[22:25], v[18:19], off
	s_waitcnt vmcnt(0)
	v_lshlrev_b32_e32 v26, 16, v22
	v_and_b32_e32 v27, 0xffff0000, v22
	v_lshlrev_b32_e32 v30, 16, v25
	v_and_b32_e32 v22, 0xffff0000, v25
	v_lshlrev_b32_e32 v29, 16, v24
	v_and_b32_e32 v24, 0xffff0000, v24
	v_lshlrev_b32_e32 v28, 16, v23
	v_rcp_f32_e32 v14, v14
	s_nop 0
	v_mul_f32_e32 v14, v26, v14
	v_and_b32_e32 v23, 0xffff0000, v23
	v_rcp_f32_e32 v10, v10
	s_nop 0
	v_mul_f32_e32 v10, v29, v10
	s_nop 0
	v_rcp_f32_e32 v15, v15
	s_nop 0
	v_mul_f32_e32 v15, v27, v15
	s_nop 0
	v_rcp_f32_e32 v11, v11
	s_nop 0
	v_mul_f32_e32 v11, v24, v11
	s_nop 0
	v_rcp_f32_e32 v16, v16
	s_nop 0
	v_mul_f32_e32 v16, v28, v16
	s_nop 0
	v_rcp_f32_e32 v24, v12
	s_nop 0
	v_mul_f32_e32 v24, v30, v24
	v_mul_f32_e32 v12, 0xbfb8aa3b, v17
	v_exp_f32_e32 v12, v12
	s_nop 0
	v_add_f32_e32 v12, 1.0, v12
	s_nop 0
	v_rcp_f32_e32 v17, v12
	s_nop 0
	v_mul_f32_e32 v17, v23, v17
	v_mul_f32_e32 v12, 0xbfb8aa3b, v13
	v_exp_f32_e32 v12, v12
	s_nop 0
	v_add_f32_e32 v12, 1.0, v12
	s_nop 0
	v_rcp_f32_e32 v13, v12
	s_nop 0
	v_mul_f32_e32 v22, v22, v13
	v_cvt_pk_bf16_f32 v12, v14, v15
	v_cvt_pk_bf16_f32 v13, v16, v17
	v_cvt_pk_bf16_f32 v14, v10, v11
	v_lshl_add_u64 v[10:11], s[88:89], 0, v[20:21]
	v_cvt_pk_bf16_f32 v15, v24, v22
	v_lshl_add_u64 v[10:11], v[10:11], 0, v[142:143]
	global_store_dwordx4 v[10:11], v[12:15], off offset:2048
	global_load_dwordx4 v[12:15], v[18:19], off offset:256
	s_waitcnt vmcnt(0)
	v_lshlrev_b32_e32 v16, 16, v12
	v_and_b32_e32 v17, 0xffff0000, v12
	v_lshlrev_b32_e32 v20, 16, v15
	v_and_b32_e32 v12, 0xffff0000, v15
	v_lshlrev_b32_e32 v19, 16, v14
	v_and_b32_e32 v14, 0xffff0000, v14
	v_lshlrev_b32_e32 v18, 16, v13
	v_rcp_f32_e32 v6, v6
	s_nop 0
	v_mul_f32_e32 v6, v16, v6
	v_and_b32_e32 v13, 0xffff0000, v13
	v_rcp_f32_e32 v15, v2
	s_nop 0
	v_mul_f32_e32 v15, v19, v15
	v_mul_f32_e32 v2, 0xbfb8aa3b, v7
	v_exp_f32_e32 v2, v2
	s_nop 0
	v_add_f32_e32 v2, 1.0, v2
	s_nop 0
	v_rcp_f32_e32 v2, v2
	s_nop 0
	v_mul_f32_e32 v2, v17, v2
	v_cvt_pk_bf16_f32 v2, v6, v2
	s_nop 0
	v_rcp_f32_e32 v7, v3
	s_nop 0
	v_mul_f32_e32 v7, v14, v7
	v_mul_f32_e32 v3, 0xbfb8aa3b, v8
	v_exp_f32_e32 v3, v3
	s_nop 0
	v_add_f32_e32 v3, 1.0, v3
	s_nop 0
	v_rcp_f32_e32 v3, v3
	s_nop 0
	v_mul_f32_e32 v3, v18, v3
	s_nop 0
	v_rcp_f32_e32 v8, v4
	s_nop 0
	v_mul_f32_e32 v8, v20, v8
	v_mul_f32_e32 v4, 0xbfb8aa3b, v9
	v_exp_f32_e32 v4, v4
	s_nop 0
	v_add_f32_e32 v4, 1.0, v4
	s_nop 0
	v_rcp_f32_e32 v4, v4
	s_nop 0
	v_mul_f32_e32 v4, v13, v4
	v_div_scale_f32 v9, s[12:13], v5, v5, v12
	s_mov_b32 s12, s0
	s_mov_b32 s13, s42
	v_cvt_pk_bf16_f32 v3, v3, v4
	v_div_scale_f32 v14, vcc, v12, v5, v12
	v_rcp_f32_e32 v5, v5
	s_nop 0
	v_mul_f32_e32 v5, v12, v5
	s_and_b64 vcc, exec, s[40:41]
	v_cvt_pk_bf16_f32 v4, v15, v7
	v_cvt_pk_bf16_f32 v5, v8, v5
	global_store_dwordx4 v[10:11], v[2:5], off offset:2304
	s_cbranch_vccz .LBB0_661
	s_waitcnt vmcnt(0)
	s_cmpk_gt_u32 s27, 0xff
	s_cbranch_scc1 .LBB0_672
	s_barrier
